# deleted the 160 per-block s_setprio flips in the 10 GEMM K-loops (on top of hoisted epilogue loads)
# speedup vs baseline: 1.0062x; 1.0062x over previous
; #define PG8_STAGE(bufoff, gbase, voff) do { _Pragma("unroll") for (int _i = 0; _i < 2; ++_i) \
;         __builtin_amdgcn_global_load_lds((const unsigned*)((const char*)(gbase) + (voff)[_i]), (PG8_LAS unsigned*)(lds + (bufoff) + ldsw + _i * 8192), 16, 0, 0); } while (0)
; #define PG8_LDA(dst, b, h) do { _Pragma("unroll") for (int m = 0; m < 4; ++m) _Pragma("unroll") for (int k = 0; k < 2; ++k) dst[m][k] = *(const PG8_LAS bf16x8*)(lds + PG8_SA(b, h) + aoff + m * 2048 + k * 1024); } while (0)
; #define PG8_LDB(dst, b, h) do { _Pragma("unroll") for (int n = 0; n < 2; ++n) _Pragma("unroll") for (int k = 0; k < 2; ++k) dst[n][k] = *(const PG8_LAS bf16x8*)(lds + PG8_SB(b, h) + boff + n * 2048 + k * 1024); } while (0)
; #define PG8_MMA(ai, bj, At, Bt) do { __builtin_amdgcn_s_setprio(1); _Pragma("unroll") for (int m = 0; m < 4; ++m) _Pragma("unroll") for (int n = 0; n < 2; ++n) _Pragma("unroll") for (int k = 0; k < 2; ++k) \
;         acc[ai][bj][m][n] = __builtin_amdgcn_mfma_f32_16x16x32_bf16(Bt[n][k], At[m][k], acc[ai][bj][m][n], 0, 0, 0); __builtin_amdgcn_s_setprio(0); } while (0)
; #define PG8_WAIT_V(n) asm volatile("s_waitcnt vmcnt(" #n ")" ::: "memory")
; #define PG8_WAIT_L(n) asm volatile("s_waitcnt lgkmcnt(" #n ")" ::: "memory")
; #define PG8_BAR __builtin_amdgcn_s_barrier()
; #define PG8_SCHED __builtin_amdgcn_sched_barrier(0)
; template <class Epi, class Sched, bool ALIGN_EPI = false, bool SP2 = false>
; __device__ __forceinline__ void gemm_phase(PG8_LAS unsigned char* lds, const Gemm g, const Sched& S, const Epi& E) {
;     ...
;             PG8_LDB(B0, 0, 0); PG8_LDB(B1, 0, 1); PG8_SCHED; PG8_LDA(At, 0, 0); PG8_STAGE(PG8_SA(1, 1), a1 + hstep, voffA);
;             PG8_WAIT_V(8); PG8_WAIT_L(0); PG8_BAR; PG8_MMA(0, 0, At, B0); PG8_MMA(0, 1, At, B1); PG8_BAR; PG8_SCHED;
;             PG8_LDA(At, 0, 1); PG8_STAGE(PG8_SB(0, 0), b2, voffB); PG8_STAGE(PG8_SB(0, 1), b2 + hstep, voffB); PG8_STAGE(PG8_SA(0, 0), a2, voffA);
;             PG8_WAIT_V(8); PG8_WAIT_L(0); PG8_BAR; PG8_MMA(1, 0, At, B0); PG8_MMA(1, 1, At, B1); PG8_BAR; PG8_SCHED;
.LBB0_234:
	ds_read_b128 v[144:147], v160
	ds_read_b128 v[164:167], v160 offset:1024
	ds_read_b128 v[168:171], v160 offset:2048
	ds_read_b128 v[172:175], v160 offset:3072
	ds_read_b128 v[176:179], v161
	ds_read_b128 v[180:183], v161 offset:1024
	ds_read_b128 v[184:187], v161 offset:2048
	ds_read_b128 v[188:191], v161 offset:3072
	s_add_u32 s6, s58, 0xfffc0080
	s_addc_u32 s7, s59, -1
	s_cmp_eq_u32 s85, 12
	s_cselect_b32 s11, s45, s7
	s_cselect_b32 s10, s81, s6
	s_cselect_b32 s7, s35, s84
	s_cselect_b32 s6, s82, s83
	v_lshl_add_u64 v[226:227], s[58:59], 0, v[136:137]
	s_add_i32 m0, s57, 0xc000
	ds_read_b128 v[192:195], v162
	ds_read_b128 v[196:199], v162 offset:1024
	ds_read_b128 v[200:203], v162 offset:2048
	ds_read_b128 v[204:207], v162 offset:3072
	ds_read_b128 v[208:211], v162 offset:4096
	ds_read_b128 v[212:215], v162 offset:5120
	ds_read_b128 v[216:219], v162 offset:6144
	ds_read_b128 v[222:225], v162 offset:7168
	global_load_lds_dwordx4 v[226:227], off
	v_lshl_add_u64 v[226:227], s[58:59], 0, v[138:139]
	s_add_i32 m0, s57, 0xe000
	s_nop 0
	global_load_lds_dwordx4 v[226:227], off
	s_waitcnt vmcnt(8)
	s_waitcnt lgkmcnt(0)
	s_barrier
	s_waitcnt lgkmcnt(0)
	v_mfma_f32_16x16x32_bf16 v[124:127], v[144:147], v[192:195], v[124:127]
	v_mfma_f32_16x16x32_bf16 v[120:123], v[168:171], v[192:195], v[120:123]
	v_mfma_f32_16x16x32_bf16 v[108:111], v[144:147], v[200:203], v[108:111]
	v_mfma_f32_16x16x32_bf16 v[104:107], v[168:171], v[200:203], v[104:107]
	v_mfma_f32_16x16x32_bf16 v[92:95], v[144:147], v[208:211], v[92:95]
	v_mfma_f32_16x16x32_bf16 v[88:91], v[168:171], v[208:211], v[88:91]
	v_mfma_f32_16x16x32_bf16 v[76:79], v[144:147], v[216:219], v[76:79]
	v_mfma_f32_16x16x32_bf16 v[72:75], v[168:171], v[216:219], v[72:75]
	v_mfma_f32_16x16x32_bf16 v[124:127], v[164:167], v[196:199], v[124:127]
	v_mfma_f32_16x16x32_bf16 v[120:123], v[172:175], v[196:199], v[120:123]
	v_mfma_f32_16x16x32_bf16 v[108:111], v[164:167], v[204:207], v[108:111]
	v_mfma_f32_16x16x32_bf16 v[104:107], v[172:175], v[204:207], v[104:107]
	v_mfma_f32_16x16x32_bf16 v[92:95], v[164:167], v[212:215], v[92:95]
	v_mfma_f32_16x16x32_bf16 v[88:91], v[172:175], v[212:215], v[88:91]
	v_mfma_f32_16x16x32_bf16 v[76:79], v[164:167], v[222:225], v[76:79]
	v_mfma_f32_16x16x32_bf16 v[72:75], v[172:175], v[222:225], v[72:75]
	v_mfma_f32_16x16x32_bf16 v[116:119], v[176:179], v[192:195], v[116:119]
	v_mfma_f32_16x16x32_bf16 v[112:115], v[184:187], v[192:195], v[112:115]
	v_mfma_f32_16x16x32_bf16 v[100:103], v[176:179], v[200:203], v[100:103]
	v_mfma_f32_16x16x32_bf16 v[96:99], v[184:187], v[200:203], v[96:99]
	v_mfma_f32_16x16x32_bf16 v[84:87], v[176:179], v[208:211], v[84:87]
	v_mfma_f32_16x16x32_bf16 v[80:83], v[184:187], v[208:211], v[80:83]
	v_mfma_f32_16x16x32_bf16 v[68:71], v[176:179], v[216:219], v[68:71]
	v_mfma_f32_16x16x32_bf16 v[64:67], v[184:187], v[216:219], v[64:67]
	v_mfma_f32_16x16x32_bf16 v[116:119], v[180:183], v[196:199], v[116:119]
	v_mfma_f32_16x16x32_bf16 v[112:115], v[188:191], v[196:199], v[112:115]
	v_mfma_f32_16x16x32_bf16 v[100:103], v[180:183], v[204:207], v[100:103]
	v_mfma_f32_16x16x32_bf16 v[96:99], v[188:191], v[204:207], v[96:99]
	v_mfma_f32_16x16x32_bf16 v[84:87], v[180:183], v[212:215], v[84:87]
	v_mfma_f32_16x16x32_bf16 v[80:83], v[188:191], v[212:215], v[80:83]
	v_mfma_f32_16x16x32_bf16 v[68:71], v[180:183], v[222:225], v[68:71]
	v_mfma_f32_16x16x32_bf16 v[64:67], v[188:191], v[222:225], v[64:67]
	s_barrier
	s_add_i32 s86, s77, s3
	v_lshl_add_u64 v[226:227], s[6:7], 0, v[132:133]
	s_mov_b32 m0, s86
	ds_read_b128 v[192:195], v162 offset:16384
	ds_read_b128 v[196:199], v162 offset:17408
	ds_read_b128 v[200:203], v162 offset:18432
	ds_read_b128 v[204:207], v162 offset:19456
	ds_read_b128 v[208:211], v162 offset:20480
	ds_read_b128 v[212:215], v162 offset:21504
	ds_read_b128 v[216:219], v162 offset:22528
	ds_read_b128 v[222:225], v162 offset:23552
	global_load_lds_dwordx4 v[226:227], off
	s_add_i32 m0, s86, 0x2000
	s_add_u32 s86, s6, 0x40000
	v_lshl_add_u64 v[228:229], s[6:7], 0, v[128:129]
	s_addc_u32 s87, s7, 0
	s_add_i32 s88, s78, s3
	global_load_lds_dwordx4 v[228:229], off
	v_lshl_add_u64 v[230:231], s[86:87], 0, v[132:133]
	s_mov_b32 m0, s88
	v_lshl_add_u64 v[232:233], s[10:11], 0, v[130:131]
	global_load_lds_dwordx4 v[230:231], off
	v_lshl_add_u64 v[230:231], s[86:87], 0, v[128:129]
	s_add_i32 m0, s88, 0x2000
	s_nop 0
	global_load_lds_dwordx4 v[230:231], off
	v_lshl_add_u64 v[230:231], s[10:11], 0, v[134:135]
	s_mov_b32 m0, s57
	s_nop 0
	global_load_lds_dwordx4 v[230:231], off
	s_mov_b32 m0, s61
	s_nop 0
	global_load_lds_dwordx4 v[232:233], off
	s_waitcnt vmcnt(8)
	s_waitcnt lgkmcnt(0)
	s_barrier
; #define PG8_STAGE(bufoff, gbase, voff) do { _Pragma("unroll") for (int _i = 0; _i < 2; ++_i) \
;         __builtin_amdgcn_global_load_lds((const unsigned*)((const char*)(gbase) + (voff)[_i]), (PG8_LAS unsigned*)(lds + (bufoff) + ldsw + _i * 8192), 16, 0, 0); } while (0)
; #define PG8_LDA(dst, b, h) do { _Pragma("unroll") for (int m = 0; m < 4; ++m) _Pragma("unroll") for (int k = 0; k < 2; ++k) dst[m][k] = *(const PG8_LAS bf16x8*)(lds + PG8_SA(b, h) + aoff + m * 2048 + k * 1024); } while (0)
; #define PG8_LDB(dst, b, h) do { _Pragma("unroll") for (int n = 0; n < 2; ++n) _Pragma("unroll") for (int k = 0; k < 2; ++k) dst[n][k] = *(const PG8_LAS bf16x8*)(lds + PG8_SB(b, h) + boff + n * 2048 + k * 1024); } while (0)
; #define PG8_MMA(ai, bj, At, Bt) do { __builtin_amdgcn_s_setprio(1); _Pragma("unroll") for (int m = 0; m < 4; ++m) _Pragma("unroll") for (int n = 0; n < 2; ++n) _Pragma("unroll") for (int k = 0; k < 2; ++k) \
;         acc[ai][bj][m][n] = __builtin_amdgcn_mfma_f32_16x16x32_bf16(Bt[n][k], At[m][k], acc[ai][bj][m][n], 0, 0, 0); __builtin_amdgcn_s_setprio(0); } while (0)
; #define PG8_WAIT_V(n) asm volatile("s_waitcnt vmcnt(" #n ")" ::: "memory")
; #define PG8_WAIT_L(n) asm volatile("s_waitcnt lgkmcnt(" #n ")" ::: "memory")
; #define PG8_BAR __builtin_amdgcn_s_barrier()
; #define PG8_SCHED __builtin_amdgcn_sched_barrier(0)
; template <class Epi, class Sched, bool ALIGN_EPI = false, bool SP2 = false>
; __device__ __forceinline__ void gemm_phase(PG8_LAS unsigned char* lds, const Gemm g, const Sched& S, const Epi& E) {
;     ...
;             PG8_WAIT_V(8); PG8_WAIT_L(0); PG8_BAR; PG8_MMA(1, 0, At, B0); PG8_MMA(1, 1, At, B1); PG8_BAR; PG8_SCHED;
;             PG8_LDB(B0, 1, 0); PG8_LDB(B1, 1, 1); PG8_SCHED; PG8_LDA(At, 1, 0); PG8_STAGE(PG8_SA(0, 1), a2 + hstep, voffA);
;             PG8_WAIT_V(8); PG8_WAIT_L(0); PG8_BAR; PG8_MMA(0, 0, At, B0); PG8_MMA(0, 1, At, B1); PG8_BAR; PG8_SCHED;
	s_waitcnt lgkmcnt(0)
	v_mfma_f32_16x16x32_bf16 v[60:63], v[144:147], v[192:195], v[60:63]
	v_mfma_f32_16x16x32_bf16 v[56:59], v[168:171], v[192:195], v[56:59]
	v_mfma_f32_16x16x32_bf16 v[44:47], v[144:147], v[200:203], v[44:47]
	v_mfma_f32_16x16x32_bf16 v[40:43], v[168:171], v[200:203], v[40:43]
	v_mfma_f32_16x16x32_bf16 v[28:31], v[144:147], v[208:211], v[28:31]
	v_mfma_f32_16x16x32_bf16 v[24:27], v[168:171], v[208:211], v[24:27]
	v_mfma_f32_16x16x32_bf16 v[12:15], v[144:147], v[216:219], v[12:15]
	v_mfma_f32_16x16x32_bf16 v[8:11], v[168:171], v[216:219], v[8:11]
	v_mfma_f32_16x16x32_bf16 v[60:63], v[164:167], v[196:199], v[60:63]
	v_mfma_f32_16x16x32_bf16 v[56:59], v[172:175], v[196:199], v[56:59]
	v_mfma_f32_16x16x32_bf16 v[44:47], v[164:167], v[204:207], v[44:47]
	v_mfma_f32_16x16x32_bf16 v[40:43], v[172:175], v[204:207], v[40:43]
	v_mfma_f32_16x16x32_bf16 v[28:31], v[164:167], v[212:215], v[28:31]
	v_mfma_f32_16x16x32_bf16 v[24:27], v[172:175], v[212:215], v[24:27]
	v_mfma_f32_16x16x32_bf16 v[12:15], v[164:167], v[222:225], v[12:15]
	v_mfma_f32_16x16x32_bf16 v[8:11], v[172:175], v[222:225], v[8:11]
	v_mfma_f32_16x16x32_bf16 v[52:55], v[176:179], v[192:195], v[52:55]
	v_mfma_f32_16x16x32_bf16 v[48:51], v[184:187], v[192:195], v[48:51]
	v_mfma_f32_16x16x32_bf16 v[36:39], v[176:179], v[200:203], v[36:39]
	v_mfma_f32_16x16x32_bf16 v[32:35], v[184:187], v[200:203], v[32:35]
	v_mfma_f32_16x16x32_bf16 v[20:23], v[176:179], v[208:211], v[20:23]
	v_mfma_f32_16x16x32_bf16 v[16:19], v[184:187], v[208:211], v[16:19]
	v_mfma_f32_16x16x32_bf16 v[4:7], v[176:179], v[216:219], v[4:7]
	v_mfma_f32_16x16x32_bf16 v[0:3], v[184:187], v[216:219], v[0:3]
	v_mfma_f32_16x16x32_bf16 v[52:55], v[180:183], v[196:199], v[52:55]
	v_mfma_f32_16x16x32_bf16 v[48:51], v[188:191], v[196:199], v[48:51]
	v_mfma_f32_16x16x32_bf16 v[36:39], v[180:183], v[204:207], v[36:39]
	v_mfma_f32_16x16x32_bf16 v[32:35], v[188:191], v[204:207], v[32:35]
	v_mfma_f32_16x16x32_bf16 v[20:23], v[180:183], v[212:215], v[20:23]
	v_mfma_f32_16x16x32_bf16 v[16:19], v[188:191], v[212:215], v[16:19]
	v_mfma_f32_16x16x32_bf16 v[4:7], v[180:183], v[222:225], v[4:7]
	v_mfma_f32_16x16x32_bf16 v[0:3], v[188:191], v[222:225], v[0:3]
	s_barrier
	s_add_i32 s86, 0, 0x18000
	v_add_u32_e32 v163, s86, v158
	s_add_i32 s87, 0, 0x1c000
	ds_read_b128 v[144:147], v163
	ds_read_b128 v[164:167], v163 offset:1024
	ds_read_b128 v[168:171], v163 offset:2048
	ds_read_b128 v[172:175], v163 offset:3072
	v_add_u32_e32 v163, s87, v158
	ds_read_b128 v[176:179], v163
	ds_read_b128 v[180:183], v163 offset:1024
	ds_read_b128 v[184:187], v163 offset:2048
	ds_read_b128 v[188:191], v163 offset:3072
	s_add_u32 s10, s10, 0x40000
	s_addc_u32 s11, s11, 0
	s_mov_b32 m0, s62
	v_lshl_add_u64 v[234:235], s[10:11], 0, v[134:135]
	ds_read_b128 v[192:195], v162 offset:32768
	ds_read_b128 v[196:199], v162 offset:33792
	ds_read_b128 v[200:203], v162 offset:34816
	ds_read_b128 v[204:207], v162 offset:35840
	ds_read_b128 v[208:211], v162 offset:36864
	ds_read_b128 v[212:215], v162 offset:37888
	ds_read_b128 v[216:219], v162 offset:38912
	ds_read_b128 v[222:225], v162 offset:39936
	global_load_lds_dwordx4 v[234:235], off
	v_lshl_add_u64 v[234:235], s[10:11], 0, v[130:131]
	s_mov_b32 m0, s63
	s_nop 0
	global_load_lds_dwordx4 v[234:235], off
	s_waitcnt vmcnt(8)
	s_waitcnt lgkmcnt(0)
	s_barrier
	s_waitcnt lgkmcnt(0)
	v_mfma_f32_16x16x32_bf16 v[124:127], v[144:147], v[192:195], v[124:127]
	v_mfma_f32_16x16x32_bf16 v[120:123], v[168:171], v[192:195], v[120:123]
	v_mfma_f32_16x16x32_bf16 v[108:111], v[144:147], v[200:203], v[108:111]
	v_mfma_f32_16x16x32_bf16 v[104:107], v[168:171], v[200:203], v[104:107]
	v_mfma_f32_16x16x32_bf16 v[92:95], v[144:147], v[208:211], v[92:95]
	v_mfma_f32_16x16x32_bf16 v[88:91], v[168:171], v[208:211], v[88:91]
	v_mfma_f32_16x16x32_bf16 v[76:79], v[144:147], v[216:219], v[76:79]
	v_mfma_f32_16x16x32_bf16 v[72:75], v[168:171], v[216:219], v[72:75]
	v_mfma_f32_16x16x32_bf16 v[124:127], v[164:167], v[196:199], v[124:127]
	v_mfma_f32_16x16x32_bf16 v[120:123], v[172:175], v[196:199], v[120:123]
	v_mfma_f32_16x16x32_bf16 v[108:111], v[164:167], v[204:207], v[108:111]
	v_mfma_f32_16x16x32_bf16 v[104:107], v[172:175], v[204:207], v[104:107]
	v_mfma_f32_16x16x32_bf16 v[92:95], v[164:167], v[212:215], v[92:95]
	v_mfma_f32_16x16x32_bf16 v[88:91], v[172:175], v[212:215], v[88:91]
	v_mfma_f32_16x16x32_bf16 v[76:79], v[164:167], v[222:225], v[76:79]
	v_mfma_f32_16x16x32_bf16 v[72:75], v[172:175], v[222:225], v[72:75]
	v_mfma_f32_16x16x32_bf16 v[116:119], v[176:179], v[192:195], v[116:119]
	v_mfma_f32_16x16x32_bf16 v[112:115], v[184:187], v[192:195], v[112:115]
	v_mfma_f32_16x16x32_bf16 v[100:103], v[176:179], v[200:203], v[100:103]
	v_mfma_f32_16x16x32_bf16 v[96:99], v[184:187], v[200:203], v[96:99]
	v_mfma_f32_16x16x32_bf16 v[84:87], v[176:179], v[208:211], v[84:87]
	v_mfma_f32_16x16x32_bf16 v[80:83], v[184:187], v[208:211], v[80:83]
	v_mfma_f32_16x16x32_bf16 v[68:71], v[176:179], v[216:219], v[68:71]
	v_mfma_f32_16x16x32_bf16 v[64:67], v[184:187], v[216:219], v[64:67]
	v_mfma_f32_16x16x32_bf16 v[116:119], v[180:183], v[196:199], v[116:119]
	v_mfma_f32_16x16x32_bf16 v[112:115], v[188:191], v[196:199], v[112:115]
	v_mfma_f32_16x16x32_bf16 v[100:103], v[180:183], v[204:207], v[100:103]
	v_mfma_f32_16x16x32_bf16 v[96:99], v[188:191], v[204:207], v[96:99]
	v_mfma_f32_16x16x32_bf16 v[84:87], v[180:183], v[212:215], v[84:87]
	v_mfma_f32_16x16x32_bf16 v[80:83], v[188:191], v[212:215], v[80:83]
	v_mfma_f32_16x16x32_bf16 v[68:71], v[180:183], v[222:225], v[68:71]
	v_mfma_f32_16x16x32_bf16 v[64:67], v[188:191], v[222:225], v[64:67]
	s_barrier
; #define PG8_STAGE(bufoff, gbase, voff) do { _Pragma("unroll") for (int _i = 0; _i < 2; ++_i) \
;         __builtin_amdgcn_global_load_lds((const unsigned*)((const char*)(gbase) + (voff)[_i]), (PG8_LAS unsigned*)(lds + (bufoff) + ldsw + _i * 8192), 16, 0, 0); } while (0)
; #define PG8_LDA(dst, b, h) do { _Pragma("unroll") for (int m = 0; m < 4; ++m) _Pragma("unroll") for (int k = 0; k < 2; ++k) dst[m][k] = *(const PG8_LAS bf16x8*)(lds + PG8_SA(b, h) + aoff + m * 2048 + k * 1024); } while (0)
; #define PG8_MMA(ai, bj, At, Bt) do { __builtin_amdgcn_s_setprio(1); _Pragma("unroll") for (int m = 0; m < 4; ++m) _Pragma("unroll") for (int n = 0; n < 2; ++n) _Pragma("unroll") for (int k = 0; k < 2; ++k) \
;         acc[ai][bj][m][n] = __builtin_amdgcn_mfma_f32_16x16x32_bf16(Bt[n][k], At[m][k], acc[ai][bj][m][n], 0, 0, 0); __builtin_amdgcn_s_setprio(0); } while (0)
; #define PG8_WAIT_V(n) asm volatile("s_waitcnt vmcnt(" #n ")" ::: "memory")
; #define PG8_WAIT_L(n) asm volatile("s_waitcnt lgkmcnt(" #n ")" ::: "memory")
; #define PG8_BAR __builtin_amdgcn_s_barrier()
; #define PG8_SCHED __builtin_amdgcn_sched_barrier(0)
; template <class Epi, class Sched, bool ALIGN_EPI = false, bool SP2 = false>
; __device__ __forceinline__ void gemm_phase(PG8_LAS unsigned char* lds, const Gemm g, const Sched& S, const Epi& E) {
;     ...
;             PG8_WAIT_V(8); PG8_WAIT_L(0); PG8_BAR; PG8_MMA(0, 0, At, B0); PG8_MMA(0, 1, At, B1); PG8_BAR; PG8_SCHED;
;             PG8_LDA(At, 1, 1); PG8_STAGE(PG8_SB(1, 0), b3, voffB); PG8_STAGE(PG8_SB(1, 1), b3 + hstep, voffB); PG8_STAGE(PG8_SA(1, 0), a3, voffA);
;             PG8_WAIT_V(8); PG8_WAIT_L(0); PG8_BAR; PG8_MMA(1, 0, At, B0); PG8_MMA(1, 1, At, B1); PG8_BAR; PG8_SCHED;
	s_add_i32 s10, s86, s3
	v_lshl_add_u64 v[226:227], v[226:227], 0, s[20:21]
	s_mov_b32 m0, s10
	ds_read_b128 v[192:195], v162 offset:49152
	ds_read_b128 v[196:199], v162 offset:50176
	ds_read_b128 v[200:203], v162 offset:51200
	ds_read_b128 v[204:207], v162 offset:52224
	ds_read_b128 v[208:211], v162 offset:53248
	ds_read_b128 v[212:215], v162 offset:54272
	ds_read_b128 v[216:219], v162 offset:55296
	ds_read_b128 v[222:225], v162 offset:56320
	global_load_lds_dwordx4 v[226:227], off
	s_add_i32 m0, s10, 0x2000
	s_add_u32 s6, s6, 0x40080
	v_lshl_add_u64 v[226:227], v[228:229], 0, s[20:21]
	s_addc_u32 s7, s7, 0
	s_add_i32 s10, s87, s3
	global_load_lds_dwordx4 v[226:227], off
	v_lshl_add_u64 v[226:227], s[6:7], 0, v[132:133]
	s_mov_b32 m0, s10
	s_nop 0
	global_load_lds_dwordx4 v[226:227], off
	v_lshl_add_u64 v[226:227], s[6:7], 0, v[128:129]
	s_add_i32 m0, s10, 0x2000
	s_nop 0
	global_load_lds_dwordx4 v[226:227], off
	v_lshl_add_u64 v[226:227], v[230:231], 0, s[20:21]
	s_mov_b32 m0, s65
	s_nop 0
	global_load_lds_dwordx4 v[226:227], off
	v_lshl_add_u64 v[226:227], v[232:233], 0, s[20:21]
	s_mov_b32 m0, s66
	s_nop 0
	global_load_lds_dwordx4 v[226:227], off
	s_waitcnt vmcnt(8)
	s_waitcnt lgkmcnt(0)
	s_barrier
	s_waitcnt lgkmcnt(0)
	v_mfma_f32_16x16x32_bf16 v[60:63], v[144:147], v[192:195], v[60:63]
	v_mfma_f32_16x16x32_bf16 v[56:59], v[168:171], v[192:195], v[56:59]
	v_mfma_f32_16x16x32_bf16 v[44:47], v[144:147], v[200:203], v[44:47]
	v_mfma_f32_16x16x32_bf16 v[40:43], v[168:171], v[200:203], v[40:43]
	v_mfma_f32_16x16x32_bf16 v[28:31], v[144:147], v[208:211], v[28:31]
	v_mfma_f32_16x16x32_bf16 v[24:27], v[168:171], v[208:211], v[24:27]
	v_mfma_f32_16x16x32_bf16 v[12:15], v[144:147], v[216:219], v[12:15]
	v_mfma_f32_16x16x32_bf16 v[8:11], v[168:171], v[216:219], v[8:11]
	v_mfma_f32_16x16x32_bf16 v[60:63], v[164:167], v[196:199], v[60:63]
	v_mfma_f32_16x16x32_bf16 v[56:59], v[172:175], v[196:199], v[56:59]
	v_mfma_f32_16x16x32_bf16 v[44:47], v[164:167], v[204:207], v[44:47]
	v_mfma_f32_16x16x32_bf16 v[40:43], v[172:175], v[204:207], v[40:43]
	v_mfma_f32_16x16x32_bf16 v[28:31], v[164:167], v[212:215], v[28:31]
	v_mfma_f32_16x16x32_bf16 v[24:27], v[172:175], v[212:215], v[24:27]
	v_mfma_f32_16x16x32_bf16 v[12:15], v[164:167], v[222:225], v[12:15]
	v_mfma_f32_16x16x32_bf16 v[8:11], v[172:175], v[222:225], v[8:11]
	v_mfma_f32_16x16x32_bf16 v[52:55], v[176:179], v[192:195], v[52:55]
	v_mfma_f32_16x16x32_bf16 v[48:51], v[184:187], v[192:195], v[48:51]
	v_mfma_f32_16x16x32_bf16 v[36:39], v[176:179], v[200:203], v[36:39]
	v_mfma_f32_16x16x32_bf16 v[32:35], v[184:187], v[200:203], v[32:35]
	v_mfma_f32_16x16x32_bf16 v[20:23], v[176:179], v[208:211], v[20:23]
	v_mfma_f32_16x16x32_bf16 v[16:19], v[184:187], v[208:211], v[16:19]
	v_mfma_f32_16x16x32_bf16 v[4:7], v[176:179], v[216:219], v[4:7]
	v_mfma_f32_16x16x32_bf16 v[0:3], v[184:187], v[216:219], v[0:3]
	v_mfma_f32_16x16x32_bf16 v[52:55], v[180:183], v[196:199], v[52:55]
	v_mfma_f32_16x16x32_bf16 v[48:51], v[188:191], v[196:199], v[48:51]
	v_mfma_f32_16x16x32_bf16 v[36:39], v[180:183], v[204:207], v[36:39]
	v_mfma_f32_16x16x32_bf16 v[32:35], v[188:191], v[204:207], v[32:35]
	v_mfma_f32_16x16x32_bf16 v[20:23], v[180:183], v[212:215], v[20:23]
	v_mfma_f32_16x16x32_bf16 v[16:19], v[188:191], v[212:215], v[16:19]
	v_mfma_f32_16x16x32_bf16 v[4:7], v[180:183], v[222:225], v[4:7]
	v_mfma_f32_16x16x32_bf16 v[0:3], v[188:191], v[222:225], v[0:3]
	s_barrier
	s_add_i32 s85, s85, 2
	s_add_u32 s58, s58, 0x100
	s_addc_u32 s59, s59, 0
	s_add_u32 s83, s83, 0x100
	s_addc_u32 s84, s84, 0
	s_cmp_gt_u32 s85, 13
	s_cbranch_scc0 .LBB0_234
	s_and_b64 vcc, exec, s[26:27]
	s_cbranch_vccz .LBB0_237
	s_barrier

; #define PG8_STAGE(bufoff, gbase, voff) do { _Pragma("unroll") for (int _i = 0; _i < 2; ++_i) \
;         __builtin_amdgcn_global_load_lds((const unsigned*)((const char*)(gbase) + (voff)[_i]), (PG8_LAS unsigned*)(lds + (bufoff) + ldsw + _i * 8192), 16, 0, 0); } while (0)
; #define PG8_LDA(dst, b, h) do { _Pragma("unroll") for (int m = 0; m < 4; ++m) _Pragma("unroll") for (int k = 0; k < 2; ++k) dst[m][k] = *(const PG8_LAS bf16x8*)(lds + PG8_SA(b, h) + aoff + m * 2048 + k * 1024); } while (0)
; #define PG8_LDB(dst, b, h) do { _Pragma("unroll") for (int n = 0; n < 2; ++n) _Pragma("unroll") for (int k = 0; k < 2; ++k) dst[n][k] = *(const PG8_LAS bf16x8*)(lds + PG8_SB(b, h) + boff + n * 2048 + k * 1024); } while (0)
; #define PG8_MMA(ai, bj, At, Bt) do { __builtin_amdgcn_s_setprio(1); _Pragma("unroll") for (int m = 0; m < 4; ++m) _Pragma("unroll") for (int n = 0; n < 2; ++n) _Pragma("unroll") for (int k = 0; k < 2; ++k) \
;         acc[ai][bj][m][n] = __builtin_amdgcn_mfma_f32_16x16x32_bf16(Bt[n][k], At[m][k], acc[ai][bj][m][n], 0, 0, 0); __builtin_amdgcn_s_setprio(0); } while (0)
; #define PG8_WAIT_V(n) asm volatile("s_waitcnt vmcnt(" #n ")" ::: "memory")
; #define PG8_WAIT_L(n) asm volatile("s_waitcnt lgkmcnt(" #n ")" ::: "memory")
; #define PG8_BAR __builtin_amdgcn_s_barrier()
; #define PG8_SCHED __builtin_amdgcn_sched_barrier(0)
; template <class Epi, class Sched, bool ALIGN_EPI = false, bool SP2 = false>
; __device__ __forceinline__ void gemm_phase(PG8_LAS unsigned char* lds, const Gemm g, const Sched& S, const Epi& E) {
;     ...
;             PG8_LDB(B0, 0, 0); PG8_LDB(B1, 0, 1); PG8_SCHED; PG8_LDA(At, 0, 0); PG8_STAGE(PG8_SA(1, 1), a1 + hstep, voffA);
;             PG8_WAIT_V(8); PG8_WAIT_L(0); PG8_BAR; PG8_MMA(0, 0, At, B0); PG8_MMA(0, 1, At, B1); PG8_BAR; PG8_SCHED;
;             PG8_LDA(At, 0, 1); PG8_STAGE(PG8_SB(0, 0), b2, voffB); PG8_STAGE(PG8_SB(0, 1), b2 + hstep, voffB); PG8_STAGE(PG8_SA(0, 0), a2, voffA);
.LBB0_257:
	s_ashr_i32 s55, s54, 31
	s_lshl_b64 s[56:57], s[54:55], 16
	s_add_u32 s56, s33, s56
	s_addc_u32 s57, s64, s57
	s_and_b64 s[58:59], s[0:1], exec
	s_cselect_b32 s63, s57, s61
	s_cselect_b32 s62, s56, s60
	s_ashr_i32 s53, s52, 31
	s_lshl_b64 s[58:59], s[52:53], 16
	s_add_u32 s58, s65, s58
	s_addc_u32 s59, s66, s59
	s_add_u32 s90, s60, 0x8080
	ds_read_b128 v[0:3], v150
	ds_read_b128 v[4:7], v150 offset:1024
	ds_read_b128 v[8:11], v150 offset:2048
	ds_read_b128 v[12:15], v150 offset:3072
	ds_read_b128 v[16:19], v151
	ds_read_b128 v[20:23], v151 offset:1024
	ds_read_b128 v[24:27], v151 offset:2048
	ds_read_b128 v[28:31], v151 offset:3072
	s_addc_u32 s91, s61, 0
	s_add_u32 s60, s62, 0x8000
	s_addc_u32 s61, s63, 0
	s_and_b64 s[92:93], s[0:1], exec
	s_cselect_b32 s10, s58, s10
	s_cselect_b32 s11, s59, s11
	s_add_u32 s92, s10, 0x8000
	s_addc_u32 s93, s11, 0
	v_lshl_add_u64 v[64:65], s[90:91], 0, v[128:129]
	s_add_i32 m0, s7, 0xc000
	ds_read_b128 v[32:35], v153
	ds_read_b128 v[36:39], v153 offset:1024
	ds_read_b128 v[40:43], v153 offset:2048
	ds_read_b128 v[44:47], v153 offset:3072
	ds_read_b128 v[48:51], v153 offset:4096
	ds_read_b128 v[52:55], v153 offset:5120
	ds_read_b128 v[56:59], v153 offset:6144
	ds_read_b128 v[60:63], v153 offset:7168
	global_load_lds_dwordx4 v[64:65], off
	v_lshl_add_u64 v[64:65], s[90:91], 0, v[132:133]
	s_add_i32 m0, s7, 0xe000
	s_nop 0
	global_load_lds_dwordx4 v[64:65], off
	s_waitcnt vmcnt(8)
	s_waitcnt lgkmcnt(0)
	s_barrier
	s_waitcnt lgkmcnt(0)
	v_mfma_f32_16x16x32_bf16 v[64:67], v[0:3], v[32:35], 0
	v_mfma_f32_16x16x32_bf16 v[68:71], v[8:11], v[32:35], 0
	v_mfma_f32_16x16x32_bf16 v[72:75], v[0:3], v[40:43], 0
	v_mfma_f32_16x16x32_bf16 v[76:79], v[8:11], v[40:43], 0
	v_mfma_f32_16x16x32_bf16 v[80:83], v[0:3], v[48:51], 0
	v_mfma_f32_16x16x32_bf16 v[84:87], v[8:11], v[48:51], 0
	v_mfma_f32_16x16x32_bf16 v[88:91], v[0:3], v[56:59], 0
	v_mfma_f32_16x16x32_bf16 v[92:95], v[8:11], v[56:59], 0
	v_mfma_f32_16x16x32_bf16 v[64:67], v[4:7], v[36:39], v[64:67]
	v_mfma_f32_16x16x32_bf16 v[68:71], v[12:15], v[36:39], v[68:71]
	v_mfma_f32_16x16x32_bf16 v[72:75], v[4:7], v[44:47], v[72:75]
	v_mfma_f32_16x16x32_bf16 v[76:79], v[12:15], v[44:47], v[76:79]
	v_mfma_f32_16x16x32_bf16 v[80:83], v[4:7], v[52:55], v[80:83]
	v_mfma_f32_16x16x32_bf16 v[84:87], v[12:15], v[52:55], v[84:87]
	v_mfma_f32_16x16x32_bf16 v[88:91], v[4:7], v[60:63], v[88:91]
	v_mfma_f32_16x16x32_bf16 v[92:95], v[12:15], v[60:63], v[92:95]
	v_mfma_f32_16x16x32_bf16 v[96:99], v[16:19], v[32:35], 0
	v_mfma_f32_16x16x32_bf16 v[32:35], v[24:27], v[32:35], 0
	v_mfma_f32_16x16x32_bf16 v[104:107], v[20:23], v[36:39], v[96:99]
	v_mfma_f32_16x16x32_bf16 v[32:35], v[28:31], v[36:39], v[32:35]
	v_mfma_f32_16x16x32_bf16 v[36:39], v[16:19], v[40:43], 0
	v_mfma_f32_16x16x32_bf16 v[40:43], v[24:27], v[40:43], 0
	v_mfma_f32_16x16x32_bf16 v[36:39], v[20:23], v[44:47], v[36:39]
	v_mfma_f32_16x16x32_bf16 v[40:43], v[28:31], v[44:47], v[40:43]
	v_mfma_f32_16x16x32_bf16 v[44:47], v[16:19], v[48:51], 0
	v_mfma_f32_16x16x32_bf16 v[48:51], v[24:27], v[48:51], 0
	v_mfma_f32_16x16x32_bf16 v[44:47], v[20:23], v[52:55], v[44:47]
	v_mfma_f32_16x16x32_bf16 v[48:51], v[28:31], v[52:55], v[48:51]
	v_mfma_f32_16x16x32_bf16 v[52:55], v[16:19], v[56:59], 0
	v_mfma_f32_16x16x32_bf16 v[56:59], v[24:27], v[56:59], 0
	v_mfma_f32_16x16x32_bf16 v[52:55], v[20:23], v[60:63], v[52:55]
	v_mfma_f32_16x16x32_bf16 v[56:59], v[28:31], v[60:63], v[56:59]
	s_barrier
	s_add_i32 s53, s82, s3
	v_lshl_add_u64 v[218:219], s[10:11], 0, v[130:131]
	s_mov_b32 m0, s53
	ds_read_b128 v[60:63], v153 offset:16384
	ds_read_b128 v[96:99], v153 offset:17408
	ds_read_b128 v[100:103], v153 offset:18432
	ds_read_b128 v[108:111], v153 offset:19456
	ds_read_b128 v[112:115], v153 offset:20480
	ds_read_b128 v[116:119], v153 offset:21504
	ds_read_b128 v[120:123], v153 offset:22528
	ds_read_b128 v[124:127], v153 offset:23552
	global_load_lds_dwordx4 v[218:219], off
	v_lshl_add_u64 v[242:243], s[10:11], 0, v[134:135]
	s_add_i32 m0, s53, 0x2000
	s_add_i32 s53, s83, s3
	global_load_lds_dwordx4 v[242:243], off
	v_lshl_add_u64 v[140:141], s[92:93], 0, v[130:131]
	s_mov_b32 m0, s53
	v_lshl_add_u64 v[244:245], s[62:63], 0, v[128:129]
	global_load_lds_dwordx4 v[140:141], off
	v_lshl_add_u64 v[140:141], s[92:93], 0, v[134:135]
	s_add_i32 m0, s53, 0x2000
	v_lshl_add_u64 v[246:247], s[62:63], 0, v[132:133]
	global_load_lds_dwordx4 v[140:141], off
	s_mov_b32 m0, s7
	s_nop 0
	global_load_lds_dwordx4 v[244:245], off
	s_mov_b32 m0, s67
	s_nop 0
	global_load_lds_dwordx4 v[246:247], off
	s_waitcnt vmcnt(8)
	s_waitcnt lgkmcnt(0)
	s_barrier
; #define PG8_STAGE(bufoff, gbase, voff) do { _Pragma("unroll") for (int _i = 0; _i < 2; ++_i) \
;         __builtin_amdgcn_global_load_lds((const unsigned*)((const char*)(gbase) + (voff)[_i]), (PG8_LAS unsigned*)(lds + (bufoff) + ldsw + _i * 8192), 16, 0, 0); } while (0)
; #define PG8_LDA(dst, b, h) do { _Pragma("unroll") for (int m = 0; m < 4; ++m) _Pragma("unroll") for (int k = 0; k < 2; ++k) dst[m][k] = *(const PG8_LAS bf16x8*)(lds + PG8_SA(b, h) + aoff + m * 2048 + k * 1024); } while (0)
; #define PG8_LDB(dst, b, h) do { _Pragma("unroll") for (int n = 0; n < 2; ++n) _Pragma("unroll") for (int k = 0; k < 2; ++k) dst[n][k] = *(const PG8_LAS bf16x8*)(lds + PG8_SB(b, h) + boff + n * 2048 + k * 1024); } while (0)
; #define PG8_MMA(ai, bj, At, Bt) do { __builtin_amdgcn_s_setprio(1); _Pragma("unroll") for (int m = 0; m < 4; ++m) _Pragma("unroll") for (int n = 0; n < 2; ++n) _Pragma("unroll") for (int k = 0; k < 2; ++k) \
;         acc[ai][bj][m][n] = __builtin_amdgcn_mfma_f32_16x16x32_bf16(Bt[n][k], At[m][k], acc[ai][bj][m][n], 0, 0, 0); __builtin_amdgcn_s_setprio(0); } while (0)
; #define PG8_WAIT_V(n) asm volatile("s_waitcnt vmcnt(" #n ")" ::: "memory")
; #define PG8_WAIT_L(n) asm volatile("s_waitcnt lgkmcnt(" #n ")" ::: "memory")
; #define PG8_BAR __builtin_amdgcn_s_barrier()
; #define PG8_SCHED __builtin_amdgcn_sched_barrier(0)
; template <class Epi, class Sched, bool ALIGN_EPI = false, bool SP2 = false>
; __device__ __forceinline__ void gemm_phase(PG8_LAS unsigned char* lds, const Gemm g, const Sched& S, const Epi& E) {
;     ...
;             PG8_LDA(At, 0, 1); PG8_STAGE(PG8_SB(0, 0), b2, voffB); PG8_STAGE(PG8_SB(0, 1), b2 + hstep, voffB); PG8_STAGE(PG8_SA(0, 0), a2, voffA);
;             PG8_WAIT_V(8); PG8_WAIT_L(0); PG8_BAR; PG8_MMA(1, 0, At, B0); PG8_MMA(1, 1, At, B1); PG8_BAR; PG8_SCHED;
;             PG8_LDB(B0, 1, 0); PG8_LDB(B1, 1, 1); PG8_SCHED; PG8_LDA(At, 1, 0); PG8_STAGE(PG8_SA(0, 1), a2 + hstep, voffA);
;             PG8_WAIT_V(8); PG8_WAIT_L(0); PG8_BAR; PG8_MMA(0, 0, At, B0); PG8_MMA(0, 1, At, B1); PG8_BAR; PG8_SCHED;
	s_waitcnt lgkmcnt(0)
	v_mfma_f32_16x16x32_bf16 v[140:143], v[0:3], v[60:63], 0
	v_mfma_f32_16x16x32_bf16 v[154:157], v[0:3], v[100:103], 0
	v_mfma_f32_16x16x32_bf16 v[162:165], v[0:3], v[112:115], 0
	v_mfma_f32_16x16x32_bf16 v[0:3], v[0:3], v[120:123], 0
	v_mfma_f32_16x16x32_bf16 v[140:143], v[4:7], v[96:99], v[140:143]
	v_mfma_f32_16x16x32_bf16 v[154:157], v[4:7], v[108:111], v[154:157]
	v_mfma_f32_16x16x32_bf16 v[162:165], v[4:7], v[116:119], v[162:165]
	v_mfma_f32_16x16x32_bf16 v[0:3], v[4:7], v[124:127], v[0:3]
	v_mfma_f32_16x16x32_bf16 v[4:7], v[8:11], v[120:123], 0
	v_mfma_f32_16x16x32_bf16 v[144:147], v[8:11], v[60:63], 0
	v_mfma_f32_16x16x32_bf16 v[158:161], v[8:11], v[100:103], 0
	v_mfma_f32_16x16x32_bf16 v[166:169], v[8:11], v[112:115], 0
	v_mfma_f32_16x16x32_bf16 v[4:7], v[12:15], v[124:127], v[4:7]
	v_mfma_f32_16x16x32_bf16 v[144:147], v[12:15], v[96:99], v[144:147]
	v_mfma_f32_16x16x32_bf16 v[158:161], v[12:15], v[108:111], v[158:161]
	v_mfma_f32_16x16x32_bf16 v[166:169], v[12:15], v[116:119], v[166:169]
	v_mfma_f32_16x16x32_bf16 v[8:11], v[16:19], v[60:63], 0
	v_mfma_f32_16x16x32_bf16 v[12:15], v[24:27], v[60:63], 0
	v_mfma_f32_16x16x32_bf16 v[60:63], v[16:19], v[100:103], 0
	v_mfma_f32_16x16x32_bf16 v[170:173], v[20:23], v[108:111], v[60:63]
	v_mfma_f32_16x16x32_bf16 v[60:63], v[24:27], v[100:103], 0
	v_mfma_f32_16x16x32_bf16 v[174:177], v[28:31], v[108:111], v[60:63]
	v_mfma_f32_16x16x32_bf16 v[60:63], v[16:19], v[112:115], 0
	v_mfma_f32_16x16x32_bf16 v[16:19], v[16:19], v[120:123], 0
	v_mfma_f32_16x16x32_bf16 v[8:11], v[20:23], v[96:99], v[8:11]
	v_mfma_f32_16x16x32_bf16 v[12:15], v[28:31], v[96:99], v[12:15]
	v_mfma_f32_16x16x32_bf16 v[178:181], v[20:23], v[116:119], v[60:63]
	v_mfma_f32_16x16x32_bf16 v[60:63], v[24:27], v[112:115], 0
	v_mfma_f32_16x16x32_bf16 v[186:189], v[20:23], v[124:127], v[16:19]
	v_mfma_f32_16x16x32_bf16 v[16:19], v[24:27], v[120:123], 0
	v_mfma_f32_16x16x32_bf16 v[182:185], v[28:31], v[116:119], v[60:63]
	v_mfma_f32_16x16x32_bf16 v[190:193], v[28:31], v[124:127], v[16:19]
	s_barrier
	s_add_i32 s53, 0, 0x18000
	s_nop 2
	v_add_u32_e32 v16, s53, v149
	s_add_i32 s55, 0, 0x1c000
	ds_read_b128 v[24:27], v16
	ds_read_b128 v[28:31], v16 offset:1024
	ds_read_b128 v[60:63], v16 offset:2048
	ds_read_b128 v[194:197], v16 offset:3072
	v_add_u32_e32 v16, s55, v149
	ds_read_b128 v[198:201], v16
	ds_read_b128 v[202:205], v16 offset:1024
	ds_read_b128 v[206:209], v16 offset:2048
	ds_read_b128 v[210:213], v16 offset:3072
	s_mov_b32 m0, s76
	v_lshl_add_u64 v[96:97], s[60:61], 0, v[128:129]
	ds_read_b128 v[16:19], v153 offset:32768
	ds_read_b128 v[20:23], v153 offset:33792
	ds_read_b128 v[108:111], v153 offset:34816
	ds_read_b128 v[214:217], v153 offset:35840
	ds_read_b128 v[222:225], v153 offset:36864
	ds_read_b128 v[226:229], v153 offset:37888
	ds_read_b128 v[230:233], v153 offset:38912
	ds_read_b128 v[234:237], v153 offset:39936
	global_load_lds_dwordx4 v[96:97], off
	v_lshl_add_u64 v[96:97], s[60:61], 0, v[132:133]
	s_mov_b32 m0, s77
	s_nop 0
	global_load_lds_dwordx4 v[96:97], off
	s_waitcnt vmcnt(8)
	s_waitcnt lgkmcnt(0)
	s_barrier
	s_waitcnt lgkmcnt(0)
	v_mfma_f32_16x16x32_bf16 v[64:67], v[24:27], v[16:19], v[64:67]
	v_mfma_f32_16x16x32_bf16 v[112:115], v[28:31], v[20:23], v[64:67]
	v_mfma_f32_16x16x32_bf16 v[64:67], v[60:63], v[16:19], v[68:71]
	v_mfma_f32_16x16x32_bf16 v[116:119], v[194:197], v[20:23], v[64:67]
	v_mfma_f32_16x16x32_bf16 v[64:67], v[24:27], v[108:111], v[72:75]
	v_mfma_f32_16x16x32_bf16 v[96:99], v[28:31], v[214:217], v[64:67]
	v_mfma_f32_16x16x32_bf16 v[64:67], v[60:63], v[108:111], v[76:79]
	v_mfma_f32_16x16x32_bf16 v[100:103], v[194:197], v[214:217], v[64:67]
	v_mfma_f32_16x16x32_bf16 v[64:67], v[24:27], v[222:225], v[80:83]
	v_mfma_f32_16x16x32_bf16 v[80:83], v[28:31], v[226:229], v[64:67]
	v_mfma_f32_16x16x32_bf16 v[64:67], v[60:63], v[222:225], v[84:87]
	v_mfma_f32_16x16x32_bf16 v[84:87], v[194:197], v[226:229], v[64:67]
	v_mfma_f32_16x16x32_bf16 v[64:67], v[24:27], v[230:233], v[88:91]
	v_mfma_f32_16x16x32_bf16 v[68:71], v[60:63], v[230:233], v[92:95]
	v_mfma_f32_16x16x32_bf16 v[64:67], v[28:31], v[234:237], v[64:67]
	v_mfma_f32_16x16x32_bf16 v[68:71], v[194:197], v[234:237], v[68:71]
	v_mfma_f32_16x16x32_bf16 v[72:75], v[198:201], v[16:19], v[104:107]
	v_mfma_f32_16x16x32_bf16 v[16:19], v[206:209], v[16:19], v[32:35]
	v_mfma_f32_16x16x32_bf16 v[124:127], v[210:213], v[20:23], v[16:19]
	v_mfma_f32_16x16x32_bf16 v[16:19], v[198:201], v[108:111], v[36:39]
	v_mfma_f32_16x16x32_bf16 v[104:107], v[202:205], v[214:217], v[16:19]
	v_mfma_f32_16x16x32_bf16 v[16:19], v[206:209], v[108:111], v[40:43]
	v_mfma_f32_16x16x32_bf16 v[108:111], v[210:213], v[214:217], v[16:19]
	v_mfma_f32_16x16x32_bf16 v[16:19], v[198:201], v[222:225], v[44:47]
	v_mfma_f32_16x16x32_bf16 v[88:91], v[202:205], v[226:229], v[16:19]
	v_mfma_f32_16x16x32_bf16 v[16:19], v[206:209], v[222:225], v[48:51]
	v_mfma_f32_16x16x32_bf16 v[92:95], v[210:213], v[226:229], v[16:19]
	v_mfma_f32_16x16x32_bf16 v[16:19], v[198:201], v[230:233], v[52:55]
	v_mfma_f32_16x16x32_bf16 v[120:123], v[202:205], v[20:23], v[72:75]
	v_mfma_f32_16x16x32_bf16 v[72:75], v[202:205], v[234:237], v[16:19]
	v_mfma_f32_16x16x32_bf16 v[16:19], v[206:209], v[230:233], v[56:59]
	v_mfma_f32_16x16x32_bf16 v[76:79], v[210:213], v[234:237], v[16:19]
	s_barrier
; #define PG8_STAGE(bufoff, gbase, voff) do { _Pragma("unroll") for (int _i = 0; _i < 2; ++_i) \
;         __builtin_amdgcn_global_load_lds((const unsigned*)((const char*)(gbase) + (voff)[_i]), (PG8_LAS unsigned*)(lds + (bufoff) + ldsw + _i * 8192), 16, 0, 0); } while (0)
; #define PG8_LDA(dst, b, h) do { _Pragma("unroll") for (int m = 0; m < 4; ++m) _Pragma("unroll") for (int k = 0; k < 2; ++k) dst[m][k] = *(const PG8_LAS bf16x8*)(lds + PG8_SA(b, h) + aoff + m * 2048 + k * 1024); } while (0)
; #define PG8_MMA(ai, bj, At, Bt) do { __builtin_amdgcn_s_setprio(1); _Pragma("unroll") for (int m = 0; m < 4; ++m) _Pragma("unroll") for (int n = 0; n < 2; ++n) _Pragma("unroll") for (int k = 0; k < 2; ++k) \
;         acc[ai][bj][m][n] = __builtin_amdgcn_mfma_f32_16x16x32_bf16(Bt[n][k], At[m][k], acc[ai][bj][m][n], 0, 0, 0); __builtin_amdgcn_s_setprio(0); } while (0)
; #define PG8_WAIT_V(n) asm volatile("s_waitcnt vmcnt(" #n ")" ::: "memory")
; #define PG8_WAIT_L(n) asm volatile("s_waitcnt lgkmcnt(" #n ")" ::: "memory")
; #define PG8_BAR __builtin_amdgcn_s_barrier()
; #define PG8_SCHED __builtin_amdgcn_sched_barrier(0)
; template <class Epi, class Sched, bool ALIGN_EPI = false, bool SP2 = false>
; __device__ __forceinline__ void gemm_phase(PG8_LAS unsigned char* lds, const Gemm g, const Sched& S, const Epi& E) {
;     ...
;             PG8_LDA(At, 1, 1); PG8_STAGE(PG8_SB(1, 0), b3, voffB); PG8_STAGE(PG8_SB(1, 1), b3 + hstep, voffB); PG8_STAGE(PG8_SA(1, 0), a3, voffA);
;             PG8_WAIT_V(8); PG8_WAIT_L(0); PG8_BAR; PG8_MMA(1, 0, At, B0); PG8_MMA(1, 1, At, B1); PG8_BAR; PG8_SCHED;
;     ...
;         if constexpr (ALIGN_EPI) { if (wr == 0) PG8_BAR; }
;         if constexpr (!Epi::AFTER_DRAIN) { E(acc, cur, wr, wc, fr, fq); S.done(cur); }
;         if (!has_next) break;
	s_add_i32 s53, s53, s3
	s_nop 3
	v_lshl_add_u64 v[16:17], v[218:219], 0, s[20:21]
	s_mov_b32 m0, s53
	ds_read_b128 v[40:43], v153 offset:49152
	ds_read_b128 v[44:47], v153 offset:50176
	ds_read_b128 v[214:217], v153 offset:51200
	ds_read_b128 v[222:225], v153 offset:52224
	ds_read_b128 v[226:229], v153 offset:53248
	ds_read_b128 v[230:233], v153 offset:54272
	ds_read_b128 v[234:237], v153 offset:55296
	ds_read_b128 v[238:241], v153 offset:56320
	global_load_lds_dwordx4 v[16:17], off
	s_add_i32 m0, s53, 0x2000
	s_add_u32 s10, s10, 0x8080
	v_lshl_add_u64 v[16:17], v[242:243], 0, s[20:21]
	s_addc_u32 s11, s11, 0
	s_add_i32 s53, s55, s3
	global_load_lds_dwordx4 v[16:17], off
	v_lshl_add_u64 v[16:17], s[10:11], 0, v[130:131]
	s_mov_b32 m0, s53
	s_nop 0
	global_load_lds_dwordx4 v[16:17], off
	v_lshl_add_u64 v[16:17], s[10:11], 0, v[134:135]
	s_add_i32 m0, s53, 0x2000
	s_nop 0
	global_load_lds_dwordx4 v[16:17], off
	v_lshl_add_u64 v[16:17], v[244:245], 0, s[20:21]
	s_mov_b32 m0, s78
	s_nop 0
	global_load_lds_dwordx4 v[16:17], off
	v_lshl_add_u64 v[16:17], v[246:247], 0, s[20:21]
	s_mov_b32 m0, s79
	s_nop 0
	global_load_lds_dwordx4 v[16:17], off
	s_waitcnt vmcnt(8)
	s_waitcnt lgkmcnt(0)
	s_barrier
	s_waitcnt lgkmcnt(0)
	v_mfma_f32_16x16x32_bf16 v[16:19], v[24:27], v[40:43], v[140:143]
	v_mfma_f32_16x16x32_bf16 v[48:51], v[28:31], v[44:47], v[16:19]
	v_mfma_f32_16x16x32_bf16 v[16:19], v[60:63], v[40:43], v[144:147]
	v_mfma_f32_16x16x32_bf16 v[52:55], v[194:197], v[44:47], v[16:19]
	v_mfma_f32_16x16x32_bf16 v[16:19], v[24:27], v[214:217], v[154:157]
	v_mfma_f32_16x16x32_bf16 v[32:35], v[28:31], v[222:225], v[16:19]
	v_mfma_f32_16x16x32_bf16 v[16:19], v[60:63], v[214:217], v[158:161]
	v_mfma_f32_16x16x32_bf16 v[36:39], v[194:197], v[222:225], v[16:19]
	v_mfma_f32_16x16x32_bf16 v[16:19], v[24:27], v[226:229], v[162:165]
	v_mfma_f32_16x16x32_bf16 v[20:23], v[60:63], v[226:229], v[166:169]
	v_mfma_f32_16x16x32_bf16 v[0:3], v[24:27], v[234:237], v[0:3]
	v_mfma_f32_16x16x32_bf16 v[4:7], v[60:63], v[234:237], v[4:7]
	v_mfma_f32_16x16x32_bf16 v[16:19], v[28:31], v[230:233], v[16:19]
	v_mfma_f32_16x16x32_bf16 v[20:23], v[194:197], v[230:233], v[20:23]
	v_mfma_f32_16x16x32_bf16 v[0:3], v[28:31], v[238:241], v[0:3]
	v_mfma_f32_16x16x32_bf16 v[4:7], v[194:197], v[238:241], v[4:7]
	v_mfma_f32_16x16x32_bf16 v[8:11], v[198:201], v[40:43], v[8:11]
	v_mfma_f32_16x16x32_bf16 v[56:59], v[202:205], v[44:47], v[8:11]
	v_mfma_f32_16x16x32_bf16 v[8:11], v[206:209], v[40:43], v[12:15]
	v_mfma_f32_16x16x32_bf16 v[60:63], v[210:213], v[44:47], v[8:11]
	v_mfma_f32_16x16x32_bf16 v[8:11], v[198:201], v[214:217], v[170:173]
	v_mfma_f32_16x16x32_bf16 v[40:43], v[202:205], v[222:225], v[8:11]
	v_mfma_f32_16x16x32_bf16 v[8:11], v[206:209], v[214:217], v[174:177]
	v_mfma_f32_16x16x32_bf16 v[44:47], v[210:213], v[222:225], v[8:11]
	v_mfma_f32_16x16x32_bf16 v[8:11], v[198:201], v[226:229], v[178:181]
	v_mfma_f32_16x16x32_bf16 v[24:27], v[202:205], v[230:233], v[8:11]
	v_mfma_f32_16x16x32_bf16 v[8:11], v[206:209], v[226:229], v[182:185]
	v_mfma_f32_16x16x32_bf16 v[28:31], v[210:213], v[230:233], v[8:11]
	v_mfma_f32_16x16x32_bf16 v[8:11], v[198:201], v[234:237], v[186:189]
	v_mfma_f32_16x16x32_bf16 v[12:15], v[206:209], v[234:237], v[190:193]
	v_mfma_f32_16x16x32_bf16 v[8:11], v[202:205], v[238:241], v[8:11]
	v_mfma_f32_16x16x32_bf16 v[12:15], v[210:213], v[238:241], v[12:15]
	s_barrier
	s_andn2_b64 vcc, exec, s[26:27]
	s_cbranch_vccnz .LBB0_259
	s_barrier

; #define PG8_STAGE(bufoff, gbase, voff) do { _Pragma("unroll") for (int _i = 0; _i < 2; ++_i) \
;         __builtin_amdgcn_global_load_lds((const unsigned*)((const char*)(gbase) + (voff)[_i]), (PG8_LAS unsigned*)(lds + (bufoff) + ldsw + _i * 8192), 16, 0, 0); } while (0)
; #define PG8_LDA(dst, b, h) do { _Pragma("unroll") for (int m = 0; m < 4; ++m) _Pragma("unroll") for (int k = 0; k < 2; ++k) dst[m][k] = *(const PG8_LAS bf16x8*)(lds + PG8_SA(b, h) + aoff + m * 2048 + k * 1024); } while (0)
; #define PG8_LDB(dst, b, h) do { _Pragma("unroll") for (int n = 0; n < 2; ++n) _Pragma("unroll") for (int k = 0; k < 2; ++k) dst[n][k] = *(const PG8_LAS bf16x8*)(lds + PG8_SB(b, h) + boff + n * 2048 + k * 1024); } while (0)
; #define PG8_WAIT_V(n) asm volatile("s_waitcnt vmcnt(" #n ")" ::: "memory")
; #define PG8_WAIT_L(n) asm volatile("s_waitcnt lgkmcnt(" #n ")" ::: "memory")
; #define PG8_BAR __builtin_amdgcn_s_barrier()
; #define PG8_SCHED __builtin_amdgcn_sched_barrier(0)
; template <class Epi, class Sched, bool ALIGN_EPI = false, bool SP2 = false>
; __device__ __forceinline__ void gemm_phase(PG8_LAS unsigned char* lds, const Gemm g, const Sched& S, const Epi& E) {
;     ...
;         const bool has_next = S.next(ui + 1, nxt);
;         const char* nA = has_next ? (const char*)g.A + (size_t)nxt.pm * tstep : cA; const char* nB = has_next ? (const char*)g.Bt + (size_t)nxt.pn * tstep : cB;
;         for (int t = 0; t < nt; t += 2) {
;             const bool last = (t == nt - 2);
;             const char* a1 = cA + (size_t)(t + 1) * kstep;
;             const char* a2 = last ? nA : cA + (size_t)(t + 2) * kstep; const char* b2 = last ? nB : cB + (size_t)(t + 2) * kstep;
;             const char* a3 = a2 + kstep; const char* b3 = b2 + kstep;
;             if (last && has_next) S.a_ready(nxt);
;             if constexpr (SP2) {
;             PG8_LDB(B0, 0, 0); PG8_LDB(B1, 0, 1); PG8_SCHED; PG8_LDA(At, 0, 0); PG8_STAGE(PG8_SA(1, 1), a1 + hstep, voffA);
;             PG8_WAIT_V(8); PG8_WAIT_L(0); PG8_BAR; PG8_MMA(0, 0, At, B0); PG8_MMA(0, 1, At, B1); PG8_BAR; PG8_SCHED;
;             PG8_LDA(At, 0, 1); PG8_STAGE(PG8_SB(0, 0), b2, voffB); PG8_STAGE(PG8_SB(0, 1), b2 + hstep, voffB); PG8_STAGE(PG8_SA(0, 0), a2, voffA);
;             PG8_WAIT_V(8); PG8_WAIT_L(0); PG8_BAR; PG8_MMA(1, 0, At, B0); PG8_MMA(1, 1, At, B1); PG8_BAR; PG8_SCHED;
.LBB0_480:
	ds_read_b128 v[88:91], v225
	ds_read_b128 v[92:95], v225 offset:1024
	ds_read_b128 v[96:99], v225 offset:2048
	ds_read_b128 v[104:107], v225 offset:3072
	ds_read_b128 v[144:147], v226
	ds_read_b128 v[148:151], v226 offset:1024
	ds_read_b128 v[152:155], v226 offset:2048
	ds_read_b128 v[156:159], v226 offset:3072
	s_add_u32 s6, s8, 0xfffc0080
	s_addc_u32 s7, s9, -1
	s_cmp_eq_u32 s77, 12
	s_cselect_b32 s11, s47, s7
	s_cselect_b32 s10, s65, s6
	s_cselect_b32 s7, s35, s76
	s_cselect_b32 s6, s66, s67
	v_lshl_add_u64 v[208:209], s[8:9], 0, v[200:201]
	s_add_i32 m0, s33, 0xc000
	ds_read_b128 v[160:163], v227
	ds_read_b128 v[164:167], v227 offset:1024
	ds_read_b128 v[168:171], v227 offset:2048
	ds_read_b128 v[172:175], v227 offset:3072
	ds_read_b128 v[176:179], v227 offset:4096
	ds_read_b128 v[180:183], v227 offset:5120
	ds_read_b128 v[184:187], v227 offset:6144
	ds_read_b128 v[188:191], v227 offset:7168
	global_load_lds_dwordx4 v[208:209], off
	v_lshl_add_u64 v[208:209], s[8:9], 0, v[202:203]
	s_add_i32 m0, s33, 0xe000
	s_nop 0
	global_load_lds_dwordx4 v[208:209], off
	s_waitcnt vmcnt(8)
	s_waitcnt lgkmcnt(0)
	s_barrier
	s_waitcnt lgkmcnt(0)
	v_mfma_f32_16x16x32_bf16 v[140:143], v[88:91], v[160:163], v[140:143]
	v_mfma_f32_16x16x32_bf16 v[136:139], v[96:99], v[160:163], v[136:139]
	v_mfma_f32_16x16x32_bf16 v[124:127], v[88:91], v[168:171], v[124:127]
	v_mfma_f32_16x16x32_bf16 v[120:123], v[96:99], v[168:171], v[120:123]
	v_mfma_f32_16x16x32_bf16 v[108:111], v[88:91], v[176:179], v[108:111]
	v_mfma_f32_16x16x32_bf16 v[100:103], v[96:99], v[176:179], v[100:103]
	v_mfma_f32_16x16x32_bf16 v[76:79], v[88:91], v[184:187], v[76:79]
	v_mfma_f32_16x16x32_bf16 v[72:75], v[96:99], v[184:187], v[72:75]
	v_mfma_f32_16x16x32_bf16 v[140:143], v[92:95], v[164:167], v[140:143]
	v_mfma_f32_16x16x32_bf16 v[136:139], v[104:107], v[164:167], v[136:139]
	v_mfma_f32_16x16x32_bf16 v[124:127], v[92:95], v[172:175], v[124:127]
	v_mfma_f32_16x16x32_bf16 v[120:123], v[104:107], v[172:175], v[120:123]
	v_mfma_f32_16x16x32_bf16 v[108:111], v[92:95], v[180:183], v[108:111]
	v_mfma_f32_16x16x32_bf16 v[100:103], v[104:107], v[180:183], v[100:103]
	v_mfma_f32_16x16x32_bf16 v[76:79], v[92:95], v[188:191], v[76:79]
	v_mfma_f32_16x16x32_bf16 v[72:75], v[104:107], v[188:191], v[72:75]
	v_mfma_f32_16x16x32_bf16 v[132:135], v[144:147], v[160:163], v[132:135]
	v_mfma_f32_16x16x32_bf16 v[128:131], v[152:155], v[160:163], v[128:131]
	v_mfma_f32_16x16x32_bf16 v[116:119], v[144:147], v[168:171], v[116:119]
	v_mfma_f32_16x16x32_bf16 v[112:115], v[152:155], v[168:171], v[112:115]
	v_mfma_f32_16x16x32_bf16 v[84:87], v[144:147], v[176:179], v[84:87]
	v_mfma_f32_16x16x32_bf16 v[80:83], v[152:155], v[176:179], v[80:83]
	v_mfma_f32_16x16x32_bf16 v[68:71], v[144:147], v[184:187], v[68:71]
	v_mfma_f32_16x16x32_bf16 v[64:67], v[152:155], v[184:187], v[64:67]
	v_mfma_f32_16x16x32_bf16 v[132:135], v[148:151], v[164:167], v[132:135]
	v_mfma_f32_16x16x32_bf16 v[128:131], v[156:159], v[164:167], v[128:131]
	v_mfma_f32_16x16x32_bf16 v[116:119], v[148:151], v[172:175], v[116:119]
	v_mfma_f32_16x16x32_bf16 v[112:115], v[156:159], v[172:175], v[112:115]
	v_mfma_f32_16x16x32_bf16 v[84:87], v[148:151], v[180:183], v[84:87]
	v_mfma_f32_16x16x32_bf16 v[80:83], v[156:159], v[180:183], v[80:83]
	v_mfma_f32_16x16x32_bf16 v[68:71], v[148:151], v[188:191], v[68:71]
	v_mfma_f32_16x16x32_bf16 v[64:67], v[156:159], v[188:191], v[64:67]
	s_barrier
	s_add_i32 s78, s62, s3
	v_lshl_add_u64 v[208:209], s[6:7], 0, v[194:195]
	s_mov_b32 m0, s78
	ds_read_b128 v[160:163], v227 offset:16384
	ds_read_b128 v[164:167], v227 offset:17408
	ds_read_b128 v[168:171], v227 offset:18432
	ds_read_b128 v[172:175], v227 offset:19456
	ds_read_b128 v[176:179], v227 offset:20480
	ds_read_b128 v[180:183], v227 offset:21504
	ds_read_b128 v[184:187], v227 offset:22528
	ds_read_b128 v[188:191], v227 offset:23552
	global_load_lds_dwordx4 v[208:209], off
	s_add_i32 m0, s78, 0x2000
	s_add_u32 s78, s6, 0x40000
	v_lshl_add_u64 v[210:211], s[6:7], 0, v[198:199]
	s_addc_u32 s79, s7, 0
	s_add_i32 s80, s63, s3
	global_load_lds_dwordx4 v[210:211], off
	v_lshl_add_u64 v[212:213], s[78:79], 0, v[194:195]
	s_mov_b32 m0, s80
	v_lshl_add_u64 v[214:215], s[10:11], 0, v[196:197]
	global_load_lds_dwordx4 v[212:213], off
	v_lshl_add_u64 v[212:213], s[78:79], 0, v[198:199]
	s_add_i32 m0, s80, 0x2000
	s_nop 0
	global_load_lds_dwordx4 v[212:213], off
	v_lshl_add_u64 v[212:213], s[10:11], 0, v[192:193]
	s_mov_b32 m0, s33
	s_nop 0
	global_load_lds_dwordx4 v[212:213], off
	s_mov_b32 m0, s53
	s_nop 0
	global_load_lds_dwordx4 v[214:215], off
	s_waitcnt vmcnt(8)
	s_waitcnt lgkmcnt(0)
	s_barrier
; #define PG8_STAGE(bufoff, gbase, voff) do { _Pragma("unroll") for (int _i = 0; _i < 2; ++_i) \
;         __builtin_amdgcn_global_load_lds((const unsigned*)((const char*)(gbase) + (voff)[_i]), (PG8_LAS unsigned*)(lds + (bufoff) + ldsw + _i * 8192), 16, 0, 0); } while (0)
; #define PG8_LDA(dst, b, h) do { _Pragma("unroll") for (int m = 0; m < 4; ++m) _Pragma("unroll") for (int k = 0; k < 2; ++k) dst[m][k] = *(const PG8_LAS bf16x8*)(lds + PG8_SA(b, h) + aoff + m * 2048 + k * 1024); } while (0)
; #define PG8_LDB(dst, b, h) do { _Pragma("unroll") for (int n = 0; n < 2; ++n) _Pragma("unroll") for (int k = 0; k < 2; ++k) dst[n][k] = *(const PG8_LAS bf16x8*)(lds + PG8_SB(b, h) + boff + n * 2048 + k * 1024); } while (0)
; #define PG8_MMA(ai, bj, At, Bt) do { __builtin_amdgcn_s_setprio(1); _Pragma("unroll") for (int m = 0; m < 4; ++m) _Pragma("unroll") for (int n = 0; n < 2; ++n) _Pragma("unroll") for (int k = 0; k < 2; ++k) \
;         acc[ai][bj][m][n] = __builtin_amdgcn_mfma_f32_16x16x32_bf16(Bt[n][k], At[m][k], acc[ai][bj][m][n], 0, 0, 0); __builtin_amdgcn_s_setprio(0); } while (0)
; #define PG8_WAIT_V(n) asm volatile("s_waitcnt vmcnt(" #n ")" ::: "memory")
; #define PG8_WAIT_L(n) asm volatile("s_waitcnt lgkmcnt(" #n ")" ::: "memory")
; #define PG8_BAR __builtin_amdgcn_s_barrier()
; #define PG8_SCHED __builtin_amdgcn_sched_barrier(0)
; template <class Epi, class Sched, bool ALIGN_EPI = false, bool SP2 = false>
; __device__ __forceinline__ void gemm_phase(PG8_LAS unsigned char* lds, const Gemm g, const Sched& S, const Epi& E) {
;     ...
;             PG8_WAIT_V(8); PG8_WAIT_L(0); PG8_BAR; PG8_MMA(1, 0, At, B0); PG8_MMA(1, 1, At, B1); PG8_BAR; PG8_SCHED;
;             PG8_LDB(B0, 1, 0); PG8_LDB(B1, 1, 1); PG8_SCHED; PG8_LDA(At, 1, 0); PG8_STAGE(PG8_SA(0, 1), a2 + hstep, voffA);
;             PG8_WAIT_V(8); PG8_WAIT_L(0); PG8_BAR; PG8_MMA(0, 0, At, B0); PG8_MMA(0, 1, At, B1); PG8_BAR; PG8_SCHED;
	s_waitcnt lgkmcnt(0)
	v_mfma_f32_16x16x32_bf16 v[60:63], v[88:91], v[160:163], v[60:63]
	v_mfma_f32_16x16x32_bf16 v[56:59], v[96:99], v[160:163], v[56:59]
	v_mfma_f32_16x16x32_bf16 v[44:47], v[88:91], v[168:171], v[44:47]
	v_mfma_f32_16x16x32_bf16 v[40:43], v[96:99], v[168:171], v[40:43]
	v_mfma_f32_16x16x32_bf16 v[28:31], v[88:91], v[176:179], v[28:31]
	v_mfma_f32_16x16x32_bf16 v[24:27], v[96:99], v[176:179], v[24:27]
	v_mfma_f32_16x16x32_bf16 v[12:15], v[88:91], v[184:187], v[12:15]
	v_mfma_f32_16x16x32_bf16 v[8:11], v[96:99], v[184:187], v[8:11]
	v_mfma_f32_16x16x32_bf16 v[60:63], v[92:95], v[164:167], v[60:63]
	v_mfma_f32_16x16x32_bf16 v[56:59], v[104:107], v[164:167], v[56:59]
	v_mfma_f32_16x16x32_bf16 v[44:47], v[92:95], v[172:175], v[44:47]
	v_mfma_f32_16x16x32_bf16 v[40:43], v[104:107], v[172:175], v[40:43]
	v_mfma_f32_16x16x32_bf16 v[28:31], v[92:95], v[180:183], v[28:31]
	v_mfma_f32_16x16x32_bf16 v[24:27], v[104:107], v[180:183], v[24:27]
	v_mfma_f32_16x16x32_bf16 v[12:15], v[92:95], v[188:191], v[12:15]
	v_mfma_f32_16x16x32_bf16 v[8:11], v[104:107], v[188:191], v[8:11]
	v_mfma_f32_16x16x32_bf16 v[52:55], v[144:147], v[160:163], v[52:55]
	v_mfma_f32_16x16x32_bf16 v[48:51], v[152:155], v[160:163], v[48:51]
	v_mfma_f32_16x16x32_bf16 v[36:39], v[144:147], v[168:171], v[36:39]
	v_mfma_f32_16x16x32_bf16 v[32:35], v[152:155], v[168:171], v[32:35]
	v_mfma_f32_16x16x32_bf16 v[20:23], v[144:147], v[176:179], v[20:23]
	v_mfma_f32_16x16x32_bf16 v[16:19], v[152:155], v[176:179], v[16:19]
	v_mfma_f32_16x16x32_bf16 v[4:7], v[144:147], v[184:187], v[4:7]
	v_mfma_f32_16x16x32_bf16 v[0:3], v[152:155], v[184:187], v[0:3]
	v_mfma_f32_16x16x32_bf16 v[52:55], v[148:151], v[164:167], v[52:55]
	v_mfma_f32_16x16x32_bf16 v[48:51], v[156:159], v[164:167], v[48:51]
	v_mfma_f32_16x16x32_bf16 v[36:39], v[148:151], v[172:175], v[36:39]
	v_mfma_f32_16x16x32_bf16 v[32:35], v[156:159], v[172:175], v[32:35]
	v_mfma_f32_16x16x32_bf16 v[20:23], v[148:151], v[180:183], v[20:23]
	v_mfma_f32_16x16x32_bf16 v[16:19], v[156:159], v[180:183], v[16:19]
	v_mfma_f32_16x16x32_bf16 v[4:7], v[148:151], v[188:191], v[4:7]
	v_mfma_f32_16x16x32_bf16 v[0:3], v[156:159], v[188:191], v[0:3]
	s_barrier
	s_add_i32 s78, 0, 0x18000
	s_add_i32 s79, 0, 0x1c000
	v_add_u32_e32 v104, s78, v223
	v_add_u32_e32 v156, s79, v223
	ds_read_b128 v[88:91], v104
	ds_read_b128 v[92:95], v104 offset:1024
	ds_read_b128 v[96:99], v104 offset:2048
	ds_read_b128 v[104:107], v104 offset:3072
	ds_read_b128 v[144:147], v156
	ds_read_b128 v[148:151], v156 offset:1024
	ds_read_b128 v[152:155], v156 offset:2048
	ds_read_b128 v[156:159], v156 offset:3072
	s_add_u32 s10, s10, 0x40000
	s_addc_u32 s11, s11, 0
	s_mov_b32 m0, s54
	v_lshl_add_u64 v[216:217], s[10:11], 0, v[192:193]
	ds_read_b128 v[160:163], v227 offset:32768
	ds_read_b128 v[164:167], v227 offset:33792
	ds_read_b128 v[168:171], v227 offset:34816
	ds_read_b128 v[172:175], v227 offset:35840
	ds_read_b128 v[176:179], v227 offset:36864
	ds_read_b128 v[180:183], v227 offset:37888
	ds_read_b128 v[184:187], v227 offset:38912
	ds_read_b128 v[188:191], v227 offset:39936
	global_load_lds_dwordx4 v[216:217], off
	v_lshl_add_u64 v[216:217], s[10:11], 0, v[196:197]
	s_mov_b32 m0, s55
	s_nop 0
	global_load_lds_dwordx4 v[216:217], off
	s_waitcnt vmcnt(8)
	s_waitcnt lgkmcnt(0)
	s_barrier
	s_waitcnt lgkmcnt(0)
	v_mfma_f32_16x16x32_bf16 v[140:143], v[88:91], v[160:163], v[140:143]
	v_mfma_f32_16x16x32_bf16 v[136:139], v[96:99], v[160:163], v[136:139]
	v_mfma_f32_16x16x32_bf16 v[124:127], v[88:91], v[168:171], v[124:127]
	v_mfma_f32_16x16x32_bf16 v[120:123], v[96:99], v[168:171], v[120:123]
	v_mfma_f32_16x16x32_bf16 v[108:111], v[88:91], v[176:179], v[108:111]
	v_mfma_f32_16x16x32_bf16 v[100:103], v[96:99], v[176:179], v[100:103]
	v_mfma_f32_16x16x32_bf16 v[76:79], v[88:91], v[184:187], v[76:79]
	v_mfma_f32_16x16x32_bf16 v[72:75], v[96:99], v[184:187], v[72:75]
	v_mfma_f32_16x16x32_bf16 v[140:143], v[92:95], v[164:167], v[140:143]
	v_mfma_f32_16x16x32_bf16 v[136:139], v[104:107], v[164:167], v[136:139]
	v_mfma_f32_16x16x32_bf16 v[124:127], v[92:95], v[172:175], v[124:127]
	v_mfma_f32_16x16x32_bf16 v[120:123], v[104:107], v[172:175], v[120:123]
	v_mfma_f32_16x16x32_bf16 v[108:111], v[92:95], v[180:183], v[108:111]
	v_mfma_f32_16x16x32_bf16 v[100:103], v[104:107], v[180:183], v[100:103]
	v_mfma_f32_16x16x32_bf16 v[76:79], v[92:95], v[188:191], v[76:79]
	v_mfma_f32_16x16x32_bf16 v[72:75], v[104:107], v[188:191], v[72:75]
	v_mfma_f32_16x16x32_bf16 v[132:135], v[144:147], v[160:163], v[132:135]
	v_mfma_f32_16x16x32_bf16 v[128:131], v[152:155], v[160:163], v[128:131]
	v_mfma_f32_16x16x32_bf16 v[116:119], v[144:147], v[168:171], v[116:119]
	v_mfma_f32_16x16x32_bf16 v[112:115], v[152:155], v[168:171], v[112:115]
	v_mfma_f32_16x16x32_bf16 v[84:87], v[144:147], v[176:179], v[84:87]
	v_mfma_f32_16x16x32_bf16 v[80:83], v[152:155], v[176:179], v[80:83]
	v_mfma_f32_16x16x32_bf16 v[68:71], v[144:147], v[184:187], v[68:71]
	v_mfma_f32_16x16x32_bf16 v[64:67], v[152:155], v[184:187], v[64:67]
	v_mfma_f32_16x16x32_bf16 v[132:135], v[148:151], v[164:167], v[132:135]
	v_mfma_f32_16x16x32_bf16 v[128:131], v[156:159], v[164:167], v[128:131]
	v_mfma_f32_16x16x32_bf16 v[116:119], v[148:151], v[172:175], v[116:119]
	v_mfma_f32_16x16x32_bf16 v[112:115], v[156:159], v[172:175], v[112:115]
	v_mfma_f32_16x16x32_bf16 v[84:87], v[148:151], v[180:183], v[84:87]
	v_mfma_f32_16x16x32_bf16 v[80:83], v[156:159], v[180:183], v[80:83]
	v_mfma_f32_16x16x32_bf16 v[68:71], v[148:151], v[188:191], v[68:71]
	v_mfma_f32_16x16x32_bf16 v[64:67], v[156:159], v[188:191], v[64:67]
	s_barrier
; #define PG8_STAGE(bufoff, gbase, voff) do { _Pragma("unroll") for (int _i = 0; _i < 2; ++_i) \
;         __builtin_amdgcn_global_load_lds((const unsigned*)((const char*)(gbase) + (voff)[_i]), (PG8_LAS unsigned*)(lds + (bufoff) + ldsw + _i * 8192), 16, 0, 0); } while (0)
; #define PG8_LDA(dst, b, h) do { _Pragma("unroll") for (int m = 0; m < 4; ++m) _Pragma("unroll") for (int k = 0; k < 2; ++k) dst[m][k] = *(const PG8_LAS bf16x8*)(lds + PG8_SA(b, h) + aoff + m * 2048 + k * 1024); } while (0)
; #define PG8_MMA(ai, bj, At, Bt) do { __builtin_amdgcn_s_setprio(1); _Pragma("unroll") for (int m = 0; m < 4; ++m) _Pragma("unroll") for (int n = 0; n < 2; ++n) _Pragma("unroll") for (int k = 0; k < 2; ++k) \
;         acc[ai][bj][m][n] = __builtin_amdgcn_mfma_f32_16x16x32_bf16(Bt[n][k], At[m][k], acc[ai][bj][m][n], 0, 0, 0); __builtin_amdgcn_s_setprio(0); } while (0)
; #define PG8_WAIT_V(n) asm volatile("s_waitcnt vmcnt(" #n ")" ::: "memory")
; #define PG8_WAIT_L(n) asm volatile("s_waitcnt lgkmcnt(" #n ")" ::: "memory")
; #define PG8_BAR __builtin_amdgcn_s_barrier()
; #define PG8_SCHED __builtin_amdgcn_sched_barrier(0)
; template <class Epi, class Sched, bool ALIGN_EPI = false, bool SP2 = false>
; __device__ __forceinline__ void gemm_phase(PG8_LAS unsigned char* lds, const Gemm g, const Sched& S, const Epi& E) {
;     ...
;             PG8_LDA(At, 1, 1); PG8_STAGE(PG8_SB(1, 0), b3, voffB); PG8_STAGE(PG8_SB(1, 1), b3 + hstep, voffB); PG8_STAGE(PG8_SA(1, 0), a3, voffA);
;             PG8_WAIT_V(8); PG8_WAIT_L(0); PG8_BAR; PG8_MMA(1, 0, At, B0); PG8_MMA(1, 1, At, B1); PG8_BAR; PG8_SCHED;
;     ...
;         if constexpr (ALIGN_EPI) { if (wr == 0) PG8_BAR; }
;         if constexpr (!Epi::AFTER_DRAIN) { E(acc, cur, wr, wc, fr, fq); S.done(cur); }
;         if (!has_next) break;
	s_add_i32 s10, s78, s3
	v_lshl_add_u64 v[208:209], v[208:209], 0, s[20:21]
	s_mov_b32 m0, s10
	ds_read_b128 v[160:163], v227 offset:49152
	ds_read_b128 v[164:167], v227 offset:50176
	ds_read_b128 v[168:171], v227 offset:51200
	ds_read_b128 v[172:175], v227 offset:52224
	ds_read_b128 v[176:179], v227 offset:53248
	ds_read_b128 v[180:183], v227 offset:54272
	ds_read_b128 v[184:187], v227 offset:55296
	ds_read_b128 v[188:191], v227 offset:56320
	global_load_lds_dwordx4 v[208:209], off
	s_add_i32 m0, s10, 0x2000
	s_add_u32 s6, s6, 0x40080
	v_lshl_add_u64 v[208:209], v[210:211], 0, s[20:21]
	s_addc_u32 s7, s7, 0
	s_add_i32 s10, s79, s3
	global_load_lds_dwordx4 v[208:209], off
	v_lshl_add_u64 v[208:209], s[6:7], 0, v[194:195]
	s_mov_b32 m0, s10
	s_nop 0
	global_load_lds_dwordx4 v[208:209], off
	v_lshl_add_u64 v[208:209], s[6:7], 0, v[198:199]
	s_add_i32 m0, s10, 0x2000
	s_nop 0
	global_load_lds_dwordx4 v[208:209], off
	v_lshl_add_u64 v[208:209], v[212:213], 0, s[20:21]
	s_mov_b32 m0, s57
	s_nop 0
	global_load_lds_dwordx4 v[208:209], off
	v_lshl_add_u64 v[208:209], v[214:215], 0, s[20:21]
	s_mov_b32 m0, s58
	s_nop 0
	global_load_lds_dwordx4 v[208:209], off
	s_waitcnt vmcnt(8)
	s_waitcnt lgkmcnt(0)
	s_barrier
	s_waitcnt lgkmcnt(0)
	v_mfma_f32_16x16x32_bf16 v[60:63], v[88:91], v[160:163], v[60:63]
	v_mfma_f32_16x16x32_bf16 v[56:59], v[96:99], v[160:163], v[56:59]
	v_mfma_f32_16x16x32_bf16 v[44:47], v[88:91], v[168:171], v[44:47]
	v_mfma_f32_16x16x32_bf16 v[40:43], v[96:99], v[168:171], v[40:43]
	v_mfma_f32_16x16x32_bf16 v[28:31], v[88:91], v[176:179], v[28:31]
	v_mfma_f32_16x16x32_bf16 v[24:27], v[96:99], v[176:179], v[24:27]
	v_mfma_f32_16x16x32_bf16 v[12:15], v[88:91], v[184:187], v[12:15]
	v_mfma_f32_16x16x32_bf16 v[8:11], v[96:99], v[184:187], v[8:11]
	v_mfma_f32_16x16x32_bf16 v[60:63], v[92:95], v[164:167], v[60:63]
	v_mfma_f32_16x16x32_bf16 v[56:59], v[104:107], v[164:167], v[56:59]
	v_mfma_f32_16x16x32_bf16 v[44:47], v[92:95], v[172:175], v[44:47]
	v_mfma_f32_16x16x32_bf16 v[40:43], v[104:107], v[172:175], v[40:43]
	v_mfma_f32_16x16x32_bf16 v[28:31], v[92:95], v[180:183], v[28:31]
	v_mfma_f32_16x16x32_bf16 v[24:27], v[104:107], v[180:183], v[24:27]
	v_mfma_f32_16x16x32_bf16 v[12:15], v[92:95], v[188:191], v[12:15]
	v_mfma_f32_16x16x32_bf16 v[8:11], v[104:107], v[188:191], v[8:11]
	v_mfma_f32_16x16x32_bf16 v[52:55], v[144:147], v[160:163], v[52:55]
	v_mfma_f32_16x16x32_bf16 v[48:51], v[152:155], v[160:163], v[48:51]
	v_mfma_f32_16x16x32_bf16 v[36:39], v[144:147], v[168:171], v[36:39]
	v_mfma_f32_16x16x32_bf16 v[32:35], v[152:155], v[168:171], v[32:35]
	v_mfma_f32_16x16x32_bf16 v[20:23], v[144:147], v[176:179], v[20:23]
	v_mfma_f32_16x16x32_bf16 v[16:19], v[152:155], v[176:179], v[16:19]
	v_mfma_f32_16x16x32_bf16 v[4:7], v[144:147], v[184:187], v[4:7]
	v_mfma_f32_16x16x32_bf16 v[0:3], v[152:155], v[184:187], v[0:3]
	v_mfma_f32_16x16x32_bf16 v[52:55], v[148:151], v[164:167], v[52:55]
	v_mfma_f32_16x16x32_bf16 v[48:51], v[156:159], v[164:167], v[48:51]
	v_mfma_f32_16x16x32_bf16 v[36:39], v[148:151], v[172:175], v[36:39]
	v_mfma_f32_16x16x32_bf16 v[32:35], v[156:159], v[172:175], v[32:35]
	v_mfma_f32_16x16x32_bf16 v[20:23], v[148:151], v[180:183], v[20:23]
	v_mfma_f32_16x16x32_bf16 v[16:19], v[156:159], v[180:183], v[16:19]
	v_mfma_f32_16x16x32_bf16 v[4:7], v[148:151], v[188:191], v[4:7]
	v_mfma_f32_16x16x32_bf16 v[0:3], v[156:159], v[188:191], v[0:3]
	s_barrier
	s_add_i32 s77, s77, 2
	s_add_u32 s8, s8, 0x100
	s_addc_u32 s9, s9, 0
	s_add_u32 s67, s67, 0x100
	s_addc_u32 s76, s76, 0
	s_cmp_gt_u32 s77, 13
	s_cbranch_scc0 .LBB0_480
	s_and_b64 vcc, exec, s[26:27]
	s_cbranch_vccz .LBB0_483
	s_barrier

; #define PG8_STAGE(bufoff, gbase, voff) do { _Pragma("unroll") for (int _i = 0; _i < 2; ++_i) \
;         __builtin_amdgcn_global_load_lds((const unsigned*)((const char*)(gbase) + (voff)[_i]), (PG8_LAS unsigned*)(lds + (bufoff) + ldsw + _i * 8192), 16, 0, 0); } while (0)
; #define PG8_LDA(dst, b, h) do { _Pragma("unroll") for (int m = 0; m < 4; ++m) _Pragma("unroll") for (int k = 0; k < 2; ++k) dst[m][k] = *(const PG8_LAS bf16x8*)(lds + PG8_SA(b, h) + aoff + m * 2048 + k * 1024); } while (0)
; #define PG8_LDB(dst, b, h) do { _Pragma("unroll") for (int n = 0; n < 2; ++n) _Pragma("unroll") for (int k = 0; k < 2; ++k) dst[n][k] = *(const PG8_LAS bf16x8*)(lds + PG8_SB(b, h) + boff + n * 2048 + k * 1024); } while (0)
; #define PG8_WAIT_V(n) asm volatile("s_waitcnt vmcnt(" #n ")" ::: "memory")
; #define PG8_WAIT_L(n) asm volatile("s_waitcnt lgkmcnt(" #n ")" ::: "memory")
; #define PG8_BAR __builtin_amdgcn_s_barrier()
; #define PG8_SCHED __builtin_amdgcn_sched_barrier(0)
; template <class Epi, class Sched, bool ALIGN_EPI = false, bool SP2 = false>
; __device__ __forceinline__ void gemm_phase(PG8_LAS unsigned char* lds, const Gemm g, const Sched& S, const Epi& E) {
;     ...
;         const bool has_next = S.next(ui + 1, nxt);
;         const char* nA = has_next ? (const char*)g.A + (size_t)nxt.pm * tstep : cA; const char* nB = has_next ? (const char*)g.Bt + (size_t)nxt.pn * tstep : cB;
;         for (int t = 0; t < nt; t += 2) {
;             const bool last = (t == nt - 2);
;             const char* a1 = cA + (size_t)(t + 1) * kstep;
;             const char* a2 = last ? nA : cA + (size_t)(t + 2) * kstep; const char* b2 = last ? nB : cB + (size_t)(t + 2) * kstep;
;             const char* a3 = a2 + kstep; const char* b3 = b2 + kstep;
;             if (last && has_next) S.a_ready(nxt);
;             if constexpr (SP2) {
;             PG8_LDB(B0, 0, 0); PG8_LDB(B1, 0, 1); PG8_SCHED; PG8_LDA(At, 0, 0); PG8_STAGE(PG8_SA(1, 1), a1 + hstep, voffA);
;             PG8_WAIT_V(8); PG8_WAIT_L(0); PG8_BAR; PG8_MMA(0, 0, At, B0); PG8_MMA(0, 1, At, B1); PG8_BAR; PG8_SCHED;
;             PG8_LDA(At, 0, 1); PG8_STAGE(PG8_SB(0, 0), b2, voffB); PG8_STAGE(PG8_SB(0, 1), b2 + hstep, voffB); PG8_STAGE(PG8_SA(0, 0), a2, voffA);
;             PG8_WAIT_V(8); PG8_WAIT_L(0); PG8_BAR; PG8_MMA(1, 0, At, B0); PG8_MMA(1, 1, At, B1); PG8_BAR; PG8_SCHED;
.LBB0_575:
	ds_read_b128 v[154:157], v149
	ds_read_b128 v[158:161], v149 offset:1024
	ds_read_b128 v[162:165], v149 offset:2048
	ds_read_b128 v[166:169], v149 offset:3072
	ds_read_b128 v[170:173], v150
	ds_read_b128 v[174:177], v150 offset:1024
	ds_read_b128 v[178:181], v150 offset:2048
	ds_read_b128 v[182:185], v150 offset:3072
	s_add_u32 s6, s30, 0xfffc0080
	s_addc_u32 s7, s31, -1
	s_cmp_eq_u32 s61, 12
	s_cselect_b32 s11, s19, s7
	s_cselect_b32 s10, s57, s6
	s_cselect_b32 s7, s17, s60
	s_cselect_b32 s6, s58, s59
	v_lshl_add_u64 v[144:145], s[30:31], 0, v[136:137]
	s_add_i32 m0, s29, 0xc000
	ds_read_b128 v[186:189], v151
	ds_read_b128 v[190:193], v151 offset:1024
	ds_read_b128 v[194:197], v151 offset:2048
	ds_read_b128 v[198:201], v151 offset:3072
	ds_read_b128 v[202:205], v151 offset:4096
	ds_read_b128 v[206:209], v151 offset:5120
	ds_read_b128 v[210:213], v151 offset:6144
	ds_read_b128 v[214:217], v151 offset:7168
	global_load_lds_dwordx4 v[144:145], off
	v_lshl_add_u64 v[144:145], s[30:31], 0, v[138:139]
	s_add_i32 m0, s29, 0xe000
	s_nop 0
	global_load_lds_dwordx4 v[144:145], off
	s_waitcnt vmcnt(8)
	s_waitcnt lgkmcnt(0)
	s_barrier
	s_waitcnt lgkmcnt(0)
	v_mfma_f32_16x16x32_bf16 v[116:119], v[154:157], v[186:189], v[116:119]
	v_mfma_f32_16x16x32_bf16 v[112:115], v[162:165], v[186:189], v[112:115]
	v_mfma_f32_16x16x32_bf16 v[100:103], v[154:157], v[194:197], v[100:103]
	v_mfma_f32_16x16x32_bf16 v[96:99], v[162:165], v[194:197], v[96:99]
	v_mfma_f32_16x16x32_bf16 v[84:87], v[154:157], v[202:205], v[84:87]
	v_mfma_f32_16x16x32_bf16 v[80:83], v[162:165], v[202:205], v[80:83]
	v_mfma_f32_16x16x32_bf16 v[68:71], v[154:157], v[210:213], v[68:71]
	v_mfma_f32_16x16x32_bf16 v[64:67], v[162:165], v[210:213], v[64:67]
	v_mfma_f32_16x16x32_bf16 v[116:119], v[158:161], v[190:193], v[116:119]
	v_mfma_f32_16x16x32_bf16 v[112:115], v[166:169], v[190:193], v[112:115]
	v_mfma_f32_16x16x32_bf16 v[100:103], v[158:161], v[198:201], v[100:103]
	v_mfma_f32_16x16x32_bf16 v[96:99], v[166:169], v[198:201], v[96:99]
	v_mfma_f32_16x16x32_bf16 v[84:87], v[158:161], v[206:209], v[84:87]
	v_mfma_f32_16x16x32_bf16 v[80:83], v[166:169], v[206:209], v[80:83]
	v_mfma_f32_16x16x32_bf16 v[68:71], v[158:161], v[214:217], v[68:71]
	v_mfma_f32_16x16x32_bf16 v[64:67], v[166:169], v[214:217], v[64:67]
	v_mfma_f32_16x16x32_bf16 v[124:127], v[170:173], v[186:189], v[124:127]
	v_mfma_f32_16x16x32_bf16 v[120:123], v[178:181], v[186:189], v[120:123]
	v_mfma_f32_16x16x32_bf16 v[108:111], v[170:173], v[194:197], v[108:111]
	v_mfma_f32_16x16x32_bf16 v[104:107], v[178:181], v[194:197], v[104:107]
	v_mfma_f32_16x16x32_bf16 v[92:95], v[170:173], v[202:205], v[92:95]
	v_mfma_f32_16x16x32_bf16 v[88:91], v[178:181], v[202:205], v[88:91]
	v_mfma_f32_16x16x32_bf16 v[76:79], v[170:173], v[210:213], v[76:79]
	v_mfma_f32_16x16x32_bf16 v[72:75], v[178:181], v[210:213], v[72:75]
	v_mfma_f32_16x16x32_bf16 v[124:127], v[174:177], v[190:193], v[124:127]
	v_mfma_f32_16x16x32_bf16 v[120:123], v[182:185], v[190:193], v[120:123]
	v_mfma_f32_16x16x32_bf16 v[108:111], v[174:177], v[198:201], v[108:111]
	v_mfma_f32_16x16x32_bf16 v[104:107], v[182:185], v[198:201], v[104:107]
	v_mfma_f32_16x16x32_bf16 v[92:95], v[174:177], v[206:209], v[92:95]
	v_mfma_f32_16x16x32_bf16 v[88:91], v[182:185], v[206:209], v[88:91]
	v_mfma_f32_16x16x32_bf16 v[76:79], v[174:177], v[214:217], v[76:79]
	v_mfma_f32_16x16x32_bf16 v[72:75], v[182:185], v[214:217], v[72:75]
	s_barrier
	s_add_i32 s62, s53, s34
	v_lshl_add_u64 v[144:145], s[6:7], 0, v[132:133]
	s_mov_b32 m0, s62
	ds_read_b128 v[186:189], v151 offset:16384
	ds_read_b128 v[190:193], v151 offset:17408
	ds_read_b128 v[194:197], v151 offset:18432
	ds_read_b128 v[198:201], v151 offset:19456
	ds_read_b128 v[202:205], v151 offset:20480
	ds_read_b128 v[206:209], v151 offset:21504
	ds_read_b128 v[210:213], v151 offset:22528
	ds_read_b128 v[214:217], v151 offset:23552
	global_load_lds_dwordx4 v[144:145], off
	s_add_i32 m0, s62, 0x2000
	s_add_u32 s62, s6, 0x40000
	v_lshl_add_u64 v[218:219], s[6:7], 0, v[128:129]
	s_addc_u32 s63, s7, 0
	s_add_i32 s64, s54, s34
	global_load_lds_dwordx4 v[218:219], off
	v_lshl_add_u64 v[222:223], s[62:63], 0, v[132:133]
	s_mov_b32 m0, s64
	v_lshl_add_u64 v[224:225], s[10:11], 0, v[130:131]
	global_load_lds_dwordx4 v[222:223], off
	v_lshl_add_u64 v[222:223], s[62:63], 0, v[128:129]
	s_add_i32 m0, s64, 0x2000
	s_nop 0
	global_load_lds_dwordx4 v[222:223], off
	v_lshl_add_u64 v[222:223], s[10:11], 0, v[134:135]
	s_mov_b32 m0, s29
	s_nop 0
	global_load_lds_dwordx4 v[222:223], off
	s_mov_b32 m0, s37
	s_nop 0
	global_load_lds_dwordx4 v[224:225], off
	s_waitcnt vmcnt(8)
	s_waitcnt lgkmcnt(0)
	s_barrier
; #define PG8_STAGE(bufoff, gbase, voff) do { _Pragma("unroll") for (int _i = 0; _i < 2; ++_i) \
;         __builtin_amdgcn_global_load_lds((const unsigned*)((const char*)(gbase) + (voff)[_i]), (PG8_LAS unsigned*)(lds + (bufoff) + ldsw + _i * 8192), 16, 0, 0); } while (0)
; #define PG8_LDA(dst, b, h) do { _Pragma("unroll") for (int m = 0; m < 4; ++m) _Pragma("unroll") for (int k = 0; k < 2; ++k) dst[m][k] = *(const PG8_LAS bf16x8*)(lds + PG8_SA(b, h) + aoff + m * 2048 + k * 1024); } while (0)
; #define PG8_LDB(dst, b, h) do { _Pragma("unroll") for (int n = 0; n < 2; ++n) _Pragma("unroll") for (int k = 0; k < 2; ++k) dst[n][k] = *(const PG8_LAS bf16x8*)(lds + PG8_SB(b, h) + boff + n * 2048 + k * 1024); } while (0)
; #define PG8_MMA(ai, bj, At, Bt) do { __builtin_amdgcn_s_setprio(1); _Pragma("unroll") for (int m = 0; m < 4; ++m) _Pragma("unroll") for (int n = 0; n < 2; ++n) _Pragma("unroll") for (int k = 0; k < 2; ++k) \
;         acc[ai][bj][m][n] = __builtin_amdgcn_mfma_f32_16x16x32_bf16(Bt[n][k], At[m][k], acc[ai][bj][m][n], 0, 0, 0); __builtin_amdgcn_s_setprio(0); } while (0)
; #define PG8_WAIT_V(n) asm volatile("s_waitcnt vmcnt(" #n ")" ::: "memory")
; #define PG8_WAIT_L(n) asm volatile("s_waitcnt lgkmcnt(" #n ")" ::: "memory")
; #define PG8_BAR __builtin_amdgcn_s_barrier()
; #define PG8_SCHED __builtin_amdgcn_sched_barrier(0)
; template <class Epi, class Sched, bool ALIGN_EPI = false, bool SP2 = false>
; __device__ __forceinline__ void gemm_phase(PG8_LAS unsigned char* lds, const Gemm g, const Sched& S, const Epi& E) {
;     ...
;             PG8_WAIT_V(8); PG8_WAIT_L(0); PG8_BAR; PG8_MMA(1, 0, At, B0); PG8_MMA(1, 1, At, B1); PG8_BAR; PG8_SCHED;
;             PG8_LDB(B0, 1, 0); PG8_LDB(B1, 1, 1); PG8_SCHED; PG8_LDA(At, 1, 0); PG8_STAGE(PG8_SA(0, 1), a2 + hstep, voffA);
;             PG8_WAIT_V(8); PG8_WAIT_L(0); PG8_BAR; PG8_MMA(0, 0, At, B0); PG8_MMA(0, 1, At, B1); PG8_BAR; PG8_SCHED;
	s_waitcnt lgkmcnt(0)
	v_mfma_f32_16x16x32_bf16 v[52:55], v[154:157], v[186:189], v[52:55]
	v_mfma_f32_16x16x32_bf16 v[48:51], v[162:165], v[186:189], v[48:51]
	v_mfma_f32_16x16x32_bf16 v[36:39], v[154:157], v[194:197], v[36:39]
	v_mfma_f32_16x16x32_bf16 v[32:35], v[162:165], v[194:197], v[32:35]
	v_mfma_f32_16x16x32_bf16 v[20:23], v[154:157], v[202:205], v[20:23]
	v_mfma_f32_16x16x32_bf16 v[16:19], v[162:165], v[202:205], v[16:19]
	v_mfma_f32_16x16x32_bf16 v[4:7], v[154:157], v[210:213], v[4:7]
	v_mfma_f32_16x16x32_bf16 v[0:3], v[162:165], v[210:213], v[0:3]
	v_mfma_f32_16x16x32_bf16 v[52:55], v[158:161], v[190:193], v[52:55]
	v_mfma_f32_16x16x32_bf16 v[48:51], v[166:169], v[190:193], v[48:51]
	v_mfma_f32_16x16x32_bf16 v[36:39], v[158:161], v[198:201], v[36:39]
	v_mfma_f32_16x16x32_bf16 v[32:35], v[166:169], v[198:201], v[32:35]
	v_mfma_f32_16x16x32_bf16 v[20:23], v[158:161], v[206:209], v[20:23]
	v_mfma_f32_16x16x32_bf16 v[16:19], v[166:169], v[206:209], v[16:19]
	v_mfma_f32_16x16x32_bf16 v[4:7], v[158:161], v[214:217], v[4:7]
	v_mfma_f32_16x16x32_bf16 v[0:3], v[166:169], v[214:217], v[0:3]
	v_mfma_f32_16x16x32_bf16 v[60:63], v[170:173], v[186:189], v[60:63]
	v_mfma_f32_16x16x32_bf16 v[56:59], v[178:181], v[186:189], v[56:59]
	v_mfma_f32_16x16x32_bf16 v[44:47], v[170:173], v[194:197], v[44:47]
	v_mfma_f32_16x16x32_bf16 v[40:43], v[178:181], v[194:197], v[40:43]
	v_mfma_f32_16x16x32_bf16 v[28:31], v[170:173], v[202:205], v[28:31]
	v_mfma_f32_16x16x32_bf16 v[24:27], v[178:181], v[202:205], v[24:27]
	v_mfma_f32_16x16x32_bf16 v[12:15], v[170:173], v[210:213], v[12:15]
	v_mfma_f32_16x16x32_bf16 v[8:11], v[178:181], v[210:213], v[8:11]
	v_mfma_f32_16x16x32_bf16 v[60:63], v[174:177], v[190:193], v[60:63]
	v_mfma_f32_16x16x32_bf16 v[56:59], v[182:185], v[190:193], v[56:59]
	v_mfma_f32_16x16x32_bf16 v[44:47], v[174:177], v[198:201], v[44:47]
	v_mfma_f32_16x16x32_bf16 v[40:43], v[182:185], v[198:201], v[40:43]
	v_mfma_f32_16x16x32_bf16 v[28:31], v[174:177], v[206:209], v[28:31]
	v_mfma_f32_16x16x32_bf16 v[24:27], v[182:185], v[206:209], v[24:27]
	v_mfma_f32_16x16x32_bf16 v[12:15], v[174:177], v[214:217], v[12:15]
	v_mfma_f32_16x16x32_bf16 v[8:11], v[182:185], v[214:217], v[8:11]
	s_barrier
	s_add_i32 s62, 0, 0x18000
	v_add_u32_e32 v153, s62, v147
	s_add_i32 s63, 0, 0x1c000
	ds_read_b128 v[154:157], v153
	ds_read_b128 v[158:161], v153 offset:1024
	ds_read_b128 v[162:165], v153 offset:2048
	ds_read_b128 v[166:169], v153 offset:3072
	v_add_u32_e32 v153, s63, v147
	ds_read_b128 v[170:173], v153
	ds_read_b128 v[174:177], v153 offset:1024
	ds_read_b128 v[178:181], v153 offset:2048
	ds_read_b128 v[182:185], v153 offset:3072
	s_add_u32 s10, s10, 0x40000
	s_addc_u32 s11, s11, 0
	s_mov_b32 m0, s46
	v_lshl_add_u64 v[226:227], s[10:11], 0, v[134:135]
	ds_read_b128 v[186:189], v151 offset:32768
	ds_read_b128 v[190:193], v151 offset:33792
	ds_read_b128 v[194:197], v151 offset:34816
	ds_read_b128 v[198:201], v151 offset:35840
	ds_read_b128 v[202:205], v151 offset:36864
	ds_read_b128 v[206:209], v151 offset:37888
	ds_read_b128 v[210:213], v151 offset:38912
	ds_read_b128 v[214:217], v151 offset:39936
	global_load_lds_dwordx4 v[226:227], off
	v_lshl_add_u64 v[226:227], s[10:11], 0, v[130:131]
	s_mov_b32 m0, s47
	s_nop 0
	global_load_lds_dwordx4 v[226:227], off
	s_waitcnt vmcnt(8)
	s_waitcnt lgkmcnt(0)
	s_barrier
	s_waitcnt lgkmcnt(0)
	v_mfma_f32_16x16x32_bf16 v[116:119], v[154:157], v[186:189], v[116:119]
	v_mfma_f32_16x16x32_bf16 v[112:115], v[162:165], v[186:189], v[112:115]
	v_mfma_f32_16x16x32_bf16 v[100:103], v[154:157], v[194:197], v[100:103]
	v_mfma_f32_16x16x32_bf16 v[96:99], v[162:165], v[194:197], v[96:99]
	v_mfma_f32_16x16x32_bf16 v[84:87], v[154:157], v[202:205], v[84:87]
	v_mfma_f32_16x16x32_bf16 v[80:83], v[162:165], v[202:205], v[80:83]
	v_mfma_f32_16x16x32_bf16 v[68:71], v[154:157], v[210:213], v[68:71]
	v_mfma_f32_16x16x32_bf16 v[64:67], v[162:165], v[210:213], v[64:67]
	v_mfma_f32_16x16x32_bf16 v[116:119], v[158:161], v[190:193], v[116:119]
	v_mfma_f32_16x16x32_bf16 v[112:115], v[166:169], v[190:193], v[112:115]
	v_mfma_f32_16x16x32_bf16 v[100:103], v[158:161], v[198:201], v[100:103]
	v_mfma_f32_16x16x32_bf16 v[96:99], v[166:169], v[198:201], v[96:99]
	v_mfma_f32_16x16x32_bf16 v[84:87], v[158:161], v[206:209], v[84:87]
	v_mfma_f32_16x16x32_bf16 v[80:83], v[166:169], v[206:209], v[80:83]
	v_mfma_f32_16x16x32_bf16 v[68:71], v[158:161], v[214:217], v[68:71]
	v_mfma_f32_16x16x32_bf16 v[64:67], v[166:169], v[214:217], v[64:67]
	v_mfma_f32_16x16x32_bf16 v[124:127], v[170:173], v[186:189], v[124:127]
	v_mfma_f32_16x16x32_bf16 v[120:123], v[178:181], v[186:189], v[120:123]
	v_mfma_f32_16x16x32_bf16 v[108:111], v[170:173], v[194:197], v[108:111]
	v_mfma_f32_16x16x32_bf16 v[104:107], v[178:181], v[194:197], v[104:107]
	v_mfma_f32_16x16x32_bf16 v[92:95], v[170:173], v[202:205], v[92:95]
	v_mfma_f32_16x16x32_bf16 v[88:91], v[178:181], v[202:205], v[88:91]
	v_mfma_f32_16x16x32_bf16 v[76:79], v[170:173], v[210:213], v[76:79]
	v_mfma_f32_16x16x32_bf16 v[72:75], v[178:181], v[210:213], v[72:75]
	v_mfma_f32_16x16x32_bf16 v[124:127], v[174:177], v[190:193], v[124:127]
	v_mfma_f32_16x16x32_bf16 v[120:123], v[182:185], v[190:193], v[120:123]
	v_mfma_f32_16x16x32_bf16 v[108:111], v[174:177], v[198:201], v[108:111]
	v_mfma_f32_16x16x32_bf16 v[104:107], v[182:185], v[198:201], v[104:107]
	v_mfma_f32_16x16x32_bf16 v[92:95], v[174:177], v[206:209], v[92:95]
	v_mfma_f32_16x16x32_bf16 v[88:91], v[182:185], v[206:209], v[88:91]
	v_mfma_f32_16x16x32_bf16 v[76:79], v[174:177], v[214:217], v[76:79]
	v_mfma_f32_16x16x32_bf16 v[72:75], v[182:185], v[214:217], v[72:75]
	s_barrier
; #define PG8_STAGE(bufoff, gbase, voff) do { _Pragma("unroll") for (int _i = 0; _i < 2; ++_i) \
;         __builtin_amdgcn_global_load_lds((const unsigned*)((const char*)(gbase) + (voff)[_i]), (PG8_LAS unsigned*)(lds + (bufoff) + ldsw + _i * 8192), 16, 0, 0); } while (0)
; #define PG8_LDA(dst, b, h) do { _Pragma("unroll") for (int m = 0; m < 4; ++m) _Pragma("unroll") for (int k = 0; k < 2; ++k) dst[m][k] = *(const PG8_LAS bf16x8*)(lds + PG8_SA(b, h) + aoff + m * 2048 + k * 1024); } while (0)
; #define PG8_MMA(ai, bj, At, Bt) do { __builtin_amdgcn_s_setprio(1); _Pragma("unroll") for (int m = 0; m < 4; ++m) _Pragma("unroll") for (int n = 0; n < 2; ++n) _Pragma("unroll") for (int k = 0; k < 2; ++k) \
;         acc[ai][bj][m][n] = __builtin_amdgcn_mfma_f32_16x16x32_bf16(Bt[n][k], At[m][k], acc[ai][bj][m][n], 0, 0, 0); __builtin_amdgcn_s_setprio(0); } while (0)
; #define PG8_WAIT_V(n) asm volatile("s_waitcnt vmcnt(" #n ")" ::: "memory")
; #define PG8_WAIT_L(n) asm volatile("s_waitcnt lgkmcnt(" #n ")" ::: "memory")
; #define PG8_BAR __builtin_amdgcn_s_barrier()
; #define PG8_SCHED __builtin_amdgcn_sched_barrier(0)
; template <class Epi, class Sched, bool ALIGN_EPI = false, bool SP2 = false>
; __device__ __forceinline__ void gemm_phase(PG8_LAS unsigned char* lds, const Gemm g, const Sched& S, const Epi& E) {
;     ...
;             PG8_LDA(At, 1, 1); PG8_STAGE(PG8_SB(1, 0), b3, voffB); PG8_STAGE(PG8_SB(1, 1), b3 + hstep, voffB); PG8_STAGE(PG8_SA(1, 0), a3, voffA);
;             PG8_WAIT_V(8); PG8_WAIT_L(0); PG8_BAR; PG8_MMA(1, 0, At, B0); PG8_MMA(1, 1, At, B1); PG8_BAR; PG8_SCHED;
;     ...
;         if constexpr (ALIGN_EPI) { if (wr == 0) PG8_BAR; }
;         if constexpr (!Epi::AFTER_DRAIN) { E(acc, cur, wr, wc, fr, fq); S.done(cur); }
;         if (!has_next) break;
	s_add_i32 s10, s62, s34
	v_lshl_add_u64 v[144:145], v[144:145], 0, s[12:13]
	s_mov_b32 m0, s10
	ds_read_b128 v[186:189], v151 offset:49152
	ds_read_b128 v[190:193], v151 offset:50176
	ds_read_b128 v[194:197], v151 offset:51200
	ds_read_b128 v[198:201], v151 offset:52224
	ds_read_b128 v[202:205], v151 offset:53248
	ds_read_b128 v[206:209], v151 offset:54272
	ds_read_b128 v[210:213], v151 offset:55296
	ds_read_b128 v[214:217], v151 offset:56320
	global_load_lds_dwordx4 v[144:145], off
	s_add_i32 m0, s10, 0x2000
	s_add_u32 s6, s6, 0x40080
	v_lshl_add_u64 v[144:145], v[218:219], 0, s[12:13]
	s_addc_u32 s7, s7, 0
	s_add_i32 s10, s63, s34
	global_load_lds_dwordx4 v[144:145], off
	v_lshl_add_u64 v[144:145], s[6:7], 0, v[132:133]
	s_mov_b32 m0, s10
	s_nop 0
	global_load_lds_dwordx4 v[144:145], off
	v_lshl_add_u64 v[144:145], s[6:7], 0, v[128:129]
	s_add_i32 m0, s10, 0x2000
	s_nop 0
	global_load_lds_dwordx4 v[144:145], off
	v_lshl_add_u64 v[144:145], v[222:223], 0, s[12:13]
	s_mov_b32 m0, s49
	s_nop 0
	global_load_lds_dwordx4 v[144:145], off
	v_lshl_add_u64 v[144:145], v[224:225], 0, s[12:13]
	s_mov_b32 m0, s50
	s_nop 0
	global_load_lds_dwordx4 v[144:145], off
	s_waitcnt vmcnt(8)
	s_waitcnt lgkmcnt(0)
	s_barrier
	s_waitcnt lgkmcnt(0)
	v_mfma_f32_16x16x32_bf16 v[52:55], v[154:157], v[186:189], v[52:55]
	v_mfma_f32_16x16x32_bf16 v[48:51], v[162:165], v[186:189], v[48:51]
	v_mfma_f32_16x16x32_bf16 v[36:39], v[154:157], v[194:197], v[36:39]
	v_mfma_f32_16x16x32_bf16 v[32:35], v[162:165], v[194:197], v[32:35]
	v_mfma_f32_16x16x32_bf16 v[20:23], v[154:157], v[202:205], v[20:23]
	v_mfma_f32_16x16x32_bf16 v[16:19], v[162:165], v[202:205], v[16:19]
	v_mfma_f32_16x16x32_bf16 v[4:7], v[154:157], v[210:213], v[4:7]
	v_mfma_f32_16x16x32_bf16 v[0:3], v[162:165], v[210:213], v[0:3]
	v_mfma_f32_16x16x32_bf16 v[52:55], v[158:161], v[190:193], v[52:55]
	v_mfma_f32_16x16x32_bf16 v[48:51], v[166:169], v[190:193], v[48:51]
	v_mfma_f32_16x16x32_bf16 v[36:39], v[158:161], v[198:201], v[36:39]
	v_mfma_f32_16x16x32_bf16 v[32:35], v[166:169], v[198:201], v[32:35]
	v_mfma_f32_16x16x32_bf16 v[20:23], v[158:161], v[206:209], v[20:23]
	v_mfma_f32_16x16x32_bf16 v[16:19], v[166:169], v[206:209], v[16:19]
	v_mfma_f32_16x16x32_bf16 v[4:7], v[158:161], v[214:217], v[4:7]
	v_mfma_f32_16x16x32_bf16 v[0:3], v[166:169], v[214:217], v[0:3]
	v_mfma_f32_16x16x32_bf16 v[60:63], v[170:173], v[186:189], v[60:63]
	v_mfma_f32_16x16x32_bf16 v[56:59], v[178:181], v[186:189], v[56:59]
	v_mfma_f32_16x16x32_bf16 v[44:47], v[170:173], v[194:197], v[44:47]
	v_mfma_f32_16x16x32_bf16 v[40:43], v[178:181], v[194:197], v[40:43]
	v_mfma_f32_16x16x32_bf16 v[28:31], v[170:173], v[202:205], v[28:31]
	v_mfma_f32_16x16x32_bf16 v[24:27], v[178:181], v[202:205], v[24:27]
	v_mfma_f32_16x16x32_bf16 v[12:15], v[170:173], v[210:213], v[12:15]
	v_mfma_f32_16x16x32_bf16 v[8:11], v[178:181], v[210:213], v[8:11]
	v_mfma_f32_16x16x32_bf16 v[60:63], v[174:177], v[190:193], v[60:63]
	v_mfma_f32_16x16x32_bf16 v[56:59], v[182:185], v[190:193], v[56:59]
	v_mfma_f32_16x16x32_bf16 v[44:47], v[174:177], v[198:201], v[44:47]
	v_mfma_f32_16x16x32_bf16 v[40:43], v[182:185], v[198:201], v[40:43]
	v_mfma_f32_16x16x32_bf16 v[28:31], v[174:177], v[206:209], v[28:31]
	v_mfma_f32_16x16x32_bf16 v[24:27], v[182:185], v[206:209], v[24:27]
	v_mfma_f32_16x16x32_bf16 v[12:15], v[174:177], v[214:217], v[12:15]
	v_mfma_f32_16x16x32_bf16 v[8:11], v[182:185], v[214:217], v[8:11]
	s_barrier
	s_add_i32 s61, s61, 2
	s_add_u32 s30, s30, 0x100
	s_addc_u32 s31, s31, 0
	s_add_u32 s59, s59, 0x100
	s_addc_u32 s60, s60, 0
	s_cmp_gt_u32 s61, 13
	s_cbranch_scc0 .LBB0_575
	s_and_b64 vcc, exec, s[14:15]
	s_cbranch_vccz .LBB0_578
	s_barrier

; #define PG8_STAGE(bufoff, gbase, voff) do { _Pragma("unroll") for (int _i = 0; _i < 2; ++_i) \
;         __builtin_amdgcn_global_load_lds((const unsigned*)((const char*)(gbase) + (voff)[_i]), (PG8_LAS unsigned*)(lds + (bufoff) + ldsw + _i * 8192), 16, 0, 0); } while (0)
; #define PG8_LDA(dst, b, h) do { _Pragma("unroll") for (int m = 0; m < 4; ++m) _Pragma("unroll") for (int k = 0; k < 2; ++k) dst[m][k] = *(const PG8_LAS bf16x8*)(lds + PG8_SA(b, h) + aoff + m * 2048 + k * 1024); } while (0)
; #define PG8_LDB(dst, b, h) do { _Pragma("unroll") for (int n = 0; n < 2; ++n) _Pragma("unroll") for (int k = 0; k < 2; ++k) dst[n][k] = *(const PG8_LAS bf16x8*)(lds + PG8_SB(b, h) + boff + n * 2048 + k * 1024); } while (0)
; #define PG8_WAIT_V(n) asm volatile("s_waitcnt vmcnt(" #n ")" ::: "memory")
; #define PG8_WAIT_L(n) asm volatile("s_waitcnt lgkmcnt(" #n ")" ::: "memory")
; #define PG8_BAR __builtin_amdgcn_s_barrier()
; #define PG8_SCHED __builtin_amdgcn_sched_barrier(0)
; template <class Epi, class Sched, bool ALIGN_EPI = false, bool SP2 = false>
; __device__ __forceinline__ void gemm_phase(PG8_LAS unsigned char* lds, const Gemm g, const Sched& S, const Epi& E) {
;     ...
;         const bool has_next = S.next(ui + 1, nxt);
;         const char* nA = has_next ? (const char*)g.A + (size_t)nxt.pm * tstep : cA; const char* nB = has_next ? (const char*)g.Bt + (size_t)nxt.pn * tstep : cB;
;         for (int t = 0; t < nt; t += 2) {
;             const bool last = (t == nt - 2);
;             const char* a1 = cA + (size_t)(t + 1) * kstep;
;             const char* a2 = last ? nA : cA + (size_t)(t + 2) * kstep; const char* b2 = last ? nB : cB + (size_t)(t + 2) * kstep;
;             const char* a3 = a2 + kstep; const char* b3 = b2 + kstep;
;             if (last && has_next) S.a_ready(nxt);
;             if constexpr (SP2) {
;             PG8_LDB(B0, 0, 0); PG8_LDB(B1, 0, 1); PG8_SCHED; PG8_LDA(At, 0, 0); PG8_STAGE(PG8_SA(1, 1), a1 + hstep, voffA);
;             PG8_WAIT_V(8); PG8_WAIT_L(0); PG8_BAR; PG8_MMA(0, 0, At, B0); PG8_MMA(0, 1, At, B1); PG8_BAR; PG8_SCHED;
;             PG8_LDA(At, 0, 1); PG8_STAGE(PG8_SB(0, 0), b2, voffB); PG8_STAGE(PG8_SB(0, 1), b2 + hstep, voffB); PG8_STAGE(PG8_SA(0, 0), a2, voffA);
;             PG8_WAIT_V(8); PG8_WAIT_L(0); PG8_BAR; PG8_MMA(1, 0, At, B0); PG8_MMA(1, 1, At, B1); PG8_BAR; PG8_SCHED;
.LBB0_660:
	ds_read_b128 v[128:131], v189
	ds_read_b128 v[132:135], v189 offset:1024
	ds_read_b128 v[136:139], v189 offset:2048
	ds_read_b128 v[140:143], v189 offset:3072
	ds_read_b128 v[144:147], v190
	ds_read_b128 v[148:151], v190 offset:1024
	ds_read_b128 v[168:171], v190 offset:2048
	ds_read_b128 v[172:175], v190 offset:3072
	s_add_u32 s6, s28, 0xfff50080
	s_addc_u32 s7, s29, -1
	s_cmp_eq_u32 s59, 40
	s_cselect_b32 s11, s9, s7
	s_cselect_b32 s10, s8, s6
	s_cselect_b32 s7, s27, s58
	s_cselect_b32 s6, s26, s57
	v_lshl_add_u64 v[184:185], s[28:29], 0, v[160:161]
	s_add_i32 m0, s33, 0xc000
	ds_read_b128 v[176:179], v191
	ds_read_b128 v[180:183], v191 offset:1024
	ds_read_b128 v[194:197], v191 offset:2048
	ds_read_b128 v[198:201], v191 offset:3072
	ds_read_b128 v[202:205], v191 offset:4096
	ds_read_b128 v[206:209], v191 offset:5120
	ds_read_b128 v[210:213], v191 offset:6144
	ds_read_b128 v[214:217], v191 offset:7168
	global_load_lds_dwordx4 v[184:185], off
	v_lshl_add_u64 v[184:185], s[28:29], 0, v[162:163]
	s_add_i32 m0, s33, 0xe000
	s_nop 0
	global_load_lds_dwordx4 v[184:185], off
	s_waitcnt vmcnt(8)
	s_waitcnt lgkmcnt(0)
	s_barrier
	s_waitcnt lgkmcnt(0)
	v_mfma_f32_16x16x32_bf16 v[124:127], v[128:131], v[176:179], v[124:127]
	v_mfma_f32_16x16x32_bf16 v[120:123], v[136:139], v[176:179], v[120:123]
	v_mfma_f32_16x16x32_bf16 v[108:111], v[128:131], v[194:197], v[108:111]
	v_mfma_f32_16x16x32_bf16 v[104:107], v[136:139], v[194:197], v[104:107]
	v_mfma_f32_16x16x32_bf16 v[92:95], v[128:131], v[202:205], v[92:95]
	v_mfma_f32_16x16x32_bf16 v[88:91], v[136:139], v[202:205], v[88:91]
	v_mfma_f32_16x16x32_bf16 v[76:79], v[128:131], v[210:213], v[76:79]
	v_mfma_f32_16x16x32_bf16 v[72:75], v[136:139], v[210:213], v[72:75]
	v_mfma_f32_16x16x32_bf16 v[124:127], v[132:135], v[180:183], v[124:127]
	v_mfma_f32_16x16x32_bf16 v[120:123], v[140:143], v[180:183], v[120:123]
	v_mfma_f32_16x16x32_bf16 v[108:111], v[132:135], v[198:201], v[108:111]
	v_mfma_f32_16x16x32_bf16 v[104:107], v[140:143], v[198:201], v[104:107]
	v_mfma_f32_16x16x32_bf16 v[92:95], v[132:135], v[206:209], v[92:95]
	v_mfma_f32_16x16x32_bf16 v[88:91], v[140:143], v[206:209], v[88:91]
	v_mfma_f32_16x16x32_bf16 v[76:79], v[132:135], v[214:217], v[76:79]
	v_mfma_f32_16x16x32_bf16 v[72:75], v[140:143], v[214:217], v[72:75]
	v_mfma_f32_16x16x32_bf16 v[116:119], v[144:147], v[176:179], v[116:119]
	v_mfma_f32_16x16x32_bf16 v[112:115], v[168:171], v[176:179], v[112:115]
	v_mfma_f32_16x16x32_bf16 v[100:103], v[144:147], v[194:197], v[100:103]
	v_mfma_f32_16x16x32_bf16 v[96:99], v[168:171], v[194:197], v[96:99]
	v_mfma_f32_16x16x32_bf16 v[84:87], v[144:147], v[202:205], v[84:87]
	v_mfma_f32_16x16x32_bf16 v[80:83], v[168:171], v[202:205], v[80:83]
	v_mfma_f32_16x16x32_bf16 v[68:71], v[144:147], v[210:213], v[68:71]
	v_mfma_f32_16x16x32_bf16 v[64:67], v[168:171], v[210:213], v[64:67]
	v_mfma_f32_16x16x32_bf16 v[116:119], v[148:151], v[180:183], v[116:119]
	v_mfma_f32_16x16x32_bf16 v[112:115], v[172:175], v[180:183], v[112:115]
	v_mfma_f32_16x16x32_bf16 v[100:103], v[148:151], v[198:201], v[100:103]
	v_mfma_f32_16x16x32_bf16 v[96:99], v[172:175], v[198:201], v[96:99]
	v_mfma_f32_16x16x32_bf16 v[84:87], v[148:151], v[206:209], v[84:87]
	v_mfma_f32_16x16x32_bf16 v[80:83], v[172:175], v[206:209], v[80:83]
	v_mfma_f32_16x16x32_bf16 v[68:71], v[148:151], v[214:217], v[68:71]
	v_mfma_f32_16x16x32_bf16 v[64:67], v[172:175], v[214:217], v[64:67]
	s_barrier
	s_add_i32 s60, s51, s31
	v_lshl_add_u64 v[184:185], s[6:7], 0, v[154:155]
	s_mov_b32 m0, s60
	ds_read_b128 v[176:179], v191 offset:16384
	ds_read_b128 v[180:183], v191 offset:17408
	ds_read_b128 v[194:197], v191 offset:18432
	ds_read_b128 v[198:201], v191 offset:19456
	ds_read_b128 v[202:205], v191 offset:20480
	ds_read_b128 v[206:209], v191 offset:21504
	ds_read_b128 v[210:213], v191 offset:22528
	ds_read_b128 v[214:217], v191 offset:23552
	global_load_lds_dwordx4 v[184:185], off
	s_add_i32 m0, s60, 0x2000
	s_add_u32 s60, s6, 0xb0000
	v_lshl_add_u64 v[218:219], s[6:7], 0, v[158:159]
	s_addc_u32 s61, s7, 0
	s_add_i32 s62, s52, s31
	global_load_lds_dwordx4 v[218:219], off
	v_lshl_add_u64 v[222:223], s[60:61], 0, v[154:155]
	s_mov_b32 m0, s62
	v_lshl_add_u64 v[224:225], s[10:11], 0, v[156:157]
	global_load_lds_dwordx4 v[222:223], off
	v_lshl_add_u64 v[222:223], s[60:61], 0, v[158:159]
	s_add_i32 m0, s62, 0x2000
	s_nop 0
	global_load_lds_dwordx4 v[222:223], off
	v_lshl_add_u64 v[222:223], s[10:11], 0, v[152:153]
	s_mov_b32 m0, s33
	s_nop 0
	global_load_lds_dwordx4 v[222:223], off
	s_mov_b32 m0, s34
	s_nop 0
	global_load_lds_dwordx4 v[224:225], off
	s_waitcnt vmcnt(8)
	s_waitcnt lgkmcnt(0)
	s_barrier
; #define PG8_STAGE(bufoff, gbase, voff) do { _Pragma("unroll") for (int _i = 0; _i < 2; ++_i) \
;         __builtin_amdgcn_global_load_lds((const unsigned*)((const char*)(gbase) + (voff)[_i]), (PG8_LAS unsigned*)(lds + (bufoff) + ldsw + _i * 8192), 16, 0, 0); } while (0)
; #define PG8_LDA(dst, b, h) do { _Pragma("unroll") for (int m = 0; m < 4; ++m) _Pragma("unroll") for (int k = 0; k < 2; ++k) dst[m][k] = *(const PG8_LAS bf16x8*)(lds + PG8_SA(b, h) + aoff + m * 2048 + k * 1024); } while (0)
; #define PG8_LDB(dst, b, h) do { _Pragma("unroll") for (int n = 0; n < 2; ++n) _Pragma("unroll") for (int k = 0; k < 2; ++k) dst[n][k] = *(const PG8_LAS bf16x8*)(lds + PG8_SB(b, h) + boff + n * 2048 + k * 1024); } while (0)
; #define PG8_MMA(ai, bj, At, Bt) do { __builtin_amdgcn_s_setprio(1); _Pragma("unroll") for (int m = 0; m < 4; ++m) _Pragma("unroll") for (int n = 0; n < 2; ++n) _Pragma("unroll") for (int k = 0; k < 2; ++k) \
;         acc[ai][bj][m][n] = __builtin_amdgcn_mfma_f32_16x16x32_bf16(Bt[n][k], At[m][k], acc[ai][bj][m][n], 0, 0, 0); __builtin_amdgcn_s_setprio(0); } while (0)
; #define PG8_WAIT_V(n) asm volatile("s_waitcnt vmcnt(" #n ")" ::: "memory")
; #define PG8_WAIT_L(n) asm volatile("s_waitcnt lgkmcnt(" #n ")" ::: "memory")
; #define PG8_BAR __builtin_amdgcn_s_barrier()
; #define PG8_SCHED __builtin_amdgcn_sched_barrier(0)
; template <class Epi, class Sched, bool ALIGN_EPI = false, bool SP2 = false>
; __device__ __forceinline__ void gemm_phase(PG8_LAS unsigned char* lds, const Gemm g, const Sched& S, const Epi& E) {
;     ...
;             PG8_WAIT_V(8); PG8_WAIT_L(0); PG8_BAR; PG8_MMA(1, 0, At, B0); PG8_MMA(1, 1, At, B1); PG8_BAR; PG8_SCHED;
;             PG8_LDB(B0, 1, 0); PG8_LDB(B1, 1, 1); PG8_SCHED; PG8_LDA(At, 1, 0); PG8_STAGE(PG8_SA(0, 1), a2 + hstep, voffA);
;             PG8_WAIT_V(8); PG8_WAIT_L(0); PG8_BAR; PG8_MMA(0, 0, At, B0); PG8_MMA(0, 1, At, B1); PG8_BAR; PG8_SCHED;
	s_waitcnt lgkmcnt(0)
	v_mfma_f32_16x16x32_bf16 v[60:63], v[128:131], v[176:179], v[60:63]
	v_mfma_f32_16x16x32_bf16 v[56:59], v[136:139], v[176:179], v[56:59]
	v_mfma_f32_16x16x32_bf16 v[44:47], v[128:131], v[194:197], v[44:47]
	v_mfma_f32_16x16x32_bf16 v[40:43], v[136:139], v[194:197], v[40:43]
	v_mfma_f32_16x16x32_bf16 v[28:31], v[128:131], v[202:205], v[28:31]
	v_mfma_f32_16x16x32_bf16 v[24:27], v[136:139], v[202:205], v[24:27]
	v_mfma_f32_16x16x32_bf16 v[12:15], v[128:131], v[210:213], v[12:15]
	v_mfma_f32_16x16x32_bf16 v[8:11], v[136:139], v[210:213], v[8:11]
	v_mfma_f32_16x16x32_bf16 v[60:63], v[132:135], v[180:183], v[60:63]
	v_mfma_f32_16x16x32_bf16 v[56:59], v[140:143], v[180:183], v[56:59]
	v_mfma_f32_16x16x32_bf16 v[44:47], v[132:135], v[198:201], v[44:47]
	v_mfma_f32_16x16x32_bf16 v[40:43], v[140:143], v[198:201], v[40:43]
	v_mfma_f32_16x16x32_bf16 v[28:31], v[132:135], v[206:209], v[28:31]
	v_mfma_f32_16x16x32_bf16 v[24:27], v[140:143], v[206:209], v[24:27]
	v_mfma_f32_16x16x32_bf16 v[12:15], v[132:135], v[214:217], v[12:15]
	v_mfma_f32_16x16x32_bf16 v[8:11], v[140:143], v[214:217], v[8:11]
	v_mfma_f32_16x16x32_bf16 v[52:55], v[144:147], v[176:179], v[52:55]
	v_mfma_f32_16x16x32_bf16 v[48:51], v[168:171], v[176:179], v[48:51]
	v_mfma_f32_16x16x32_bf16 v[36:39], v[144:147], v[194:197], v[36:39]
	v_mfma_f32_16x16x32_bf16 v[32:35], v[168:171], v[194:197], v[32:35]
	v_mfma_f32_16x16x32_bf16 v[20:23], v[144:147], v[202:205], v[20:23]
	v_mfma_f32_16x16x32_bf16 v[16:19], v[168:171], v[202:205], v[16:19]
	v_mfma_f32_16x16x32_bf16 v[4:7], v[144:147], v[210:213], v[4:7]
	v_mfma_f32_16x16x32_bf16 v[0:3], v[168:171], v[210:213], v[0:3]
	v_mfma_f32_16x16x32_bf16 v[52:55], v[148:151], v[180:183], v[52:55]
	v_mfma_f32_16x16x32_bf16 v[48:51], v[172:175], v[180:183], v[48:51]
	v_mfma_f32_16x16x32_bf16 v[36:39], v[148:151], v[198:201], v[36:39]
	v_mfma_f32_16x16x32_bf16 v[32:35], v[172:175], v[198:201], v[32:35]
	v_mfma_f32_16x16x32_bf16 v[20:23], v[148:151], v[206:209], v[20:23]
	v_mfma_f32_16x16x32_bf16 v[16:19], v[172:175], v[206:209], v[16:19]
	v_mfma_f32_16x16x32_bf16 v[4:7], v[148:151], v[214:217], v[4:7]
	v_mfma_f32_16x16x32_bf16 v[0:3], v[172:175], v[214:217], v[0:3]
	s_barrier
	s_add_i32 s60, 0, 0x18000
	s_add_i32 s61, 0, 0x1c000
	v_add_u32_e32 v140, s60, v187
	v_add_u32_e32 v172, s61, v187
	ds_read_b128 v[128:131], v140
	ds_read_b128 v[132:135], v140 offset:1024
	ds_read_b128 v[136:139], v140 offset:2048
	ds_read_b128 v[140:143], v140 offset:3072
	ds_read_b128 v[144:147], v172
	ds_read_b128 v[148:151], v172 offset:1024
	ds_read_b128 v[168:171], v172 offset:2048
	ds_read_b128 v[172:175], v172 offset:3072
	s_add_u32 s10, s10, 0xb0000
	s_addc_u32 s11, s11, 0
	s_mov_b32 m0, s35
	v_lshl_add_u64 v[226:227], s[10:11], 0, v[152:153]
	ds_read_b128 v[176:179], v191 offset:32768
	ds_read_b128 v[180:183], v191 offset:33792
	ds_read_b128 v[194:197], v191 offset:34816
	ds_read_b128 v[198:201], v191 offset:35840
	ds_read_b128 v[202:205], v191 offset:36864
	ds_read_b128 v[206:209], v191 offset:37888
	ds_read_b128 v[210:213], v191 offset:38912
	ds_read_b128 v[214:217], v191 offset:39936
	global_load_lds_dwordx4 v[226:227], off
	v_lshl_add_u64 v[226:227], s[10:11], 0, v[156:157]
	s_mov_b32 m0, s36
	s_nop 0
	global_load_lds_dwordx4 v[226:227], off
	s_waitcnt vmcnt(8)
	s_waitcnt lgkmcnt(0)
	s_barrier
	s_waitcnt lgkmcnt(0)
	v_mfma_f32_16x16x32_bf16 v[124:127], v[128:131], v[176:179], v[124:127]
	v_mfma_f32_16x16x32_bf16 v[120:123], v[136:139], v[176:179], v[120:123]
	v_mfma_f32_16x16x32_bf16 v[108:111], v[128:131], v[194:197], v[108:111]
	v_mfma_f32_16x16x32_bf16 v[104:107], v[136:139], v[194:197], v[104:107]
	v_mfma_f32_16x16x32_bf16 v[92:95], v[128:131], v[202:205], v[92:95]
	v_mfma_f32_16x16x32_bf16 v[88:91], v[136:139], v[202:205], v[88:91]
	v_mfma_f32_16x16x32_bf16 v[76:79], v[128:131], v[210:213], v[76:79]
	v_mfma_f32_16x16x32_bf16 v[72:75], v[136:139], v[210:213], v[72:75]
	v_mfma_f32_16x16x32_bf16 v[124:127], v[132:135], v[180:183], v[124:127]
	v_mfma_f32_16x16x32_bf16 v[120:123], v[140:143], v[180:183], v[120:123]
	v_mfma_f32_16x16x32_bf16 v[108:111], v[132:135], v[198:201], v[108:111]
	v_mfma_f32_16x16x32_bf16 v[104:107], v[140:143], v[198:201], v[104:107]
	v_mfma_f32_16x16x32_bf16 v[92:95], v[132:135], v[206:209], v[92:95]
	v_mfma_f32_16x16x32_bf16 v[88:91], v[140:143], v[206:209], v[88:91]
	v_mfma_f32_16x16x32_bf16 v[76:79], v[132:135], v[214:217], v[76:79]
	v_mfma_f32_16x16x32_bf16 v[72:75], v[140:143], v[214:217], v[72:75]
	v_mfma_f32_16x16x32_bf16 v[116:119], v[144:147], v[176:179], v[116:119]
	v_mfma_f32_16x16x32_bf16 v[112:115], v[168:171], v[176:179], v[112:115]
	v_mfma_f32_16x16x32_bf16 v[100:103], v[144:147], v[194:197], v[100:103]
	v_mfma_f32_16x16x32_bf16 v[96:99], v[168:171], v[194:197], v[96:99]
	v_mfma_f32_16x16x32_bf16 v[84:87], v[144:147], v[202:205], v[84:87]
	v_mfma_f32_16x16x32_bf16 v[80:83], v[168:171], v[202:205], v[80:83]
	v_mfma_f32_16x16x32_bf16 v[68:71], v[144:147], v[210:213], v[68:71]
	v_mfma_f32_16x16x32_bf16 v[64:67], v[168:171], v[210:213], v[64:67]
	v_mfma_f32_16x16x32_bf16 v[116:119], v[148:151], v[180:183], v[116:119]
	v_mfma_f32_16x16x32_bf16 v[112:115], v[172:175], v[180:183], v[112:115]
	v_mfma_f32_16x16x32_bf16 v[100:103], v[148:151], v[198:201], v[100:103]
	v_mfma_f32_16x16x32_bf16 v[96:99], v[172:175], v[198:201], v[96:99]
	v_mfma_f32_16x16x32_bf16 v[84:87], v[148:151], v[206:209], v[84:87]
	v_mfma_f32_16x16x32_bf16 v[80:83], v[172:175], v[206:209], v[80:83]
	v_mfma_f32_16x16x32_bf16 v[68:71], v[148:151], v[214:217], v[68:71]
	v_mfma_f32_16x16x32_bf16 v[64:67], v[172:175], v[214:217], v[64:67]
	s_barrier
; #define PG8_STAGE(bufoff, gbase, voff) do { _Pragma("unroll") for (int _i = 0; _i < 2; ++_i) \
;         __builtin_amdgcn_global_load_lds((const unsigned*)((const char*)(gbase) + (voff)[_i]), (PG8_LAS unsigned*)(lds + (bufoff) + ldsw + _i * 8192), 16, 0, 0); } while (0)
; #define PG8_LDA(dst, b, h) do { _Pragma("unroll") for (int m = 0; m < 4; ++m) _Pragma("unroll") for (int k = 0; k < 2; ++k) dst[m][k] = *(const PG8_LAS bf16x8*)(lds + PG8_SA(b, h) + aoff + m * 2048 + k * 1024); } while (0)
; #define PG8_MMA(ai, bj, At, Bt) do { __builtin_amdgcn_s_setprio(1); _Pragma("unroll") for (int m = 0; m < 4; ++m) _Pragma("unroll") for (int n = 0; n < 2; ++n) _Pragma("unroll") for (int k = 0; k < 2; ++k) \
;         acc[ai][bj][m][n] = __builtin_amdgcn_mfma_f32_16x16x32_bf16(Bt[n][k], At[m][k], acc[ai][bj][m][n], 0, 0, 0); __builtin_amdgcn_s_setprio(0); } while (0)
; #define PG8_WAIT_V(n) asm volatile("s_waitcnt vmcnt(" #n ")" ::: "memory")
; #define PG8_WAIT_L(n) asm volatile("s_waitcnt lgkmcnt(" #n ")" ::: "memory")
; #define PG8_BAR __builtin_amdgcn_s_barrier()
; #define PG8_SCHED __builtin_amdgcn_sched_barrier(0)
; template <class Epi, class Sched, bool ALIGN_EPI = false, bool SP2 = false>
; __device__ __forceinline__ void gemm_phase(PG8_LAS unsigned char* lds, const Gemm g, const Sched& S, const Epi& E) {
;     ...
;             PG8_LDA(At, 1, 1); PG8_STAGE(PG8_SB(1, 0), b3, voffB); PG8_STAGE(PG8_SB(1, 1), b3 + hstep, voffB); PG8_STAGE(PG8_SA(1, 0), a3, voffA);
;             PG8_WAIT_V(8); PG8_WAIT_L(0); PG8_BAR; PG8_MMA(1, 0, At, B0); PG8_MMA(1, 1, At, B1); PG8_BAR; PG8_SCHED;
;     ...
;         if constexpr (ALIGN_EPI) { if (wr == 0) PG8_BAR; }
;         if constexpr (!Epi::AFTER_DRAIN) { E(acc, cur, wr, wc, fr, fq); S.done(cur); }
;         if (!has_next) break;
	s_add_i32 s10, s60, s31
	v_lshl_add_u64 v[184:185], v[184:185], 0, s[18:19]
	s_mov_b32 m0, s10
	ds_read_b128 v[176:179], v191 offset:49152
	ds_read_b128 v[180:183], v191 offset:50176
	ds_read_b128 v[194:197], v191 offset:51200
	ds_read_b128 v[198:201], v191 offset:52224
	ds_read_b128 v[202:205], v191 offset:53248
	ds_read_b128 v[206:209], v191 offset:54272
	ds_read_b128 v[210:213], v191 offset:55296
	ds_read_b128 v[214:217], v191 offset:56320
	global_load_lds_dwordx4 v[184:185], off
	s_add_i32 m0, s10, 0x2000
	s_add_u32 s6, s6, 0xb0080
	v_lshl_add_u64 v[184:185], v[218:219], 0, s[18:19]
	s_addc_u32 s7, s7, 0
	s_add_i32 s10, s61, s31
	global_load_lds_dwordx4 v[184:185], off
	v_lshl_add_u64 v[184:185], s[6:7], 0, v[154:155]
	s_mov_b32 m0, s10
	s_nop 0
	global_load_lds_dwordx4 v[184:185], off
	v_lshl_add_u64 v[184:185], s[6:7], 0, v[158:159]
	s_add_i32 m0, s10, 0x2000
	s_nop 0
	global_load_lds_dwordx4 v[184:185], off
	v_lshl_add_u64 v[184:185], v[222:223], 0, s[18:19]
	s_mov_b32 m0, s46
	s_nop 0
	global_load_lds_dwordx4 v[184:185], off
	v_lshl_add_u64 v[184:185], v[224:225], 0, s[18:19]
	s_mov_b32 m0, s47
	s_nop 0
	global_load_lds_dwordx4 v[184:185], off
	s_waitcnt vmcnt(8)
	s_waitcnt lgkmcnt(0)
	s_barrier
	s_waitcnt lgkmcnt(0)
	v_mfma_f32_16x16x32_bf16 v[60:63], v[128:131], v[176:179], v[60:63]
	v_mfma_f32_16x16x32_bf16 v[56:59], v[136:139], v[176:179], v[56:59]
	v_mfma_f32_16x16x32_bf16 v[44:47], v[128:131], v[194:197], v[44:47]
	v_mfma_f32_16x16x32_bf16 v[40:43], v[136:139], v[194:197], v[40:43]
	v_mfma_f32_16x16x32_bf16 v[28:31], v[128:131], v[202:205], v[28:31]
	v_mfma_f32_16x16x32_bf16 v[24:27], v[136:139], v[202:205], v[24:27]
	v_mfma_f32_16x16x32_bf16 v[12:15], v[128:131], v[210:213], v[12:15]
	v_mfma_f32_16x16x32_bf16 v[8:11], v[136:139], v[210:213], v[8:11]
	v_mfma_f32_16x16x32_bf16 v[60:63], v[132:135], v[180:183], v[60:63]
	v_mfma_f32_16x16x32_bf16 v[56:59], v[140:143], v[180:183], v[56:59]
	v_mfma_f32_16x16x32_bf16 v[44:47], v[132:135], v[198:201], v[44:47]
	v_mfma_f32_16x16x32_bf16 v[40:43], v[140:143], v[198:201], v[40:43]
	v_mfma_f32_16x16x32_bf16 v[28:31], v[132:135], v[206:209], v[28:31]
	v_mfma_f32_16x16x32_bf16 v[24:27], v[140:143], v[206:209], v[24:27]
	v_mfma_f32_16x16x32_bf16 v[12:15], v[132:135], v[214:217], v[12:15]
	v_mfma_f32_16x16x32_bf16 v[8:11], v[140:143], v[214:217], v[8:11]
	v_mfma_f32_16x16x32_bf16 v[52:55], v[144:147], v[176:179], v[52:55]
	v_mfma_f32_16x16x32_bf16 v[48:51], v[168:171], v[176:179], v[48:51]
	v_mfma_f32_16x16x32_bf16 v[36:39], v[144:147], v[194:197], v[36:39]
	v_mfma_f32_16x16x32_bf16 v[32:35], v[168:171], v[194:197], v[32:35]
	v_mfma_f32_16x16x32_bf16 v[20:23], v[144:147], v[202:205], v[20:23]
	v_mfma_f32_16x16x32_bf16 v[16:19], v[168:171], v[202:205], v[16:19]
	v_mfma_f32_16x16x32_bf16 v[4:7], v[144:147], v[210:213], v[4:7]
	v_mfma_f32_16x16x32_bf16 v[0:3], v[168:171], v[210:213], v[0:3]
	v_mfma_f32_16x16x32_bf16 v[52:55], v[148:151], v[180:183], v[52:55]
	v_mfma_f32_16x16x32_bf16 v[48:51], v[172:175], v[180:183], v[48:51]
	v_mfma_f32_16x16x32_bf16 v[36:39], v[148:151], v[198:201], v[36:39]
	v_mfma_f32_16x16x32_bf16 v[32:35], v[172:175], v[198:201], v[32:35]
	v_mfma_f32_16x16x32_bf16 v[20:23], v[148:151], v[206:209], v[20:23]
	v_mfma_f32_16x16x32_bf16 v[16:19], v[172:175], v[206:209], v[16:19]
	v_mfma_f32_16x16x32_bf16 v[4:7], v[148:151], v[214:217], v[4:7]
	v_mfma_f32_16x16x32_bf16 v[0:3], v[172:175], v[214:217], v[0:3]
	s_barrier
	s_add_i32 s59, s59, 2
	s_add_u32 s28, s28, 0x100
	s_addc_u32 s29, s29, 0
	s_add_u32 s57, s57, 0x100
	s_addc_u32 s58, s58, 0
	s_cmp_gt_u32 s59, 41
	s_cbranch_scc0 .LBB0_660
	s_and_b64 vcc, exec, s[20:21]
	s_cbranch_vccz .LBB0_663
	s_barrier

; #define PG8_STAGE(bufoff, gbase, voff) do { _Pragma("unroll") for (int _i = 0; _i < 2; ++_i) \
;         __builtin_amdgcn_global_load_lds((const unsigned*)((const char*)(gbase) + (voff)[_i]), (PG8_LAS unsigned*)(lds + (bufoff) + ldsw + _i * 8192), 16, 0, 0); } while (0)
; #define PG8_LDA(dst, b, h) do { _Pragma("unroll") for (int m = 0; m < 4; ++m) _Pragma("unroll") for (int k = 0; k < 2; ++k) dst[m][k] = *(const PG8_LAS bf16x8*)(lds + PG8_SA(b, h) + aoff + m * 2048 + k * 1024); } while (0)
; #define PG8_LDB(dst, b, h) do { _Pragma("unroll") for (int n = 0; n < 2; ++n) _Pragma("unroll") for (int k = 0; k < 2; ++k) dst[n][k] = *(const PG8_LAS bf16x8*)(lds + PG8_SB(b, h) + boff + n * 2048 + k * 1024); } while (0)
; #define PG8_WAIT_V(n) asm volatile("s_waitcnt vmcnt(" #n ")" ::: "memory")
; #define PG8_WAIT_L(n) asm volatile("s_waitcnt lgkmcnt(" #n ")" ::: "memory")
; #define PG8_BAR __builtin_amdgcn_s_barrier()
; #define PG8_SCHED __builtin_amdgcn_sched_barrier(0)
; template <class Epi, class Sched, bool ALIGN_EPI = false, bool SP2 = false>
; __device__ __forceinline__ void gemm_phase(PG8_LAS unsigned char* lds, const Gemm g, const Sched& S, const Epi& E) {
;     ...
;         const bool has_next = S.next(ui + 1, nxt);
;         const char* nA = has_next ? (const char*)g.A + (size_t)nxt.pm * tstep : cA; const char* nB = has_next ? (const char*)g.Bt + (size_t)nxt.pn * tstep : cB;
;         for (int t = 0; t < nt; t += 2) {
;             const bool last = (t == nt - 2);
;             const char* a1 = cA + (size_t)(t + 1) * kstep;
;             const char* a2 = last ? nA : cA + (size_t)(t + 2) * kstep; const char* b2 = last ? nB : cB + (size_t)(t + 2) * kstep;
;             const char* a3 = a2 + kstep; const char* b3 = b2 + kstep;
;             if (last && has_next) S.a_ready(nxt);
;             if constexpr (SP2) {
;             PG8_LDB(B0, 0, 0); PG8_LDB(B1, 0, 1); PG8_SCHED; PG8_LDA(At, 0, 0); PG8_STAGE(PG8_SA(1, 1), a1 + hstep, voffA);
;             PG8_WAIT_V(8); PG8_WAIT_L(0); PG8_BAR; PG8_MMA(0, 0, At, B0); PG8_MMA(0, 1, At, B1); PG8_BAR; PG8_SCHED;
;             PG8_LDA(At, 0, 1); PG8_STAGE(PG8_SB(0, 0), b2, voffB); PG8_STAGE(PG8_SB(0, 1), b2 + hstep, voffB); PG8_STAGE(PG8_SA(0, 0), a2, voffA);
;             PG8_WAIT_V(8); PG8_WAIT_L(0); PG8_BAR; PG8_MMA(1, 0, At, B0); PG8_MMA(1, 1, At, B1); PG8_BAR; PG8_SCHED;
.LBB0_814:
	ds_read_b128 v[128:131], v176
	ds_read_b128 v[132:135], v176 offset:1024
	ds_read_b128 v[136:139], v176 offset:2048
	ds_read_b128 v[140:143], v176 offset:3072
	ds_read_b128 v[164:167], v177
	ds_read_b128 v[180:183], v177 offset:1024
	ds_read_b128 v[184:187], v177 offset:2048
	ds_read_b128 v[188:191], v177 offset:3072
	s_add_u32 s6, s36, 0xfffc0080
	s_addc_u32 s7, s37, -1
	s_cmp_eq_u32 s62, 12
	s_cselect_b32 s11, s27, s7
	s_cselect_b32 s10, s58, s6
	s_cselect_b32 s7, s21, s61
	s_cselect_b32 s6, s59, s60
	v_lshl_add_u64 v[226:227], s[36:37], 0, v[156:157]
	s_add_i32 m0, s46, 0xc000
	ds_read_b128 v[192:195], v178
	ds_read_b128 v[196:199], v178 offset:1024
	ds_read_b128 v[200:203], v178 offset:2048
	ds_read_b128 v[204:207], v178 offset:3072
	ds_read_b128 v[208:211], v178 offset:4096
	ds_read_b128 v[212:215], v178 offset:5120
	ds_read_b128 v[216:219], v178 offset:6144
	ds_read_b128 v[222:225], v178 offset:7168
	global_load_lds_dwordx4 v[226:227], off
	v_lshl_add_u64 v[226:227], s[36:37], 0, v[158:159]
	s_add_i32 m0, s46, 0xe000
	s_nop 0
	global_load_lds_dwordx4 v[226:227], off
	s_waitcnt vmcnt(8)
	s_waitcnt lgkmcnt(0)
	s_barrier
	s_waitcnt lgkmcnt(0)
	v_mfma_f32_16x16x32_bf16 v[124:127], v[128:131], v[192:195], v[124:127]
	v_mfma_f32_16x16x32_bf16 v[120:123], v[136:139], v[192:195], v[120:123]
	v_mfma_f32_16x16x32_bf16 v[108:111], v[128:131], v[200:203], v[108:111]
	v_mfma_f32_16x16x32_bf16 v[104:107], v[136:139], v[200:203], v[104:107]
	v_mfma_f32_16x16x32_bf16 v[92:95], v[128:131], v[208:211], v[92:95]
	v_mfma_f32_16x16x32_bf16 v[88:91], v[136:139], v[208:211], v[88:91]
	v_mfma_f32_16x16x32_bf16 v[76:79], v[128:131], v[216:219], v[76:79]
	v_mfma_f32_16x16x32_bf16 v[72:75], v[136:139], v[216:219], v[72:75]
	v_mfma_f32_16x16x32_bf16 v[124:127], v[132:135], v[196:199], v[124:127]
	v_mfma_f32_16x16x32_bf16 v[120:123], v[140:143], v[196:199], v[120:123]
	v_mfma_f32_16x16x32_bf16 v[108:111], v[132:135], v[204:207], v[108:111]
	v_mfma_f32_16x16x32_bf16 v[104:107], v[140:143], v[204:207], v[104:107]
	v_mfma_f32_16x16x32_bf16 v[92:95], v[132:135], v[212:215], v[92:95]
	v_mfma_f32_16x16x32_bf16 v[88:91], v[140:143], v[212:215], v[88:91]
	v_mfma_f32_16x16x32_bf16 v[76:79], v[132:135], v[222:225], v[76:79]
	v_mfma_f32_16x16x32_bf16 v[72:75], v[140:143], v[222:225], v[72:75]
	v_mfma_f32_16x16x32_bf16 v[116:119], v[164:167], v[192:195], v[116:119]
	v_mfma_f32_16x16x32_bf16 v[112:115], v[184:187], v[192:195], v[112:115]
	v_mfma_f32_16x16x32_bf16 v[100:103], v[164:167], v[200:203], v[100:103]
	v_mfma_f32_16x16x32_bf16 v[96:99], v[184:187], v[200:203], v[96:99]
	v_mfma_f32_16x16x32_bf16 v[84:87], v[164:167], v[208:211], v[84:87]
	v_mfma_f32_16x16x32_bf16 v[80:83], v[184:187], v[208:211], v[80:83]
	v_mfma_f32_16x16x32_bf16 v[68:71], v[164:167], v[216:219], v[68:71]
	v_mfma_f32_16x16x32_bf16 v[64:67], v[184:187], v[216:219], v[64:67]
	v_mfma_f32_16x16x32_bf16 v[116:119], v[180:183], v[196:199], v[116:119]
	v_mfma_f32_16x16x32_bf16 v[112:115], v[188:191], v[196:199], v[112:115]
	v_mfma_f32_16x16x32_bf16 v[100:103], v[180:183], v[204:207], v[100:103]
	v_mfma_f32_16x16x32_bf16 v[96:99], v[188:191], v[204:207], v[96:99]
	v_mfma_f32_16x16x32_bf16 v[84:87], v[180:183], v[212:215], v[84:87]
	v_mfma_f32_16x16x32_bf16 v[80:83], v[188:191], v[212:215], v[80:83]
	v_mfma_f32_16x16x32_bf16 v[68:71], v[180:183], v[222:225], v[68:71]
	v_mfma_f32_16x16x32_bf16 v[64:67], v[188:191], v[222:225], v[64:67]
	s_barrier
	s_add_i32 s63, s55, s33
	v_lshl_add_u64 v[226:227], s[6:7], 0, v[148:149]
	s_mov_b32 m0, s63
	ds_read_b128 v[192:195], v178 offset:16384
	ds_read_b128 v[196:199], v178 offset:17408
	ds_read_b128 v[200:203], v178 offset:18432
	ds_read_b128 v[204:207], v178 offset:19456
	ds_read_b128 v[208:211], v178 offset:20480
	ds_read_b128 v[212:215], v178 offset:21504
	ds_read_b128 v[216:219], v178 offset:22528
	ds_read_b128 v[222:225], v178 offset:23552
	global_load_lds_dwordx4 v[226:227], off
	s_add_i32 m0, s63, 0x2000
	s_add_u32 s64, s6, 0x40000
	v_lshl_add_u64 v[228:229], s[6:7], 0, v[152:153]
	s_addc_u32 s65, s7, 0
	s_add_i32 s63, s56, s33
	global_load_lds_dwordx4 v[228:229], off
	v_lshl_add_u64 v[230:231], s[64:65], 0, v[148:149]
	s_mov_b32 m0, s63
	v_lshl_add_u64 v[232:233], s[10:11], 0, v[150:151]
	global_load_lds_dwordx4 v[230:231], off
	v_lshl_add_u64 v[230:231], s[64:65], 0, v[152:153]
	s_add_i32 m0, s63, 0x2000
	s_nop 0
	global_load_lds_dwordx4 v[230:231], off
	v_lshl_add_u64 v[230:231], s[10:11], 0, v[146:147]
	s_mov_b32 m0, s46
	s_nop 0
	global_load_lds_dwordx4 v[230:231], off
	s_mov_b32 m0, s47
	s_nop 0
	global_load_lds_dwordx4 v[232:233], off
	s_waitcnt vmcnt(8)
	s_waitcnt lgkmcnt(0)
	s_barrier
; #define PG8_STAGE(bufoff, gbase, voff) do { _Pragma("unroll") for (int _i = 0; _i < 2; ++_i) \
;         __builtin_amdgcn_global_load_lds((const unsigned*)((const char*)(gbase) + (voff)[_i]), (PG8_LAS unsigned*)(lds + (bufoff) + ldsw + _i * 8192), 16, 0, 0); } while (0)
; #define PG8_LDA(dst, b, h) do { _Pragma("unroll") for (int m = 0; m < 4; ++m) _Pragma("unroll") for (int k = 0; k < 2; ++k) dst[m][k] = *(const PG8_LAS bf16x8*)(lds + PG8_SA(b, h) + aoff + m * 2048 + k * 1024); } while (0)
; #define PG8_LDB(dst, b, h) do { _Pragma("unroll") for (int n = 0; n < 2; ++n) _Pragma("unroll") for (int k = 0; k < 2; ++k) dst[n][k] = *(const PG8_LAS bf16x8*)(lds + PG8_SB(b, h) + boff + n * 2048 + k * 1024); } while (0)
; #define PG8_MMA(ai, bj, At, Bt) do { __builtin_amdgcn_s_setprio(1); _Pragma("unroll") for (int m = 0; m < 4; ++m) _Pragma("unroll") for (int n = 0; n < 2; ++n) _Pragma("unroll") for (int k = 0; k < 2; ++k) \
;         acc[ai][bj][m][n] = __builtin_amdgcn_mfma_f32_16x16x32_bf16(Bt[n][k], At[m][k], acc[ai][bj][m][n], 0, 0, 0); __builtin_amdgcn_s_setprio(0); } while (0)
; #define PG8_WAIT_V(n) asm volatile("s_waitcnt vmcnt(" #n ")" ::: "memory")
; #define PG8_WAIT_L(n) asm volatile("s_waitcnt lgkmcnt(" #n ")" ::: "memory")
; #define PG8_BAR __builtin_amdgcn_s_barrier()
; #define PG8_SCHED __builtin_amdgcn_sched_barrier(0)
; template <class Epi, class Sched, bool ALIGN_EPI = false, bool SP2 = false>
; __device__ __forceinline__ void gemm_phase(PG8_LAS unsigned char* lds, const Gemm g, const Sched& S, const Epi& E) {
;     ...
;             PG8_WAIT_V(8); PG8_WAIT_L(0); PG8_BAR; PG8_MMA(1, 0, At, B0); PG8_MMA(1, 1, At, B1); PG8_BAR; PG8_SCHED;
;             PG8_LDB(B0, 1, 0); PG8_LDB(B1, 1, 1); PG8_SCHED; PG8_LDA(At, 1, 0); PG8_STAGE(PG8_SA(0, 1), a2 + hstep, voffA);
;             PG8_WAIT_V(8); PG8_WAIT_L(0); PG8_BAR; PG8_MMA(0, 0, At, B0); PG8_MMA(0, 1, At, B1); PG8_BAR; PG8_SCHED;
	s_waitcnt lgkmcnt(0)
	v_mfma_f32_16x16x32_bf16 v[60:63], v[128:131], v[192:195], v[60:63]
	v_mfma_f32_16x16x32_bf16 v[56:59], v[136:139], v[192:195], v[56:59]
	v_mfma_f32_16x16x32_bf16 v[44:47], v[128:131], v[200:203], v[44:47]
	v_mfma_f32_16x16x32_bf16 v[40:43], v[136:139], v[200:203], v[40:43]
	v_mfma_f32_16x16x32_bf16 v[28:31], v[128:131], v[208:211], v[28:31]
	v_mfma_f32_16x16x32_bf16 v[24:27], v[136:139], v[208:211], v[24:27]
	v_mfma_f32_16x16x32_bf16 v[12:15], v[128:131], v[216:219], v[12:15]
	v_mfma_f32_16x16x32_bf16 v[8:11], v[136:139], v[216:219], v[8:11]
	v_mfma_f32_16x16x32_bf16 v[60:63], v[132:135], v[196:199], v[60:63]
	v_mfma_f32_16x16x32_bf16 v[56:59], v[140:143], v[196:199], v[56:59]
	v_mfma_f32_16x16x32_bf16 v[44:47], v[132:135], v[204:207], v[44:47]
	v_mfma_f32_16x16x32_bf16 v[40:43], v[140:143], v[204:207], v[40:43]
	v_mfma_f32_16x16x32_bf16 v[28:31], v[132:135], v[212:215], v[28:31]
	v_mfma_f32_16x16x32_bf16 v[24:27], v[140:143], v[212:215], v[24:27]
	v_mfma_f32_16x16x32_bf16 v[12:15], v[132:135], v[222:225], v[12:15]
	v_mfma_f32_16x16x32_bf16 v[8:11], v[140:143], v[222:225], v[8:11]
	v_mfma_f32_16x16x32_bf16 v[52:55], v[164:167], v[192:195], v[52:55]
	v_mfma_f32_16x16x32_bf16 v[48:51], v[184:187], v[192:195], v[48:51]
	v_mfma_f32_16x16x32_bf16 v[36:39], v[164:167], v[200:203], v[36:39]
	v_mfma_f32_16x16x32_bf16 v[32:35], v[184:187], v[200:203], v[32:35]
	v_mfma_f32_16x16x32_bf16 v[20:23], v[164:167], v[208:211], v[20:23]
	v_mfma_f32_16x16x32_bf16 v[16:19], v[184:187], v[208:211], v[16:19]
	v_mfma_f32_16x16x32_bf16 v[4:7], v[164:167], v[216:219], v[4:7]
	v_mfma_f32_16x16x32_bf16 v[0:3], v[184:187], v[216:219], v[0:3]
	v_mfma_f32_16x16x32_bf16 v[52:55], v[180:183], v[196:199], v[52:55]
	v_mfma_f32_16x16x32_bf16 v[48:51], v[188:191], v[196:199], v[48:51]
	v_mfma_f32_16x16x32_bf16 v[36:39], v[180:183], v[204:207], v[36:39]
	v_mfma_f32_16x16x32_bf16 v[32:35], v[188:191], v[204:207], v[32:35]
	v_mfma_f32_16x16x32_bf16 v[20:23], v[180:183], v[212:215], v[20:23]
	v_mfma_f32_16x16x32_bf16 v[16:19], v[188:191], v[212:215], v[16:19]
	v_mfma_f32_16x16x32_bf16 v[4:7], v[180:183], v[222:225], v[4:7]
	v_mfma_f32_16x16x32_bf16 v[0:3], v[188:191], v[222:225], v[0:3]
	s_barrier
	s_add_i32 s63, 0, 0x18000
	s_add_i32 s64, 0, 0x1c000
	v_add_u32_e32 v140, s63, v175
	v_add_u32_e32 v179, s64, v175
	ds_read_b128 v[128:131], v140
	ds_read_b128 v[132:135], v140 offset:1024
	ds_read_b128 v[136:139], v140 offset:2048
	ds_read_b128 v[140:143], v140 offset:3072
	ds_read_b128 v[164:167], v179
	ds_read_b128 v[180:183], v179 offset:1024
	ds_read_b128 v[184:187], v179 offset:2048
	ds_read_b128 v[188:191], v179 offset:3072
	s_add_u32 s10, s10, 0x40000
	s_addc_u32 s11, s11, 0
	s_mov_b32 m0, s48
	v_lshl_add_u64 v[234:235], s[10:11], 0, v[146:147]
	ds_read_b128 v[192:195], v178 offset:32768
	ds_read_b128 v[196:199], v178 offset:33792
	ds_read_b128 v[200:203], v178 offset:34816
	ds_read_b128 v[204:207], v178 offset:35840
	ds_read_b128 v[208:211], v178 offset:36864
	ds_read_b128 v[212:215], v178 offset:37888
	ds_read_b128 v[216:219], v178 offset:38912
	ds_read_b128 v[222:225], v178 offset:39936
	global_load_lds_dwordx4 v[234:235], off
	v_lshl_add_u64 v[234:235], s[10:11], 0, v[150:151]
	s_mov_b32 m0, s49
	s_nop 0
	global_load_lds_dwordx4 v[234:235], off
	s_waitcnt vmcnt(8)
	s_waitcnt lgkmcnt(0)
	s_barrier
	s_waitcnt lgkmcnt(0)
	v_mfma_f32_16x16x32_bf16 v[124:127], v[128:131], v[192:195], v[124:127]
	v_mfma_f32_16x16x32_bf16 v[120:123], v[136:139], v[192:195], v[120:123]
	v_mfma_f32_16x16x32_bf16 v[108:111], v[128:131], v[200:203], v[108:111]
	v_mfma_f32_16x16x32_bf16 v[104:107], v[136:139], v[200:203], v[104:107]
	v_mfma_f32_16x16x32_bf16 v[92:95], v[128:131], v[208:211], v[92:95]
	v_mfma_f32_16x16x32_bf16 v[88:91], v[136:139], v[208:211], v[88:91]
	v_mfma_f32_16x16x32_bf16 v[76:79], v[128:131], v[216:219], v[76:79]
	v_mfma_f32_16x16x32_bf16 v[72:75], v[136:139], v[216:219], v[72:75]
	v_mfma_f32_16x16x32_bf16 v[124:127], v[132:135], v[196:199], v[124:127]
	v_mfma_f32_16x16x32_bf16 v[120:123], v[140:143], v[196:199], v[120:123]
	v_mfma_f32_16x16x32_bf16 v[108:111], v[132:135], v[204:207], v[108:111]
	v_mfma_f32_16x16x32_bf16 v[104:107], v[140:143], v[204:207], v[104:107]
	v_mfma_f32_16x16x32_bf16 v[92:95], v[132:135], v[212:215], v[92:95]
	v_mfma_f32_16x16x32_bf16 v[88:91], v[140:143], v[212:215], v[88:91]
	v_mfma_f32_16x16x32_bf16 v[76:79], v[132:135], v[222:225], v[76:79]
	v_mfma_f32_16x16x32_bf16 v[72:75], v[140:143], v[222:225], v[72:75]
	v_mfma_f32_16x16x32_bf16 v[116:119], v[164:167], v[192:195], v[116:119]
	v_mfma_f32_16x16x32_bf16 v[112:115], v[184:187], v[192:195], v[112:115]
	v_mfma_f32_16x16x32_bf16 v[100:103], v[164:167], v[200:203], v[100:103]
	v_mfma_f32_16x16x32_bf16 v[96:99], v[184:187], v[200:203], v[96:99]
	v_mfma_f32_16x16x32_bf16 v[84:87], v[164:167], v[208:211], v[84:87]
	v_mfma_f32_16x16x32_bf16 v[80:83], v[184:187], v[208:211], v[80:83]
	v_mfma_f32_16x16x32_bf16 v[68:71], v[164:167], v[216:219], v[68:71]
	v_mfma_f32_16x16x32_bf16 v[64:67], v[184:187], v[216:219], v[64:67]
	v_mfma_f32_16x16x32_bf16 v[116:119], v[180:183], v[196:199], v[116:119]
	v_mfma_f32_16x16x32_bf16 v[112:115], v[188:191], v[196:199], v[112:115]
	v_mfma_f32_16x16x32_bf16 v[100:103], v[180:183], v[204:207], v[100:103]
	v_mfma_f32_16x16x32_bf16 v[96:99], v[188:191], v[204:207], v[96:99]
	v_mfma_f32_16x16x32_bf16 v[84:87], v[180:183], v[212:215], v[84:87]
	v_mfma_f32_16x16x32_bf16 v[80:83], v[188:191], v[212:215], v[80:83]
	v_mfma_f32_16x16x32_bf16 v[68:71], v[180:183], v[222:225], v[68:71]
	v_mfma_f32_16x16x32_bf16 v[64:67], v[188:191], v[222:225], v[64:67]
	s_barrier
; #define PG8_STAGE(bufoff, gbase, voff) do { _Pragma("unroll") for (int _i = 0; _i < 2; ++_i) \
;         __builtin_amdgcn_global_load_lds((const unsigned*)((const char*)(gbase) + (voff)[_i]), (PG8_LAS unsigned*)(lds + (bufoff) + ldsw + _i * 8192), 16, 0, 0); } while (0)
; #define PG8_LDA(dst, b, h) do { _Pragma("unroll") for (int m = 0; m < 4; ++m) _Pragma("unroll") for (int k = 0; k < 2; ++k) dst[m][k] = *(const PG8_LAS bf16x8*)(lds + PG8_SA(b, h) + aoff + m * 2048 + k * 1024); } while (0)
; #define PG8_MMA(ai, bj, At, Bt) do { __builtin_amdgcn_s_setprio(1); _Pragma("unroll") for (int m = 0; m < 4; ++m) _Pragma("unroll") for (int n = 0; n < 2; ++n) _Pragma("unroll") for (int k = 0; k < 2; ++k) \
;         acc[ai][bj][m][n] = __builtin_amdgcn_mfma_f32_16x16x32_bf16(Bt[n][k], At[m][k], acc[ai][bj][m][n], 0, 0, 0); __builtin_amdgcn_s_setprio(0); } while (0)
; #define PG8_WAIT_V(n) asm volatile("s_waitcnt vmcnt(" #n ")" ::: "memory")
; #define PG8_WAIT_L(n) asm volatile("s_waitcnt lgkmcnt(" #n ")" ::: "memory")
; #define PG8_BAR __builtin_amdgcn_s_barrier()
; #define PG8_SCHED __builtin_amdgcn_sched_barrier(0)
; template <class Epi, class Sched, bool ALIGN_EPI = false, bool SP2 = false>
; __device__ __forceinline__ void gemm_phase(PG8_LAS unsigned char* lds, const Gemm g, const Sched& S, const Epi& E) {
;     ...
;             PG8_LDA(At, 1, 1); PG8_STAGE(PG8_SB(1, 0), b3, voffB); PG8_STAGE(PG8_SB(1, 1), b3 + hstep, voffB); PG8_STAGE(PG8_SA(1, 0), a3, voffA);
;             PG8_WAIT_V(8); PG8_WAIT_L(0); PG8_BAR; PG8_MMA(1, 0, At, B0); PG8_MMA(1, 1, At, B1); PG8_BAR; PG8_SCHED;
;     ...
;         if constexpr (ALIGN_EPI) { if (wr == 0) PG8_BAR; }
;         if constexpr (!Epi::AFTER_DRAIN) { E(acc, cur, wr, wc, fr, fq); S.done(cur); }
;         if (!has_next) break;
	s_add_i32 s10, s63, s33
	v_lshl_add_u64 v[226:227], v[226:227], 0, s[16:17]
	s_mov_b32 m0, s10
	ds_read_b128 v[192:195], v178 offset:49152
	ds_read_b128 v[196:199], v178 offset:50176
	ds_read_b128 v[200:203], v178 offset:51200
	ds_read_b128 v[204:207], v178 offset:52224
	ds_read_b128 v[208:211], v178 offset:53248
	ds_read_b128 v[212:215], v178 offset:54272
	ds_read_b128 v[216:219], v178 offset:55296
	ds_read_b128 v[222:225], v178 offset:56320
	global_load_lds_dwordx4 v[226:227], off
	s_add_i32 m0, s10, 0x2000
	s_add_u32 s6, s6, 0x40080
	v_lshl_add_u64 v[226:227], v[228:229], 0, s[16:17]
	s_addc_u32 s7, s7, 0
	s_add_i32 s10, s64, s33
	global_load_lds_dwordx4 v[226:227], off
	v_lshl_add_u64 v[226:227], s[6:7], 0, v[148:149]
	s_mov_b32 m0, s10
	s_nop 0
	global_load_lds_dwordx4 v[226:227], off
	v_lshl_add_u64 v[226:227], s[6:7], 0, v[152:153]
	s_add_i32 m0, s10, 0x2000
	s_nop 0
	global_load_lds_dwordx4 v[226:227], off
	v_lshl_add_u64 v[226:227], v[230:231], 0, s[16:17]
	s_mov_b32 m0, s51
	s_nop 0
	global_load_lds_dwordx4 v[226:227], off
	v_lshl_add_u64 v[226:227], v[232:233], 0, s[16:17]
	s_mov_b32 m0, s52
	s_nop 0
	global_load_lds_dwordx4 v[226:227], off
	s_waitcnt vmcnt(8)
	s_waitcnt lgkmcnt(0)
	s_barrier
	s_waitcnt lgkmcnt(0)
	v_mfma_f32_16x16x32_bf16 v[60:63], v[128:131], v[192:195], v[60:63]
	v_mfma_f32_16x16x32_bf16 v[56:59], v[136:139], v[192:195], v[56:59]
	v_mfma_f32_16x16x32_bf16 v[44:47], v[128:131], v[200:203], v[44:47]
	v_mfma_f32_16x16x32_bf16 v[40:43], v[136:139], v[200:203], v[40:43]
	v_mfma_f32_16x16x32_bf16 v[28:31], v[128:131], v[208:211], v[28:31]
	v_mfma_f32_16x16x32_bf16 v[24:27], v[136:139], v[208:211], v[24:27]
	v_mfma_f32_16x16x32_bf16 v[12:15], v[128:131], v[216:219], v[12:15]
	v_mfma_f32_16x16x32_bf16 v[8:11], v[136:139], v[216:219], v[8:11]
	v_mfma_f32_16x16x32_bf16 v[60:63], v[132:135], v[196:199], v[60:63]
	v_mfma_f32_16x16x32_bf16 v[56:59], v[140:143], v[196:199], v[56:59]
	v_mfma_f32_16x16x32_bf16 v[44:47], v[132:135], v[204:207], v[44:47]
	v_mfma_f32_16x16x32_bf16 v[40:43], v[140:143], v[204:207], v[40:43]
	v_mfma_f32_16x16x32_bf16 v[28:31], v[132:135], v[212:215], v[28:31]
	v_mfma_f32_16x16x32_bf16 v[24:27], v[140:143], v[212:215], v[24:27]
	v_mfma_f32_16x16x32_bf16 v[12:15], v[132:135], v[222:225], v[12:15]
	v_mfma_f32_16x16x32_bf16 v[8:11], v[140:143], v[222:225], v[8:11]
	v_mfma_f32_16x16x32_bf16 v[52:55], v[164:167], v[192:195], v[52:55]
	v_mfma_f32_16x16x32_bf16 v[48:51], v[184:187], v[192:195], v[48:51]
	v_mfma_f32_16x16x32_bf16 v[36:39], v[164:167], v[200:203], v[36:39]
	v_mfma_f32_16x16x32_bf16 v[32:35], v[184:187], v[200:203], v[32:35]
	v_mfma_f32_16x16x32_bf16 v[20:23], v[164:167], v[208:211], v[20:23]
	v_mfma_f32_16x16x32_bf16 v[16:19], v[184:187], v[208:211], v[16:19]
	v_mfma_f32_16x16x32_bf16 v[4:7], v[164:167], v[216:219], v[4:7]
	v_mfma_f32_16x16x32_bf16 v[0:3], v[184:187], v[216:219], v[0:3]
	v_mfma_f32_16x16x32_bf16 v[52:55], v[180:183], v[196:199], v[52:55]
	v_mfma_f32_16x16x32_bf16 v[48:51], v[188:191], v[196:199], v[48:51]
	v_mfma_f32_16x16x32_bf16 v[36:39], v[180:183], v[204:207], v[36:39]
	v_mfma_f32_16x16x32_bf16 v[32:35], v[188:191], v[204:207], v[32:35]
	v_mfma_f32_16x16x32_bf16 v[20:23], v[180:183], v[212:215], v[20:23]
	v_mfma_f32_16x16x32_bf16 v[16:19], v[188:191], v[212:215], v[16:19]
	v_mfma_f32_16x16x32_bf16 v[4:7], v[180:183], v[222:225], v[4:7]
	v_mfma_f32_16x16x32_bf16 v[0:3], v[188:191], v[222:225], v[0:3]
	s_barrier
	s_add_i32 s62, s62, 2
	s_add_u32 s36, s36, 0x100
	s_addc_u32 s37, s37, 0
	s_add_u32 s60, s60, 0x100
	s_addc_u32 s61, s61, 0
	s_cmp_gt_u32 s62, 13
	s_cbranch_scc0 .LBB0_814
	s_and_b64 vcc, exec, s[18:19]
	s_cbranch_vccz .LBB0_817
	s_barrier

; #define PG8_STAGE(bufoff, gbase, voff) do { _Pragma("unroll") for (int _i = 0; _i < 2; ++_i) \
;         __builtin_amdgcn_global_load_lds((const unsigned*)((const char*)(gbase) + (voff)[_i]), (PG8_LAS unsigned*)(lds + (bufoff) + ldsw + _i * 8192), 16, 0, 0); } while (0)
; #define PG8_LDA(dst, b, h) do { _Pragma("unroll") for (int m = 0; m < 4; ++m) _Pragma("unroll") for (int k = 0; k < 2; ++k) dst[m][k] = *(const PG8_LAS bf16x8*)(lds + PG8_SA(b, h) + aoff + m * 2048 + k * 1024); } while (0)
; #define PG8_LDB(dst, b, h) do { _Pragma("unroll") for (int n = 0; n < 2; ++n) _Pragma("unroll") for (int k = 0; k < 2; ++k) dst[n][k] = *(const PG8_LAS bf16x8*)(lds + PG8_SB(b, h) + boff + n * 2048 + k * 1024); } while (0)
; #define PG8_WAIT_V(n) asm volatile("s_waitcnt vmcnt(" #n ")" ::: "memory")
; #define PG8_WAIT_L(n) asm volatile("s_waitcnt lgkmcnt(" #n ")" ::: "memory")
; #define PG8_BAR __builtin_amdgcn_s_barrier()
; #define PG8_SCHED __builtin_amdgcn_sched_barrier(0)
; template <class Epi, class Sched, bool ALIGN_EPI = false, bool SP2 = false>
; __device__ __forceinline__ void gemm_phase(PG8_LAS unsigned char* lds, const Gemm g, const Sched& S, const Epi& E) {
;     ...
;         const bool has_next = S.next(ui + 1, nxt);
;         const char* nA = has_next ? (const char*)g.A + (size_t)nxt.pm * tstep : cA; const char* nB = has_next ? (const char*)g.Bt + (size_t)nxt.pn * tstep : cB;
;         for (int t = 0; t < nt; t += 2) {
;             const bool last = (t == nt - 2);
;             const char* a1 = cA + (size_t)(t + 1) * kstep;
;             const char* a2 = last ? nA : cA + (size_t)(t + 2) * kstep; const char* b2 = last ? nB : cB + (size_t)(t + 2) * kstep;
;             const char* a3 = a2 + kstep; const char* b3 = b2 + kstep;
;             if (last && has_next) S.a_ready(nxt);
;             if constexpr (SP2) {
;             PG8_LDB(B0, 0, 0); PG8_LDB(B1, 0, 1); PG8_SCHED; PG8_LDA(At, 0, 0); PG8_STAGE(PG8_SA(1, 1), a1 + hstep, voffA);
;             PG8_WAIT_V(8); PG8_WAIT_L(0); PG8_BAR; PG8_MMA(0, 0, At, B0); PG8_MMA(0, 1, At, B1); PG8_BAR; PG8_SCHED;
;             PG8_LDA(At, 0, 1); PG8_STAGE(PG8_SB(0, 0), b2, voffB); PG8_STAGE(PG8_SB(0, 1), b2 + hstep, voffB); PG8_STAGE(PG8_SA(0, 0), a2, voffA);
;             PG8_WAIT_V(8); PG8_WAIT_L(0); PG8_BAR; PG8_MMA(1, 0, At, B0); PG8_MMA(1, 1, At, B1); PG8_BAR; PG8_SCHED;
.LBB0_838:
	ds_read_b128 v[128:131], v170
	ds_read_b128 v[132:135], v170 offset:1024
	ds_read_b128 v[136:139], v170 offset:2048
	ds_read_b128 v[140:143], v170 offset:3072
	ds_read_b128 v[166:169], v171
	ds_read_b128 v[174:177], v171 offset:1024
	ds_read_b128 v[178:181], v171 offset:2048
	ds_read_b128 v[182:185], v171 offset:3072
	s_add_u32 s6, s30, 0xfffc0080
	s_addc_u32 s7, s31, -1
	s_cmp_eq_u32 s65, 12
	s_cselect_b32 s35, s21, s7
	s_cselect_b32 s34, s61, s6
	s_cselect_b32 s7, s19, s64
	s_cselect_b32 s6, s62, s63
	v_lshl_add_u64 v[218:219], s[30:31], 0, v[156:157]
	s_add_i32 m0, s46, 0xc000
	ds_read_b128 v[186:189], v173
	ds_read_b128 v[190:193], v173 offset:1024
	ds_read_b128 v[194:197], v173 offset:2048
	ds_read_b128 v[198:201], v173 offset:3072
	ds_read_b128 v[202:205], v173 offset:4096
	ds_read_b128 v[206:209], v173 offset:5120
	ds_read_b128 v[210:213], v173 offset:6144
	ds_read_b128 v[214:217], v173 offset:7168
	global_load_lds_dwordx4 v[218:219], off
	v_lshl_add_u64 v[218:219], s[30:31], 0, v[158:159]
	s_add_i32 m0, s46, 0xe000
	s_nop 0
	global_load_lds_dwordx4 v[218:219], off
	s_waitcnt vmcnt(8)
	s_waitcnt lgkmcnt(0)
	s_barrier
	s_waitcnt lgkmcnt(0)
	v_mfma_f32_16x16x32_bf16 v[124:127], v[128:131], v[186:189], v[124:127]
	v_mfma_f32_16x16x32_bf16 v[120:123], v[136:139], v[186:189], v[120:123]
	v_mfma_f32_16x16x32_bf16 v[108:111], v[128:131], v[194:197], v[108:111]
	v_mfma_f32_16x16x32_bf16 v[104:107], v[136:139], v[194:197], v[104:107]
	v_mfma_f32_16x16x32_bf16 v[92:95], v[128:131], v[202:205], v[92:95]
	v_mfma_f32_16x16x32_bf16 v[88:91], v[136:139], v[202:205], v[88:91]
	v_mfma_f32_16x16x32_bf16 v[76:79], v[128:131], v[210:213], v[76:79]
	v_mfma_f32_16x16x32_bf16 v[72:75], v[136:139], v[210:213], v[72:75]
	v_mfma_f32_16x16x32_bf16 v[124:127], v[132:135], v[190:193], v[124:127]
	v_mfma_f32_16x16x32_bf16 v[120:123], v[140:143], v[190:193], v[120:123]
	v_mfma_f32_16x16x32_bf16 v[108:111], v[132:135], v[198:201], v[108:111]
	v_mfma_f32_16x16x32_bf16 v[104:107], v[140:143], v[198:201], v[104:107]
	v_mfma_f32_16x16x32_bf16 v[92:95], v[132:135], v[206:209], v[92:95]
	v_mfma_f32_16x16x32_bf16 v[88:91], v[140:143], v[206:209], v[88:91]
	v_mfma_f32_16x16x32_bf16 v[76:79], v[132:135], v[214:217], v[76:79]
	v_mfma_f32_16x16x32_bf16 v[72:75], v[140:143], v[214:217], v[72:75]
	v_mfma_f32_16x16x32_bf16 v[116:119], v[166:169], v[186:189], v[116:119]
	v_mfma_f32_16x16x32_bf16 v[112:115], v[178:181], v[186:189], v[112:115]
	v_mfma_f32_16x16x32_bf16 v[100:103], v[166:169], v[194:197], v[100:103]
	v_mfma_f32_16x16x32_bf16 v[96:99], v[178:181], v[194:197], v[96:99]
	v_mfma_f32_16x16x32_bf16 v[84:87], v[166:169], v[202:205], v[84:87]
	v_mfma_f32_16x16x32_bf16 v[80:83], v[178:181], v[202:205], v[80:83]
	v_mfma_f32_16x16x32_bf16 v[68:71], v[166:169], v[210:213], v[68:71]
	v_mfma_f32_16x16x32_bf16 v[64:67], v[178:181], v[210:213], v[64:67]
	v_mfma_f32_16x16x32_bf16 v[116:119], v[174:177], v[190:193], v[116:119]
	v_mfma_f32_16x16x32_bf16 v[112:115], v[182:185], v[190:193], v[112:115]
	v_mfma_f32_16x16x32_bf16 v[100:103], v[174:177], v[198:201], v[100:103]
	v_mfma_f32_16x16x32_bf16 v[96:99], v[182:185], v[198:201], v[96:99]
	v_mfma_f32_16x16x32_bf16 v[84:87], v[174:177], v[206:209], v[84:87]
	v_mfma_f32_16x16x32_bf16 v[80:83], v[182:185], v[206:209], v[80:83]
	v_mfma_f32_16x16x32_bf16 v[68:71], v[174:177], v[214:217], v[68:71]
	v_mfma_f32_16x16x32_bf16 v[64:67], v[182:185], v[214:217], v[64:67]
	s_barrier
	s_add_i32 s66, s59, s37
	v_lshl_add_u64 v[218:219], s[6:7], 0, v[148:149]
	s_mov_b32 m0, s66
	ds_read_b128 v[186:189], v173 offset:16384
	ds_read_b128 v[190:193], v173 offset:17408
	ds_read_b128 v[194:197], v173 offset:18432
	ds_read_b128 v[198:201], v173 offset:19456
	ds_read_b128 v[202:205], v173 offset:20480
	ds_read_b128 v[206:209], v173 offset:21504
	ds_read_b128 v[210:213], v173 offset:22528
	ds_read_b128 v[214:217], v173 offset:23552
	global_load_lds_dwordx4 v[218:219], off
	s_add_i32 m0, s66, 0x2000
	s_add_u32 s66, s6, 0x40000
	v_lshl_add_u64 v[222:223], s[6:7], 0, v[152:153]
	s_addc_u32 s67, s7, 0
	s_add_i32 s76, s60, s37
	global_load_lds_dwordx4 v[222:223], off
	v_lshl_add_u64 v[224:225], s[66:67], 0, v[148:149]
	s_mov_b32 m0, s76
	v_lshl_add_u64 v[226:227], s[34:35], 0, v[150:151]
	global_load_lds_dwordx4 v[224:225], off
	v_lshl_add_u64 v[224:225], s[66:67], 0, v[152:153]
	s_add_i32 m0, s76, 0x2000
	s_nop 0
	global_load_lds_dwordx4 v[224:225], off
	v_lshl_add_u64 v[224:225], s[34:35], 0, v[146:147]
	s_mov_b32 m0, s46
	s_nop 0
	global_load_lds_dwordx4 v[224:225], off
	s_mov_b32 m0, s47
	s_nop 0
	global_load_lds_dwordx4 v[226:227], off
	s_waitcnt vmcnt(8)
	s_waitcnt lgkmcnt(0)
	s_barrier
; #define PG8_STAGE(bufoff, gbase, voff) do { _Pragma("unroll") for (int _i = 0; _i < 2; ++_i) \
;         __builtin_amdgcn_global_load_lds((const unsigned*)((const char*)(gbase) + (voff)[_i]), (PG8_LAS unsigned*)(lds + (bufoff) + ldsw + _i * 8192), 16, 0, 0); } while (0)
; #define PG8_LDA(dst, b, h) do { _Pragma("unroll") for (int m = 0; m < 4; ++m) _Pragma("unroll") for (int k = 0; k < 2; ++k) dst[m][k] = *(const PG8_LAS bf16x8*)(lds + PG8_SA(b, h) + aoff + m * 2048 + k * 1024); } while (0)
; #define PG8_LDB(dst, b, h) do { _Pragma("unroll") for (int n = 0; n < 2; ++n) _Pragma("unroll") for (int k = 0; k < 2; ++k) dst[n][k] = *(const PG8_LAS bf16x8*)(lds + PG8_SB(b, h) + boff + n * 2048 + k * 1024); } while (0)
; #define PG8_MMA(ai, bj, At, Bt) do { __builtin_amdgcn_s_setprio(1); _Pragma("unroll") for (int m = 0; m < 4; ++m) _Pragma("unroll") for (int n = 0; n < 2; ++n) _Pragma("unroll") for (int k = 0; k < 2; ++k) \
;         acc[ai][bj][m][n] = __builtin_amdgcn_mfma_f32_16x16x32_bf16(Bt[n][k], At[m][k], acc[ai][bj][m][n], 0, 0, 0); __builtin_amdgcn_s_setprio(0); } while (0)
; #define PG8_WAIT_V(n) asm volatile("s_waitcnt vmcnt(" #n ")" ::: "memory")
; #define PG8_WAIT_L(n) asm volatile("s_waitcnt lgkmcnt(" #n ")" ::: "memory")
; #define PG8_BAR __builtin_amdgcn_s_barrier()
; #define PG8_SCHED __builtin_amdgcn_sched_barrier(0)
; template <class Epi, class Sched, bool ALIGN_EPI = false, bool SP2 = false>
; __device__ __forceinline__ void gemm_phase(PG8_LAS unsigned char* lds, const Gemm g, const Sched& S, const Epi& E) {
;     ...
;             PG8_WAIT_V(8); PG8_WAIT_L(0); PG8_BAR; PG8_MMA(1, 0, At, B0); PG8_MMA(1, 1, At, B1); PG8_BAR; PG8_SCHED;
;             PG8_LDB(B0, 1, 0); PG8_LDB(B1, 1, 1); PG8_SCHED; PG8_LDA(At, 1, 0); PG8_STAGE(PG8_SA(0, 1), a2 + hstep, voffA);
;             PG8_WAIT_V(8); PG8_WAIT_L(0); PG8_BAR; PG8_MMA(0, 0, At, B0); PG8_MMA(0, 1, At, B1); PG8_BAR; PG8_SCHED;
	s_waitcnt lgkmcnt(0)
	v_mfma_f32_16x16x32_bf16 v[60:63], v[128:131], v[186:189], v[60:63]
	v_mfma_f32_16x16x32_bf16 v[56:59], v[136:139], v[186:189], v[56:59]
	v_mfma_f32_16x16x32_bf16 v[44:47], v[128:131], v[194:197], v[44:47]
	v_mfma_f32_16x16x32_bf16 v[40:43], v[136:139], v[194:197], v[40:43]
	v_mfma_f32_16x16x32_bf16 v[28:31], v[128:131], v[202:205], v[28:31]
	v_mfma_f32_16x16x32_bf16 v[24:27], v[136:139], v[202:205], v[24:27]
	v_mfma_f32_16x16x32_bf16 v[12:15], v[128:131], v[210:213], v[12:15]
	v_mfma_f32_16x16x32_bf16 v[8:11], v[136:139], v[210:213], v[8:11]
	v_mfma_f32_16x16x32_bf16 v[60:63], v[132:135], v[190:193], v[60:63]
	v_mfma_f32_16x16x32_bf16 v[56:59], v[140:143], v[190:193], v[56:59]
	v_mfma_f32_16x16x32_bf16 v[44:47], v[132:135], v[198:201], v[44:47]
	v_mfma_f32_16x16x32_bf16 v[40:43], v[140:143], v[198:201], v[40:43]
	v_mfma_f32_16x16x32_bf16 v[28:31], v[132:135], v[206:209], v[28:31]
	v_mfma_f32_16x16x32_bf16 v[24:27], v[140:143], v[206:209], v[24:27]
	v_mfma_f32_16x16x32_bf16 v[12:15], v[132:135], v[214:217], v[12:15]
	v_mfma_f32_16x16x32_bf16 v[8:11], v[140:143], v[214:217], v[8:11]
	v_mfma_f32_16x16x32_bf16 v[52:55], v[166:169], v[186:189], v[52:55]
	v_mfma_f32_16x16x32_bf16 v[48:51], v[178:181], v[186:189], v[48:51]
	v_mfma_f32_16x16x32_bf16 v[36:39], v[166:169], v[194:197], v[36:39]
	v_mfma_f32_16x16x32_bf16 v[32:35], v[178:181], v[194:197], v[32:35]
	v_mfma_f32_16x16x32_bf16 v[20:23], v[166:169], v[202:205], v[20:23]
	v_mfma_f32_16x16x32_bf16 v[16:19], v[178:181], v[202:205], v[16:19]
	v_mfma_f32_16x16x32_bf16 v[4:7], v[166:169], v[210:213], v[4:7]
	v_mfma_f32_16x16x32_bf16 v[0:3], v[178:181], v[210:213], v[0:3]
	v_mfma_f32_16x16x32_bf16 v[52:55], v[174:177], v[190:193], v[52:55]
	v_mfma_f32_16x16x32_bf16 v[48:51], v[182:185], v[190:193], v[48:51]
	v_mfma_f32_16x16x32_bf16 v[36:39], v[174:177], v[198:201], v[36:39]
	v_mfma_f32_16x16x32_bf16 v[32:35], v[182:185], v[198:201], v[32:35]
	v_mfma_f32_16x16x32_bf16 v[20:23], v[174:177], v[206:209], v[20:23]
	v_mfma_f32_16x16x32_bf16 v[16:19], v[182:185], v[206:209], v[16:19]
	v_mfma_f32_16x16x32_bf16 v[4:7], v[174:177], v[214:217], v[4:7]
	v_mfma_f32_16x16x32_bf16 v[0:3], v[182:185], v[214:217], v[0:3]
	s_barrier
	s_add_i32 s66, 0, 0x18000
	s_add_i32 s67, 0, 0x1c000
	v_add_u32_e32 v140, s66, v172
	v_add_u32_e32 v154, s67, v172
	ds_read_b128 v[128:131], v140
	ds_read_b128 v[132:135], v140 offset:1024
	ds_read_b128 v[136:139], v140 offset:2048
	ds_read_b128 v[140:143], v140 offset:3072
	ds_read_b128 v[166:169], v154
	ds_read_b128 v[174:177], v154 offset:1024
	ds_read_b128 v[178:181], v154 offset:2048
	ds_read_b128 v[182:185], v154 offset:3072
	s_add_u32 s34, s34, 0x40000
	s_addc_u32 s35, s35, 0
	s_mov_b32 m0, s48
	v_lshl_add_u64 v[228:229], s[34:35], 0, v[146:147]
	ds_read_b128 v[186:189], v173 offset:32768
	ds_read_b128 v[190:193], v173 offset:33792
	ds_read_b128 v[194:197], v173 offset:34816
	ds_read_b128 v[198:201], v173 offset:35840
	ds_read_b128 v[202:205], v173 offset:36864
	ds_read_b128 v[206:209], v173 offset:37888
	ds_read_b128 v[210:213], v173 offset:38912
	ds_read_b128 v[214:217], v173 offset:39936
	global_load_lds_dwordx4 v[228:229], off
	v_lshl_add_u64 v[228:229], s[34:35], 0, v[150:151]
	s_mov_b32 m0, s49
	s_nop 0
	global_load_lds_dwordx4 v[228:229], off
	s_waitcnt vmcnt(8)
	s_waitcnt lgkmcnt(0)
	s_barrier
	s_waitcnt lgkmcnt(0)
	v_mfma_f32_16x16x32_bf16 v[124:127], v[128:131], v[186:189], v[124:127]
	v_mfma_f32_16x16x32_bf16 v[120:123], v[136:139], v[186:189], v[120:123]
	v_mfma_f32_16x16x32_bf16 v[108:111], v[128:131], v[194:197], v[108:111]
	v_mfma_f32_16x16x32_bf16 v[104:107], v[136:139], v[194:197], v[104:107]
	v_mfma_f32_16x16x32_bf16 v[92:95], v[128:131], v[202:205], v[92:95]
	v_mfma_f32_16x16x32_bf16 v[88:91], v[136:139], v[202:205], v[88:91]
	v_mfma_f32_16x16x32_bf16 v[76:79], v[128:131], v[210:213], v[76:79]
	v_mfma_f32_16x16x32_bf16 v[72:75], v[136:139], v[210:213], v[72:75]
	v_mfma_f32_16x16x32_bf16 v[124:127], v[132:135], v[190:193], v[124:127]
	v_mfma_f32_16x16x32_bf16 v[120:123], v[140:143], v[190:193], v[120:123]
	v_mfma_f32_16x16x32_bf16 v[108:111], v[132:135], v[198:201], v[108:111]
	v_mfma_f32_16x16x32_bf16 v[104:107], v[140:143], v[198:201], v[104:107]
	v_mfma_f32_16x16x32_bf16 v[92:95], v[132:135], v[206:209], v[92:95]
	v_mfma_f32_16x16x32_bf16 v[88:91], v[140:143], v[206:209], v[88:91]
	v_mfma_f32_16x16x32_bf16 v[76:79], v[132:135], v[214:217], v[76:79]
	v_mfma_f32_16x16x32_bf16 v[72:75], v[140:143], v[214:217], v[72:75]
	v_mfma_f32_16x16x32_bf16 v[116:119], v[166:169], v[186:189], v[116:119]
	v_mfma_f32_16x16x32_bf16 v[112:115], v[178:181], v[186:189], v[112:115]
	v_mfma_f32_16x16x32_bf16 v[100:103], v[166:169], v[194:197], v[100:103]
	v_mfma_f32_16x16x32_bf16 v[96:99], v[178:181], v[194:197], v[96:99]
	v_mfma_f32_16x16x32_bf16 v[84:87], v[166:169], v[202:205], v[84:87]
	v_mfma_f32_16x16x32_bf16 v[80:83], v[178:181], v[202:205], v[80:83]
	v_mfma_f32_16x16x32_bf16 v[68:71], v[166:169], v[210:213], v[68:71]
	v_mfma_f32_16x16x32_bf16 v[64:67], v[178:181], v[210:213], v[64:67]
	v_mfma_f32_16x16x32_bf16 v[116:119], v[174:177], v[190:193], v[116:119]
	v_mfma_f32_16x16x32_bf16 v[112:115], v[182:185], v[190:193], v[112:115]
	v_mfma_f32_16x16x32_bf16 v[100:103], v[174:177], v[198:201], v[100:103]
	v_mfma_f32_16x16x32_bf16 v[96:99], v[182:185], v[198:201], v[96:99]
	v_mfma_f32_16x16x32_bf16 v[84:87], v[174:177], v[206:209], v[84:87]
	v_mfma_f32_16x16x32_bf16 v[80:83], v[182:185], v[206:209], v[80:83]
	v_mfma_f32_16x16x32_bf16 v[68:71], v[174:177], v[214:217], v[68:71]
	v_mfma_f32_16x16x32_bf16 v[64:67], v[182:185], v[214:217], v[64:67]
	s_barrier
; #define PG8_STAGE(bufoff, gbase, voff) do { _Pragma("unroll") for (int _i = 0; _i < 2; ++_i) \
;         __builtin_amdgcn_global_load_lds((const unsigned*)((const char*)(gbase) + (voff)[_i]), (PG8_LAS unsigned*)(lds + (bufoff) + ldsw + _i * 8192), 16, 0, 0); } while (0)
; #define PG8_LDA(dst, b, h) do { _Pragma("unroll") for (int m = 0; m < 4; ++m) _Pragma("unroll") for (int k = 0; k < 2; ++k) dst[m][k] = *(const PG8_LAS bf16x8*)(lds + PG8_SA(b, h) + aoff + m * 2048 + k * 1024); } while (0)
; #define PG8_MMA(ai, bj, At, Bt) do { __builtin_amdgcn_s_setprio(1); _Pragma("unroll") for (int m = 0; m < 4; ++m) _Pragma("unroll") for (int n = 0; n < 2; ++n) _Pragma("unroll") for (int k = 0; k < 2; ++k) \
;         acc[ai][bj][m][n] = __builtin_amdgcn_mfma_f32_16x16x32_bf16(Bt[n][k], At[m][k], acc[ai][bj][m][n], 0, 0, 0); __builtin_amdgcn_s_setprio(0); } while (0)
; #define PG8_WAIT_V(n) asm volatile("s_waitcnt vmcnt(" #n ")" ::: "memory")
; #define PG8_WAIT_L(n) asm volatile("s_waitcnt lgkmcnt(" #n ")" ::: "memory")
; #define PG8_BAR __builtin_amdgcn_s_barrier()
; #define PG8_SCHED __builtin_amdgcn_sched_barrier(0)
; template <class Epi, class Sched, bool ALIGN_EPI = false, bool SP2 = false>
; __device__ __forceinline__ void gemm_phase(PG8_LAS unsigned char* lds, const Gemm g, const Sched& S, const Epi& E) {
;     ...
;             PG8_LDA(At, 1, 1); PG8_STAGE(PG8_SB(1, 0), b3, voffB); PG8_STAGE(PG8_SB(1, 1), b3 + hstep, voffB); PG8_STAGE(PG8_SA(1, 0), a3, voffA);
;             PG8_WAIT_V(8); PG8_WAIT_L(0); PG8_BAR; PG8_MMA(1, 0, At, B0); PG8_MMA(1, 1, At, B1); PG8_BAR; PG8_SCHED;
;     ...
;         if constexpr (ALIGN_EPI) { if (wr == 0) PG8_BAR; }
;         if constexpr (!Epi::AFTER_DRAIN) { E(acc, cur, wr, wc, fr, fq); S.done(cur); }
;         if (!has_next) break;
	s_add_i32 s34, s66, s37
	v_lshl_add_u64 v[218:219], v[218:219], 0, s[14:15]
	s_mov_b32 m0, s34
	ds_read_b128 v[186:189], v173 offset:49152
	ds_read_b128 v[190:193], v173 offset:50176
	ds_read_b128 v[194:197], v173 offset:51200
	ds_read_b128 v[198:201], v173 offset:52224
	ds_read_b128 v[202:205], v173 offset:53248
	ds_read_b128 v[206:209], v173 offset:54272
	ds_read_b128 v[210:213], v173 offset:55296
	ds_read_b128 v[214:217], v173 offset:56320
	global_load_lds_dwordx4 v[218:219], off
	s_add_i32 m0, s34, 0x2000
	s_add_u32 s6, s6, 0x40080
	v_lshl_add_u64 v[218:219], v[222:223], 0, s[14:15]
	s_addc_u32 s7, s7, 0
	s_add_i32 s34, s67, s37
	global_load_lds_dwordx4 v[218:219], off
	v_lshl_add_u64 v[218:219], s[6:7], 0, v[148:149]
	s_mov_b32 m0, s34
	s_nop 0
	global_load_lds_dwordx4 v[218:219], off
	v_lshl_add_u64 v[218:219], s[6:7], 0, v[152:153]
	s_add_i32 m0, s34, 0x2000
	s_nop 0
	global_load_lds_dwordx4 v[218:219], off
	v_lshl_add_u64 v[218:219], v[224:225], 0, s[14:15]
	s_mov_b32 m0, s55
	s_nop 0
	global_load_lds_dwordx4 v[218:219], off
	v_lshl_add_u64 v[218:219], v[226:227], 0, s[14:15]
	s_mov_b32 m0, s56
	s_nop 0
	global_load_lds_dwordx4 v[218:219], off
	s_waitcnt vmcnt(8)
	s_waitcnt lgkmcnt(0)
	s_barrier
	s_waitcnt lgkmcnt(0)
	v_mfma_f32_16x16x32_bf16 v[60:63], v[128:131], v[186:189], v[60:63]
	v_mfma_f32_16x16x32_bf16 v[56:59], v[136:139], v[186:189], v[56:59]
	v_mfma_f32_16x16x32_bf16 v[44:47], v[128:131], v[194:197], v[44:47]
	v_mfma_f32_16x16x32_bf16 v[40:43], v[136:139], v[194:197], v[40:43]
	v_mfma_f32_16x16x32_bf16 v[28:31], v[128:131], v[202:205], v[28:31]
	v_mfma_f32_16x16x32_bf16 v[24:27], v[136:139], v[202:205], v[24:27]
	v_mfma_f32_16x16x32_bf16 v[12:15], v[128:131], v[210:213], v[12:15]
	v_mfma_f32_16x16x32_bf16 v[8:11], v[136:139], v[210:213], v[8:11]
	v_mfma_f32_16x16x32_bf16 v[60:63], v[132:135], v[190:193], v[60:63]
	v_mfma_f32_16x16x32_bf16 v[56:59], v[140:143], v[190:193], v[56:59]
	v_mfma_f32_16x16x32_bf16 v[44:47], v[132:135], v[198:201], v[44:47]
	v_mfma_f32_16x16x32_bf16 v[40:43], v[140:143], v[198:201], v[40:43]
	v_mfma_f32_16x16x32_bf16 v[28:31], v[132:135], v[206:209], v[28:31]
	v_mfma_f32_16x16x32_bf16 v[24:27], v[140:143], v[206:209], v[24:27]
	v_mfma_f32_16x16x32_bf16 v[12:15], v[132:135], v[214:217], v[12:15]
	v_mfma_f32_16x16x32_bf16 v[8:11], v[140:143], v[214:217], v[8:11]
	v_mfma_f32_16x16x32_bf16 v[52:55], v[166:169], v[186:189], v[52:55]
	v_mfma_f32_16x16x32_bf16 v[48:51], v[178:181], v[186:189], v[48:51]
	v_mfma_f32_16x16x32_bf16 v[36:39], v[166:169], v[194:197], v[36:39]
	v_mfma_f32_16x16x32_bf16 v[32:35], v[178:181], v[194:197], v[32:35]
	v_mfma_f32_16x16x32_bf16 v[20:23], v[166:169], v[202:205], v[20:23]
	v_mfma_f32_16x16x32_bf16 v[16:19], v[178:181], v[202:205], v[16:19]
	v_mfma_f32_16x16x32_bf16 v[4:7], v[166:169], v[210:213], v[4:7]
	v_mfma_f32_16x16x32_bf16 v[0:3], v[178:181], v[210:213], v[0:3]
	v_mfma_f32_16x16x32_bf16 v[52:55], v[174:177], v[190:193], v[52:55]
	v_mfma_f32_16x16x32_bf16 v[48:51], v[182:185], v[190:193], v[48:51]
	v_mfma_f32_16x16x32_bf16 v[36:39], v[174:177], v[198:201], v[36:39]
	v_mfma_f32_16x16x32_bf16 v[32:35], v[182:185], v[198:201], v[32:35]
	v_mfma_f32_16x16x32_bf16 v[20:23], v[174:177], v[206:209], v[20:23]
	v_mfma_f32_16x16x32_bf16 v[16:19], v[182:185], v[206:209], v[16:19]
	v_mfma_f32_16x16x32_bf16 v[4:7], v[174:177], v[214:217], v[4:7]
	v_mfma_f32_16x16x32_bf16 v[0:3], v[182:185], v[214:217], v[0:3]
	s_barrier
	s_add_i32 s65, s65, 2
	s_add_u32 s30, s30, 0x100
	s_addc_u32 s31, s31, 0
	s_add_u32 s63, s63, 0x100
	s_addc_u32 s64, s64, 0
	s_cmp_gt_u32 s65, 13
	s_cbranch_scc0 .LBB0_838
	s_and_b64 vcc, exec, s[16:17]
	s_cbranch_vccz .LBB0_841
	s_barrier

; #define PG8_STAGE(bufoff, gbase, voff) do { _Pragma("unroll") for (int _i = 0; _i < 2; ++_i) \
;         __builtin_amdgcn_global_load_lds((const unsigned*)((const char*)(gbase) + (voff)[_i]), (PG8_LAS unsigned*)(lds + (bufoff) + ldsw + _i * 8192), 16, 0, 0); } while (0)
; #define PG8_LDA(dst, b, h) do { _Pragma("unroll") for (int m = 0; m < 4; ++m) _Pragma("unroll") for (int k = 0; k < 2; ++k) dst[m][k] = *(const PG8_LAS bf16x8*)(lds + PG8_SA(b, h) + aoff + m * 2048 + k * 1024); } while (0)
; #define PG8_LDB(dst, b, h) do { _Pragma("unroll") for (int n = 0; n < 2; ++n) _Pragma("unroll") for (int k = 0; k < 2; ++k) dst[n][k] = *(const PG8_LAS bf16x8*)(lds + PG8_SB(b, h) + boff + n * 2048 + k * 1024); } while (0)
; #define PG8_WAIT_V(n) asm volatile("s_waitcnt vmcnt(" #n ")" ::: "memory")
; #define PG8_WAIT_L(n) asm volatile("s_waitcnt lgkmcnt(" #n ")" ::: "memory")
; #define PG8_BAR __builtin_amdgcn_s_barrier()
; #define PG8_SCHED __builtin_amdgcn_sched_barrier(0)
; template <class Epi, class Sched, bool ALIGN_EPI = false, bool SP2 = false>
; __device__ __forceinline__ void gemm_phase(PG8_LAS unsigned char* lds, const Gemm g, const Sched& S, const Epi& E) {
;     ...
;         const bool has_next = S.next(ui + 1, nxt);
;         const char* nA = has_next ? (const char*)g.A + (size_t)nxt.pm * tstep : cA; const char* nB = has_next ? (const char*)g.Bt + (size_t)nxt.pn * tstep : cB;
;         for (int t = 0; t < nt; t += 2) {
;             const bool last = (t == nt - 2);
;             const char* a1 = cA + (size_t)(t + 1) * kstep;
;             const char* a2 = last ? nA : cA + (size_t)(t + 2) * kstep; const char* b2 = last ? nB : cB + (size_t)(t + 2) * kstep;
;             const char* a3 = a2 + kstep; const char* b3 = b2 + kstep;
;             if (last && has_next) S.a_ready(nxt);
;             if constexpr (SP2) {
;             PG8_LDB(B0, 0, 0); PG8_LDB(B1, 0, 1); PG8_SCHED; PG8_LDA(At, 0, 0); PG8_STAGE(PG8_SA(1, 1), a1 + hstep, voffA);
;             PG8_WAIT_V(8); PG8_WAIT_L(0); PG8_BAR; PG8_MMA(0, 0, At, B0); PG8_MMA(0, 1, At, B1); PG8_BAR; PG8_SCHED;
;             PG8_LDA(At, 0, 1); PG8_STAGE(PG8_SB(0, 0), b2, voffB); PG8_STAGE(PG8_SB(0, 1), b2 + hstep, voffB); PG8_STAGE(PG8_SA(0, 0), a2, voffA);
;             PG8_WAIT_V(8); PG8_WAIT_L(0); PG8_BAR; PG8_MMA(1, 0, At, B0); PG8_MMA(1, 1, At, B1); PG8_BAR; PG8_SCHED;
.LBB0_987:
	ds_read_b128 v[80:83], v205
	ds_read_b128 v[84:87], v205 offset:1024
	ds_read_b128 v[92:95], v205 offset:2048
	ds_read_b128 v[96:99], v205 offset:3072
	ds_read_b128 v[144:147], v206
	ds_read_b128 v[148:151], v206 offset:1024
	ds_read_b128 v[152:155], v206 offset:2048
	ds_read_b128 v[156:159], v206 offset:3072
	s_add_u32 s6, s8, 0xfffc0080
	s_addc_u32 s7, s9, -1
	s_cmp_eq_u32 s59, 12
	s_cselect_b32 s35, s25, s7
	s_cselect_b32 s34, s55, s6
	s_cselect_b32 s7, s23, s58
	s_cselect_b32 s6, s56, s57
	v_lshl_add_u64 v[200:201], s[8:9], 0, v[176:177]
	s_add_i32 m0, s31, 0xc000
	ds_read_b128 v[160:163], v207
	ds_read_b128 v[164:167], v207 offset:1024
	ds_read_b128 v[184:187], v207 offset:2048
	ds_read_b128 v[188:191], v207 offset:3072
	ds_read_b128 v[192:195], v207 offset:4096
	ds_read_b128 v[196:199], v207 offset:5120
	ds_read_b128 v[210:213], v207 offset:6144
	ds_read_b128 v[214:217], v207 offset:7168
	global_load_lds_dwordx4 v[200:201], off
	v_lshl_add_u64 v[200:201], s[8:9], 0, v[178:179]
	s_add_i32 m0, s31, 0xe000
	s_nop 0
	global_load_lds_dwordx4 v[200:201], off
	s_waitcnt vmcnt(8)
	s_waitcnt lgkmcnt(0)
	s_barrier
	s_waitcnt lgkmcnt(0)
	v_mfma_f32_16x16x32_bf16 v[140:143], v[80:83], v[160:163], v[140:143]
	v_mfma_f32_16x16x32_bf16 v[136:139], v[92:95], v[160:163], v[136:139]
	v_mfma_f32_16x16x32_bf16 v[124:127], v[80:83], v[184:187], v[124:127]
	v_mfma_f32_16x16x32_bf16 v[120:123], v[92:95], v[184:187], v[120:123]
	v_mfma_f32_16x16x32_bf16 v[108:111], v[80:83], v[192:195], v[108:111]
	v_mfma_f32_16x16x32_bf16 v[104:107], v[92:95], v[192:195], v[104:107]
	v_mfma_f32_16x16x32_bf16 v[76:79], v[80:83], v[210:213], v[76:79]
	v_mfma_f32_16x16x32_bf16 v[72:75], v[92:95], v[210:213], v[72:75]
	v_mfma_f32_16x16x32_bf16 v[140:143], v[84:87], v[164:167], v[140:143]
	v_mfma_f32_16x16x32_bf16 v[136:139], v[96:99], v[164:167], v[136:139]
	v_mfma_f32_16x16x32_bf16 v[124:127], v[84:87], v[188:191], v[124:127]
	v_mfma_f32_16x16x32_bf16 v[120:123], v[96:99], v[188:191], v[120:123]
	v_mfma_f32_16x16x32_bf16 v[108:111], v[84:87], v[196:199], v[108:111]
	v_mfma_f32_16x16x32_bf16 v[104:107], v[96:99], v[196:199], v[104:107]
	v_mfma_f32_16x16x32_bf16 v[76:79], v[84:87], v[214:217], v[76:79]
	v_mfma_f32_16x16x32_bf16 v[72:75], v[96:99], v[214:217], v[72:75]
	v_mfma_f32_16x16x32_bf16 v[132:135], v[144:147], v[160:163], v[132:135]
	v_mfma_f32_16x16x32_bf16 v[128:131], v[152:155], v[160:163], v[128:131]
	v_mfma_f32_16x16x32_bf16 v[116:119], v[144:147], v[184:187], v[116:119]
	v_mfma_f32_16x16x32_bf16 v[112:115], v[152:155], v[184:187], v[112:115]
	v_mfma_f32_16x16x32_bf16 v[100:103], v[144:147], v[192:195], v[100:103]
	v_mfma_f32_16x16x32_bf16 v[88:91], v[152:155], v[192:195], v[88:91]
	v_mfma_f32_16x16x32_bf16 v[68:71], v[144:147], v[210:213], v[68:71]
	v_mfma_f32_16x16x32_bf16 v[64:67], v[152:155], v[210:213], v[64:67]
	v_mfma_f32_16x16x32_bf16 v[132:135], v[148:151], v[164:167], v[132:135]
	v_mfma_f32_16x16x32_bf16 v[128:131], v[156:159], v[164:167], v[128:131]
	v_mfma_f32_16x16x32_bf16 v[116:119], v[148:151], v[188:191], v[116:119]
	v_mfma_f32_16x16x32_bf16 v[112:115], v[156:159], v[188:191], v[112:115]
	v_mfma_f32_16x16x32_bf16 v[100:103], v[148:151], v[196:199], v[100:103]
	v_mfma_f32_16x16x32_bf16 v[88:91], v[156:159], v[196:199], v[88:91]
	v_mfma_f32_16x16x32_bf16 v[68:71], v[148:151], v[214:217], v[68:71]
	v_mfma_f32_16x16x32_bf16 v[64:67], v[156:159], v[214:217], v[64:67]
	s_barrier
	s_add_i32 s60, s52, s3
	v_lshl_add_u64 v[200:201], s[6:7], 0, v[170:171]
	s_mov_b32 m0, s60
	ds_read_b128 v[160:163], v207 offset:16384
	ds_read_b128 v[164:167], v207 offset:17408
	ds_read_b128 v[184:187], v207 offset:18432
	ds_read_b128 v[188:191], v207 offset:19456
	ds_read_b128 v[192:195], v207 offset:20480
	ds_read_b128 v[196:199], v207 offset:21504
	ds_read_b128 v[210:213], v207 offset:22528
	ds_read_b128 v[214:217], v207 offset:23552
	global_load_lds_dwordx4 v[200:201], off
	s_add_i32 m0, s60, 0x2000
	s_add_u32 s60, s6, 0x40000
	v_lshl_add_u64 v[218:219], s[6:7], 0, v[174:175]
	s_addc_u32 s61, s7, 0
	s_add_i32 s62, s53, s3
	global_load_lds_dwordx4 v[218:219], off
	v_lshl_add_u64 v[222:223], s[60:61], 0, v[170:171]
	s_mov_b32 m0, s62
	v_lshl_add_u64 v[224:225], s[34:35], 0, v[172:173]
	global_load_lds_dwordx4 v[222:223], off
	v_lshl_add_u64 v[222:223], s[60:61], 0, v[174:175]
	s_add_i32 m0, s62, 0x2000
	s_nop 0
	global_load_lds_dwordx4 v[222:223], off
	v_lshl_add_u64 v[222:223], s[34:35], 0, v[168:169]
	s_mov_b32 m0, s31
	s_nop 0
	global_load_lds_dwordx4 v[222:223], off
	s_mov_b32 m0, s33
	s_nop 0
	global_load_lds_dwordx4 v[224:225], off
	s_waitcnt vmcnt(8)
	s_waitcnt lgkmcnt(0)
	s_barrier
; #define PG8_STAGE(bufoff, gbase, voff) do { _Pragma("unroll") for (int _i = 0; _i < 2; ++_i) \
;         __builtin_amdgcn_global_load_lds((const unsigned*)((const char*)(gbase) + (voff)[_i]), (PG8_LAS unsigned*)(lds + (bufoff) + ldsw + _i * 8192), 16, 0, 0); } while (0)
; #define PG8_LDA(dst, b, h) do { _Pragma("unroll") for (int m = 0; m < 4; ++m) _Pragma("unroll") for (int k = 0; k < 2; ++k) dst[m][k] = *(const PG8_LAS bf16x8*)(lds + PG8_SA(b, h) + aoff + m * 2048 + k * 1024); } while (0)
; #define PG8_LDB(dst, b, h) do { _Pragma("unroll") for (int n = 0; n < 2; ++n) _Pragma("unroll") for (int k = 0; k < 2; ++k) dst[n][k] = *(const PG8_LAS bf16x8*)(lds + PG8_SB(b, h) + boff + n * 2048 + k * 1024); } while (0)
; #define PG8_MMA(ai, bj, At, Bt) do { __builtin_amdgcn_s_setprio(1); _Pragma("unroll") for (int m = 0; m < 4; ++m) _Pragma("unroll") for (int n = 0; n < 2; ++n) _Pragma("unroll") for (int k = 0; k < 2; ++k) \
;         acc[ai][bj][m][n] = __builtin_amdgcn_mfma_f32_16x16x32_bf16(Bt[n][k], At[m][k], acc[ai][bj][m][n], 0, 0, 0); __builtin_amdgcn_s_setprio(0); } while (0)
; #define PG8_WAIT_V(n) asm volatile("s_waitcnt vmcnt(" #n ")" ::: "memory")
; #define PG8_WAIT_L(n) asm volatile("s_waitcnt lgkmcnt(" #n ")" ::: "memory")
; #define PG8_BAR __builtin_amdgcn_s_barrier()
; #define PG8_SCHED __builtin_amdgcn_sched_barrier(0)
; template <class Epi, class Sched, bool ALIGN_EPI = false, bool SP2 = false>
; __device__ __forceinline__ void gemm_phase(PG8_LAS unsigned char* lds, const Gemm g, const Sched& S, const Epi& E) {
;     ...
;             PG8_WAIT_V(8); PG8_WAIT_L(0); PG8_BAR; PG8_MMA(1, 0, At, B0); PG8_MMA(1, 1, At, B1); PG8_BAR; PG8_SCHED;
;             PG8_LDB(B0, 1, 0); PG8_LDB(B1, 1, 1); PG8_SCHED; PG8_LDA(At, 1, 0); PG8_STAGE(PG8_SA(0, 1), a2 + hstep, voffA);
;             PG8_WAIT_V(8); PG8_WAIT_L(0); PG8_BAR; PG8_MMA(0, 0, At, B0); PG8_MMA(0, 1, At, B1); PG8_BAR; PG8_SCHED;
	s_waitcnt lgkmcnt(0)
	v_mfma_f32_16x16x32_bf16 v[60:63], v[80:83], v[160:163], v[60:63]
	v_mfma_f32_16x16x32_bf16 v[56:59], v[92:95], v[160:163], v[56:59]
	v_mfma_f32_16x16x32_bf16 v[44:47], v[80:83], v[184:187], v[44:47]
	v_mfma_f32_16x16x32_bf16 v[40:43], v[92:95], v[184:187], v[40:43]
	v_mfma_f32_16x16x32_bf16 v[28:31], v[80:83], v[192:195], v[28:31]
	v_mfma_f32_16x16x32_bf16 v[24:27], v[92:95], v[192:195], v[24:27]
	v_mfma_f32_16x16x32_bf16 v[12:15], v[80:83], v[210:213], v[12:15]
	v_mfma_f32_16x16x32_bf16 v[8:11], v[92:95], v[210:213], v[8:11]
	v_mfma_f32_16x16x32_bf16 v[60:63], v[84:87], v[164:167], v[60:63]
	v_mfma_f32_16x16x32_bf16 v[56:59], v[96:99], v[164:167], v[56:59]
	v_mfma_f32_16x16x32_bf16 v[44:47], v[84:87], v[188:191], v[44:47]
	v_mfma_f32_16x16x32_bf16 v[40:43], v[96:99], v[188:191], v[40:43]
	v_mfma_f32_16x16x32_bf16 v[28:31], v[84:87], v[196:199], v[28:31]
	v_mfma_f32_16x16x32_bf16 v[24:27], v[96:99], v[196:199], v[24:27]
	v_mfma_f32_16x16x32_bf16 v[12:15], v[84:87], v[214:217], v[12:15]
	v_mfma_f32_16x16x32_bf16 v[8:11], v[96:99], v[214:217], v[8:11]
	v_mfma_f32_16x16x32_bf16 v[52:55], v[144:147], v[160:163], v[52:55]
	v_mfma_f32_16x16x32_bf16 v[48:51], v[152:155], v[160:163], v[48:51]
	v_mfma_f32_16x16x32_bf16 v[36:39], v[144:147], v[184:187], v[36:39]
	v_mfma_f32_16x16x32_bf16 v[32:35], v[152:155], v[184:187], v[32:35]
	v_mfma_f32_16x16x32_bf16 v[20:23], v[144:147], v[192:195], v[20:23]
	v_mfma_f32_16x16x32_bf16 v[16:19], v[152:155], v[192:195], v[16:19]
	v_mfma_f32_16x16x32_bf16 v[4:7], v[144:147], v[210:213], v[4:7]
	v_mfma_f32_16x16x32_bf16 v[0:3], v[152:155], v[210:213], v[0:3]
	v_mfma_f32_16x16x32_bf16 v[52:55], v[148:151], v[164:167], v[52:55]
	v_mfma_f32_16x16x32_bf16 v[48:51], v[156:159], v[164:167], v[48:51]
	v_mfma_f32_16x16x32_bf16 v[36:39], v[148:151], v[188:191], v[36:39]
	v_mfma_f32_16x16x32_bf16 v[32:35], v[156:159], v[188:191], v[32:35]
	v_mfma_f32_16x16x32_bf16 v[20:23], v[148:151], v[196:199], v[20:23]
	v_mfma_f32_16x16x32_bf16 v[16:19], v[156:159], v[196:199], v[16:19]
	v_mfma_f32_16x16x32_bf16 v[4:7], v[148:151], v[214:217], v[4:7]
	v_mfma_f32_16x16x32_bf16 v[0:3], v[156:159], v[214:217], v[0:3]
	s_barrier
	s_add_i32 s60, 0, 0x18000
	s_add_i32 s61, 0, 0x1c000
	v_add_u32_e32 v96, s60, v203
	v_add_u32_e32 v156, s61, v203
	ds_read_b128 v[80:83], v96
	ds_read_b128 v[84:87], v96 offset:1024
	ds_read_b128 v[92:95], v96 offset:2048
	ds_read_b128 v[96:99], v96 offset:3072
	ds_read_b128 v[144:147], v156
	ds_read_b128 v[148:151], v156 offset:1024
	ds_read_b128 v[152:155], v156 offset:2048
	ds_read_b128 v[156:159], v156 offset:3072
	s_add_u32 s34, s34, 0x40000
	s_addc_u32 s35, s35, 0
	s_mov_b32 m0, s36
	v_lshl_add_u64 v[226:227], s[34:35], 0, v[168:169]
	ds_read_b128 v[160:163], v207 offset:32768
	ds_read_b128 v[164:167], v207 offset:33792
	ds_read_b128 v[184:187], v207 offset:34816
	ds_read_b128 v[188:191], v207 offset:35840
	ds_read_b128 v[192:195], v207 offset:36864
	ds_read_b128 v[196:199], v207 offset:37888
	ds_read_b128 v[210:213], v207 offset:38912
	ds_read_b128 v[214:217], v207 offset:39936
	global_load_lds_dwordx4 v[226:227], off
	v_lshl_add_u64 v[226:227], s[34:35], 0, v[172:173]
	s_mov_b32 m0, s37
	s_nop 0
	global_load_lds_dwordx4 v[226:227], off
	s_waitcnt vmcnt(8)
	s_waitcnt lgkmcnt(0)
	s_barrier
	s_waitcnt lgkmcnt(0)
	v_mfma_f32_16x16x32_bf16 v[140:143], v[80:83], v[160:163], v[140:143]
	v_mfma_f32_16x16x32_bf16 v[136:139], v[92:95], v[160:163], v[136:139]
	v_mfma_f32_16x16x32_bf16 v[124:127], v[80:83], v[184:187], v[124:127]
	v_mfma_f32_16x16x32_bf16 v[120:123], v[92:95], v[184:187], v[120:123]
	v_mfma_f32_16x16x32_bf16 v[108:111], v[80:83], v[192:195], v[108:111]
	v_mfma_f32_16x16x32_bf16 v[104:107], v[92:95], v[192:195], v[104:107]
	v_mfma_f32_16x16x32_bf16 v[76:79], v[80:83], v[210:213], v[76:79]
	v_mfma_f32_16x16x32_bf16 v[72:75], v[92:95], v[210:213], v[72:75]
	v_mfma_f32_16x16x32_bf16 v[140:143], v[84:87], v[164:167], v[140:143]
	v_mfma_f32_16x16x32_bf16 v[136:139], v[96:99], v[164:167], v[136:139]
	v_mfma_f32_16x16x32_bf16 v[124:127], v[84:87], v[188:191], v[124:127]
	v_mfma_f32_16x16x32_bf16 v[120:123], v[96:99], v[188:191], v[120:123]
	v_mfma_f32_16x16x32_bf16 v[108:111], v[84:87], v[196:199], v[108:111]
	v_mfma_f32_16x16x32_bf16 v[104:107], v[96:99], v[196:199], v[104:107]
	v_mfma_f32_16x16x32_bf16 v[76:79], v[84:87], v[214:217], v[76:79]
	v_mfma_f32_16x16x32_bf16 v[72:75], v[96:99], v[214:217], v[72:75]
	v_mfma_f32_16x16x32_bf16 v[132:135], v[144:147], v[160:163], v[132:135]
	v_mfma_f32_16x16x32_bf16 v[128:131], v[152:155], v[160:163], v[128:131]
	v_mfma_f32_16x16x32_bf16 v[116:119], v[144:147], v[184:187], v[116:119]
	v_mfma_f32_16x16x32_bf16 v[112:115], v[152:155], v[184:187], v[112:115]
	v_mfma_f32_16x16x32_bf16 v[100:103], v[144:147], v[192:195], v[100:103]
	v_mfma_f32_16x16x32_bf16 v[88:91], v[152:155], v[192:195], v[88:91]
	v_mfma_f32_16x16x32_bf16 v[68:71], v[144:147], v[210:213], v[68:71]
	v_mfma_f32_16x16x32_bf16 v[64:67], v[152:155], v[210:213], v[64:67]
	v_mfma_f32_16x16x32_bf16 v[132:135], v[148:151], v[164:167], v[132:135]
	v_mfma_f32_16x16x32_bf16 v[128:131], v[156:159], v[164:167], v[128:131]
	v_mfma_f32_16x16x32_bf16 v[116:119], v[148:151], v[188:191], v[116:119]
	v_mfma_f32_16x16x32_bf16 v[112:115], v[156:159], v[188:191], v[112:115]
	v_mfma_f32_16x16x32_bf16 v[100:103], v[148:151], v[196:199], v[100:103]
	v_mfma_f32_16x16x32_bf16 v[88:91], v[156:159], v[196:199], v[88:91]
	v_mfma_f32_16x16x32_bf16 v[68:71], v[148:151], v[214:217], v[68:71]
	v_mfma_f32_16x16x32_bf16 v[64:67], v[156:159], v[214:217], v[64:67]
	s_barrier
; #define PG8_STAGE(bufoff, gbase, voff) do { _Pragma("unroll") for (int _i = 0; _i < 2; ++_i) \
;         __builtin_amdgcn_global_load_lds((const unsigned*)((const char*)(gbase) + (voff)[_i]), (PG8_LAS unsigned*)(lds + (bufoff) + ldsw + _i * 8192), 16, 0, 0); } while (0)
; #define PG8_LDA(dst, b, h) do { _Pragma("unroll") for (int m = 0; m < 4; ++m) _Pragma("unroll") for (int k = 0; k < 2; ++k) dst[m][k] = *(const PG8_LAS bf16x8*)(lds + PG8_SA(b, h) + aoff + m * 2048 + k * 1024); } while (0)
; #define PG8_MMA(ai, bj, At, Bt) do { __builtin_amdgcn_s_setprio(1); _Pragma("unroll") for (int m = 0; m < 4; ++m) _Pragma("unroll") for (int n = 0; n < 2; ++n) _Pragma("unroll") for (int k = 0; k < 2; ++k) \
;         acc[ai][bj][m][n] = __builtin_amdgcn_mfma_f32_16x16x32_bf16(Bt[n][k], At[m][k], acc[ai][bj][m][n], 0, 0, 0); __builtin_amdgcn_s_setprio(0); } while (0)
; #define PG8_WAIT_V(n) asm volatile("s_waitcnt vmcnt(" #n ")" ::: "memory")
; #define PG8_WAIT_L(n) asm volatile("s_waitcnt lgkmcnt(" #n ")" ::: "memory")
; #define PG8_BAR __builtin_amdgcn_s_barrier()
; #define PG8_SCHED __builtin_amdgcn_sched_barrier(0)
; template <class Epi, class Sched, bool ALIGN_EPI = false, bool SP2 = false>
; __device__ __forceinline__ void gemm_phase(PG8_LAS unsigned char* lds, const Gemm g, const Sched& S, const Epi& E) {
;     ...
;             PG8_LDA(At, 1, 1); PG8_STAGE(PG8_SB(1, 0), b3, voffB); PG8_STAGE(PG8_SB(1, 1), b3 + hstep, voffB); PG8_STAGE(PG8_SA(1, 0), a3, voffA);
;             PG8_WAIT_V(8); PG8_WAIT_L(0); PG8_BAR; PG8_MMA(1, 0, At, B0); PG8_MMA(1, 1, At, B1); PG8_BAR; PG8_SCHED;
;     ...
;         if constexpr (ALIGN_EPI) { if (wr == 0) PG8_BAR; }
;         if constexpr (!Epi::AFTER_DRAIN) { E(acc, cur, wr, wc, fr, fq); S.done(cur); }
;         if (!has_next) break;
	s_add_i32 s34, s60, s3
	v_lshl_add_u64 v[200:201], v[200:201], 0, s[16:17]
	s_mov_b32 m0, s34
	ds_read_b128 v[160:163], v207 offset:49152
	ds_read_b128 v[164:167], v207 offset:50176
	ds_read_b128 v[184:187], v207 offset:51200
	ds_read_b128 v[188:191], v207 offset:52224
	ds_read_b128 v[192:195], v207 offset:53248
	ds_read_b128 v[196:199], v207 offset:54272
	ds_read_b128 v[210:213], v207 offset:55296
	ds_read_b128 v[214:217], v207 offset:56320
	global_load_lds_dwordx4 v[200:201], off
	s_add_i32 m0, s34, 0x2000
	s_add_u32 s6, s6, 0x40080
	v_lshl_add_u64 v[200:201], v[218:219], 0, s[16:17]
	s_addc_u32 s7, s7, 0
	s_add_i32 s34, s61, s3
	global_load_lds_dwordx4 v[200:201], off
	v_lshl_add_u64 v[200:201], s[6:7], 0, v[170:171]
	s_mov_b32 m0, s34
	s_nop 0
	global_load_lds_dwordx4 v[200:201], off
	v_lshl_add_u64 v[200:201], s[6:7], 0, v[174:175]
	s_add_i32 m0, s34, 0x2000
	s_nop 0
	global_load_lds_dwordx4 v[200:201], off
	v_lshl_add_u64 v[200:201], v[222:223], 0, s[16:17]
	s_mov_b32 m0, s47
	s_nop 0
	global_load_lds_dwordx4 v[200:201], off
	v_lshl_add_u64 v[200:201], v[224:225], 0, s[16:17]
	s_mov_b32 m0, s48
	s_nop 0
	global_load_lds_dwordx4 v[200:201], off
	s_waitcnt vmcnt(8)
	s_waitcnt lgkmcnt(0)
	s_barrier
	s_waitcnt lgkmcnt(0)
	v_mfma_f32_16x16x32_bf16 v[60:63], v[80:83], v[160:163], v[60:63]
	v_mfma_f32_16x16x32_bf16 v[56:59], v[92:95], v[160:163], v[56:59]
	v_mfma_f32_16x16x32_bf16 v[44:47], v[80:83], v[184:187], v[44:47]
	v_mfma_f32_16x16x32_bf16 v[40:43], v[92:95], v[184:187], v[40:43]
	v_mfma_f32_16x16x32_bf16 v[28:31], v[80:83], v[192:195], v[28:31]
	v_mfma_f32_16x16x32_bf16 v[24:27], v[92:95], v[192:195], v[24:27]
	v_mfma_f32_16x16x32_bf16 v[12:15], v[80:83], v[210:213], v[12:15]
	v_mfma_f32_16x16x32_bf16 v[8:11], v[92:95], v[210:213], v[8:11]
	v_mfma_f32_16x16x32_bf16 v[60:63], v[84:87], v[164:167], v[60:63]
	v_mfma_f32_16x16x32_bf16 v[56:59], v[96:99], v[164:167], v[56:59]
	v_mfma_f32_16x16x32_bf16 v[44:47], v[84:87], v[188:191], v[44:47]
	v_mfma_f32_16x16x32_bf16 v[40:43], v[96:99], v[188:191], v[40:43]
	v_mfma_f32_16x16x32_bf16 v[28:31], v[84:87], v[196:199], v[28:31]
	v_mfma_f32_16x16x32_bf16 v[24:27], v[96:99], v[196:199], v[24:27]
	v_mfma_f32_16x16x32_bf16 v[12:15], v[84:87], v[214:217], v[12:15]
	v_mfma_f32_16x16x32_bf16 v[8:11], v[96:99], v[214:217], v[8:11]
	v_mfma_f32_16x16x32_bf16 v[52:55], v[144:147], v[160:163], v[52:55]
	v_mfma_f32_16x16x32_bf16 v[48:51], v[152:155], v[160:163], v[48:51]
	v_mfma_f32_16x16x32_bf16 v[36:39], v[144:147], v[184:187], v[36:39]
	v_mfma_f32_16x16x32_bf16 v[32:35], v[152:155], v[184:187], v[32:35]
	v_mfma_f32_16x16x32_bf16 v[20:23], v[144:147], v[192:195], v[20:23]
	v_mfma_f32_16x16x32_bf16 v[16:19], v[152:155], v[192:195], v[16:19]
	v_mfma_f32_16x16x32_bf16 v[4:7], v[144:147], v[210:213], v[4:7]
	v_mfma_f32_16x16x32_bf16 v[0:3], v[152:155], v[210:213], v[0:3]
	v_mfma_f32_16x16x32_bf16 v[52:55], v[148:151], v[164:167], v[52:55]
	v_mfma_f32_16x16x32_bf16 v[48:51], v[156:159], v[164:167], v[48:51]
	v_mfma_f32_16x16x32_bf16 v[36:39], v[148:151], v[188:191], v[36:39]
	v_mfma_f32_16x16x32_bf16 v[32:35], v[156:159], v[188:191], v[32:35]
	v_mfma_f32_16x16x32_bf16 v[20:23], v[148:151], v[196:199], v[20:23]
	v_mfma_f32_16x16x32_bf16 v[16:19], v[156:159], v[196:199], v[16:19]
	v_mfma_f32_16x16x32_bf16 v[4:7], v[148:151], v[214:217], v[4:7]
	v_mfma_f32_16x16x32_bf16 v[0:3], v[156:159], v[214:217], v[0:3]
	s_barrier
	s_add_i32 s59, s59, 2
	s_add_u32 s8, s8, 0x100
	s_addc_u32 s9, s9, 0
	s_add_u32 s57, s57, 0x100
	s_addc_u32 s58, s58, 0
	s_cmp_gt_u32 s59, 13
	s_cbranch_scc0 .LBB0_987
	s_and_b64 vcc, exec, s[18:19]
	s_cbranch_vccz .LBB0_990
	s_barrier

; #define PG8_STAGE(bufoff, gbase, voff) do { _Pragma("unroll") for (int _i = 0; _i < 2; ++_i) \
;         __builtin_amdgcn_global_load_lds((const unsigned*)((const char*)(gbase) + (voff)[_i]), (PG8_LAS unsigned*)(lds + (bufoff) + ldsw + _i * 8192), 16, 0, 0); } while (0)
; #define PG8_LDA(dst, b, h) do { _Pragma("unroll") for (int m = 0; m < 4; ++m) _Pragma("unroll") for (int k = 0; k < 2; ++k) dst[m][k] = *(const PG8_LAS bf16x8*)(lds + PG8_SA(b, h) + aoff + m * 2048 + k * 1024); } while (0)
; #define PG8_LDB(dst, b, h) do { _Pragma("unroll") for (int n = 0; n < 2; ++n) _Pragma("unroll") for (int k = 0; k < 2; ++k) dst[n][k] = *(const PG8_LAS bf16x8*)(lds + PG8_SB(b, h) + boff + n * 2048 + k * 1024); } while (0)
; #define PG8_WAIT_V(n) asm volatile("s_waitcnt vmcnt(" #n ")" ::: "memory")
; #define PG8_WAIT_L(n) asm volatile("s_waitcnt lgkmcnt(" #n ")" ::: "memory")
; #define PG8_BAR __builtin_amdgcn_s_barrier()
; #define PG8_SCHED __builtin_amdgcn_sched_barrier(0)
; template <class Epi, class Sched, bool ALIGN_EPI = false, bool SP2 = false>
; __device__ __forceinline__ void gemm_phase(PG8_LAS unsigned char* lds, const Gemm g, const Sched& S, const Epi& E) {
;     ...
;         const bool has_next = S.next(ui + 1, nxt);
;         const char* nA = has_next ? (const char*)g.A + (size_t)nxt.pm * tstep : cA; const char* nB = has_next ? (const char*)g.Bt + (size_t)nxt.pn * tstep : cB;
;         for (int t = 0; t < nt; t += 2) {
;             const bool last = (t == nt - 2);
;             const char* a1 = cA + (size_t)(t + 1) * kstep;
;             const char* a2 = last ? nA : cA + (size_t)(t + 2) * kstep; const char* b2 = last ? nB : cB + (size_t)(t + 2) * kstep;
;             const char* a3 = a2 + kstep; const char* b3 = b2 + kstep;
;             if (last && has_next) S.a_ready(nxt);
;             if constexpr (SP2) {
;             PG8_LDB(B0, 0, 0); PG8_LDB(B1, 0, 1); PG8_SCHED; PG8_LDA(At, 0, 0); PG8_STAGE(PG8_SA(1, 1), a1 + hstep, voffA);
;             PG8_WAIT_V(8); PG8_WAIT_L(0); PG8_BAR; PG8_MMA(0, 0, At, B0); PG8_MMA(0, 1, At, B1); PG8_BAR; PG8_SCHED;
;             PG8_LDA(At, 0, 1); PG8_STAGE(PG8_SB(0, 0), b2, voffB); PG8_STAGE(PG8_SB(0, 1), b2 + hstep, voffB); PG8_STAGE(PG8_SA(0, 0), a2, voffA);
;             PG8_WAIT_V(8); PG8_WAIT_L(0); PG8_BAR; PG8_MMA(1, 0, At, B0); PG8_MMA(1, 1, At, B1); PG8_BAR; PG8_SCHED;
.LBB0_1082:
	ds_read_b128 v[154:157], v149
	ds_read_b128 v[158:161], v149 offset:1024
	ds_read_b128 v[162:165], v149 offset:2048
	ds_read_b128 v[166:169], v149 offset:3072
	ds_read_b128 v[170:173], v150
	ds_read_b128 v[174:177], v150 offset:1024
	ds_read_b128 v[178:181], v150 offset:2048
	ds_read_b128 v[182:185], v150 offset:3072
	s_add_u32 s6, s24, 0xfffc0080
	s_addc_u32 s7, s25, -1
	s_cmp_eq_u32 s55, 12
	s_cselect_b32 s27, s17, s7
	s_cselect_b32 s26, s51, s6
	s_cselect_b32 s7, s15, s54
	s_cselect_b32 s6, s52, s53
	v_lshl_add_u64 v[144:145], s[24:25], 0, v[136:137]
	s_add_i32 m0, s23, 0xc000
	ds_read_b128 v[186:189], v151
	ds_read_b128 v[190:193], v151 offset:1024
	ds_read_b128 v[194:197], v151 offset:2048
	ds_read_b128 v[198:201], v151 offset:3072
	ds_read_b128 v[202:205], v151 offset:4096
	ds_read_b128 v[206:209], v151 offset:5120
	ds_read_b128 v[210:213], v151 offset:6144
	ds_read_b128 v[214:217], v151 offset:7168
	global_load_lds_dwordx4 v[144:145], off
	v_lshl_add_u64 v[144:145], s[24:25], 0, v[138:139]
	s_add_i32 m0, s23, 0xe000
	s_nop 0
	global_load_lds_dwordx4 v[144:145], off
	s_waitcnt vmcnt(8)
	s_waitcnt lgkmcnt(0)
	s_barrier
	s_waitcnt lgkmcnt(0)
	v_mfma_f32_16x16x32_bf16 v[116:119], v[154:157], v[186:189], v[116:119]
	v_mfma_f32_16x16x32_bf16 v[112:115], v[162:165], v[186:189], v[112:115]
	v_mfma_f32_16x16x32_bf16 v[100:103], v[154:157], v[194:197], v[100:103]
	v_mfma_f32_16x16x32_bf16 v[96:99], v[162:165], v[194:197], v[96:99]
	v_mfma_f32_16x16x32_bf16 v[84:87], v[154:157], v[202:205], v[84:87]
	v_mfma_f32_16x16x32_bf16 v[80:83], v[162:165], v[202:205], v[80:83]
	v_mfma_f32_16x16x32_bf16 v[68:71], v[154:157], v[210:213], v[68:71]
	v_mfma_f32_16x16x32_bf16 v[64:67], v[162:165], v[210:213], v[64:67]
	v_mfma_f32_16x16x32_bf16 v[116:119], v[158:161], v[190:193], v[116:119]
	v_mfma_f32_16x16x32_bf16 v[112:115], v[166:169], v[190:193], v[112:115]
	v_mfma_f32_16x16x32_bf16 v[100:103], v[158:161], v[198:201], v[100:103]
	v_mfma_f32_16x16x32_bf16 v[96:99], v[166:169], v[198:201], v[96:99]
	v_mfma_f32_16x16x32_bf16 v[84:87], v[158:161], v[206:209], v[84:87]
	v_mfma_f32_16x16x32_bf16 v[80:83], v[166:169], v[206:209], v[80:83]
	v_mfma_f32_16x16x32_bf16 v[68:71], v[158:161], v[214:217], v[68:71]
	v_mfma_f32_16x16x32_bf16 v[64:67], v[166:169], v[214:217], v[64:67]
	v_mfma_f32_16x16x32_bf16 v[124:127], v[170:173], v[186:189], v[124:127]
	v_mfma_f32_16x16x32_bf16 v[120:123], v[178:181], v[186:189], v[120:123]
	v_mfma_f32_16x16x32_bf16 v[108:111], v[170:173], v[194:197], v[108:111]
	v_mfma_f32_16x16x32_bf16 v[104:107], v[178:181], v[194:197], v[104:107]
	v_mfma_f32_16x16x32_bf16 v[92:95], v[170:173], v[202:205], v[92:95]
	v_mfma_f32_16x16x32_bf16 v[88:91], v[178:181], v[202:205], v[88:91]
	v_mfma_f32_16x16x32_bf16 v[76:79], v[170:173], v[210:213], v[76:79]
	v_mfma_f32_16x16x32_bf16 v[72:75], v[178:181], v[210:213], v[72:75]
	v_mfma_f32_16x16x32_bf16 v[124:127], v[174:177], v[190:193], v[124:127]
	v_mfma_f32_16x16x32_bf16 v[120:123], v[182:185], v[190:193], v[120:123]
	v_mfma_f32_16x16x32_bf16 v[108:111], v[174:177], v[198:201], v[108:111]
	v_mfma_f32_16x16x32_bf16 v[104:107], v[182:185], v[198:201], v[104:107]
	v_mfma_f32_16x16x32_bf16 v[92:95], v[174:177], v[206:209], v[92:95]
	v_mfma_f32_16x16x32_bf16 v[88:91], v[182:185], v[206:209], v[88:91]
	v_mfma_f32_16x16x32_bf16 v[76:79], v[174:177], v[214:217], v[76:79]
	v_mfma_f32_16x16x32_bf16 v[72:75], v[182:185], v[214:217], v[72:75]
	s_barrier
	s_add_i32 s56, s47, s29
	v_lshl_add_u64 v[144:145], s[6:7], 0, v[132:133]
	s_mov_b32 m0, s56
	ds_read_b128 v[186:189], v151 offset:16384
	ds_read_b128 v[190:193], v151 offset:17408
	ds_read_b128 v[194:197], v151 offset:18432
	ds_read_b128 v[198:201], v151 offset:19456
	ds_read_b128 v[202:205], v151 offset:20480
	ds_read_b128 v[206:209], v151 offset:21504
	ds_read_b128 v[210:213], v151 offset:22528
	ds_read_b128 v[214:217], v151 offset:23552
	global_load_lds_dwordx4 v[144:145], off
	s_add_i32 m0, s56, 0x2000
	s_add_u32 s56, s6, 0x40000
	v_lshl_add_u64 v[218:219], s[6:7], 0, v[128:129]
	s_addc_u32 s57, s7, 0
	s_add_i32 s58, s48, s29
	global_load_lds_dwordx4 v[218:219], off
	v_lshl_add_u64 v[222:223], s[56:57], 0, v[132:133]
	s_mov_b32 m0, s58
	v_lshl_add_u64 v[224:225], s[26:27], 0, v[130:131]
	global_load_lds_dwordx4 v[222:223], off
	v_lshl_add_u64 v[222:223], s[56:57], 0, v[128:129]
	s_add_i32 m0, s58, 0x2000
	s_nop 0
	global_load_lds_dwordx4 v[222:223], off
	v_lshl_add_u64 v[222:223], s[26:27], 0, v[134:135]
	s_mov_b32 m0, s23
	s_nop 0
	global_load_lds_dwordx4 v[222:223], off
	s_mov_b32 m0, s33
	s_nop 0
	global_load_lds_dwordx4 v[224:225], off
	s_waitcnt vmcnt(8)
	s_waitcnt lgkmcnt(0)
	s_barrier
; #define PG8_STAGE(bufoff, gbase, voff) do { _Pragma("unroll") for (int _i = 0; _i < 2; ++_i) \
;         __builtin_amdgcn_global_load_lds((const unsigned*)((const char*)(gbase) + (voff)[_i]), (PG8_LAS unsigned*)(lds + (bufoff) + ldsw + _i * 8192), 16, 0, 0); } while (0)
; #define PG8_LDA(dst, b, h) do { _Pragma("unroll") for (int m = 0; m < 4; ++m) _Pragma("unroll") for (int k = 0; k < 2; ++k) dst[m][k] = *(const PG8_LAS bf16x8*)(lds + PG8_SA(b, h) + aoff + m * 2048 + k * 1024); } while (0)
; #define PG8_LDB(dst, b, h) do { _Pragma("unroll") for (int n = 0; n < 2; ++n) _Pragma("unroll") for (int k = 0; k < 2; ++k) dst[n][k] = *(const PG8_LAS bf16x8*)(lds + PG8_SB(b, h) + boff + n * 2048 + k * 1024); } while (0)
; #define PG8_MMA(ai, bj, At, Bt) do { __builtin_amdgcn_s_setprio(1); _Pragma("unroll") for (int m = 0; m < 4; ++m) _Pragma("unroll") for (int n = 0; n < 2; ++n) _Pragma("unroll") for (int k = 0; k < 2; ++k) \
;         acc[ai][bj][m][n] = __builtin_amdgcn_mfma_f32_16x16x32_bf16(Bt[n][k], At[m][k], acc[ai][bj][m][n], 0, 0, 0); __builtin_amdgcn_s_setprio(0); } while (0)
; #define PG8_WAIT_V(n) asm volatile("s_waitcnt vmcnt(" #n ")" ::: "memory")
; #define PG8_WAIT_L(n) asm volatile("s_waitcnt lgkmcnt(" #n ")" ::: "memory")
; #define PG8_BAR __builtin_amdgcn_s_barrier()
; #define PG8_SCHED __builtin_amdgcn_sched_barrier(0)
; template <class Epi, class Sched, bool ALIGN_EPI = false, bool SP2 = false>
; __device__ __forceinline__ void gemm_phase(PG8_LAS unsigned char* lds, const Gemm g, const Sched& S, const Epi& E) {
;     ...
;             PG8_WAIT_V(8); PG8_WAIT_L(0); PG8_BAR; PG8_MMA(1, 0, At, B0); PG8_MMA(1, 1, At, B1); PG8_BAR; PG8_SCHED;
;             PG8_LDB(B0, 1, 0); PG8_LDB(B1, 1, 1); PG8_SCHED; PG8_LDA(At, 1, 0); PG8_STAGE(PG8_SA(0, 1), a2 + hstep, voffA);
;             PG8_WAIT_V(8); PG8_WAIT_L(0); PG8_BAR; PG8_MMA(0, 0, At, B0); PG8_MMA(0, 1, At, B1); PG8_BAR; PG8_SCHED;
	s_waitcnt lgkmcnt(0)
	v_mfma_f32_16x16x32_bf16 v[52:55], v[154:157], v[186:189], v[52:55]
	v_mfma_f32_16x16x32_bf16 v[48:51], v[162:165], v[186:189], v[48:51]
	v_mfma_f32_16x16x32_bf16 v[36:39], v[154:157], v[194:197], v[36:39]
	v_mfma_f32_16x16x32_bf16 v[32:35], v[162:165], v[194:197], v[32:35]
	v_mfma_f32_16x16x32_bf16 v[20:23], v[154:157], v[202:205], v[20:23]
	v_mfma_f32_16x16x32_bf16 v[16:19], v[162:165], v[202:205], v[16:19]
	v_mfma_f32_16x16x32_bf16 v[4:7], v[154:157], v[210:213], v[4:7]
	v_mfma_f32_16x16x32_bf16 v[0:3], v[162:165], v[210:213], v[0:3]
	v_mfma_f32_16x16x32_bf16 v[52:55], v[158:161], v[190:193], v[52:55]
	v_mfma_f32_16x16x32_bf16 v[48:51], v[166:169], v[190:193], v[48:51]
	v_mfma_f32_16x16x32_bf16 v[36:39], v[158:161], v[198:201], v[36:39]
	v_mfma_f32_16x16x32_bf16 v[32:35], v[166:169], v[198:201], v[32:35]
	v_mfma_f32_16x16x32_bf16 v[20:23], v[158:161], v[206:209], v[20:23]
	v_mfma_f32_16x16x32_bf16 v[16:19], v[166:169], v[206:209], v[16:19]
	v_mfma_f32_16x16x32_bf16 v[4:7], v[158:161], v[214:217], v[4:7]
	v_mfma_f32_16x16x32_bf16 v[0:3], v[166:169], v[214:217], v[0:3]
	v_mfma_f32_16x16x32_bf16 v[60:63], v[170:173], v[186:189], v[60:63]
	v_mfma_f32_16x16x32_bf16 v[56:59], v[178:181], v[186:189], v[56:59]
	v_mfma_f32_16x16x32_bf16 v[44:47], v[170:173], v[194:197], v[44:47]
	v_mfma_f32_16x16x32_bf16 v[40:43], v[178:181], v[194:197], v[40:43]
	v_mfma_f32_16x16x32_bf16 v[28:31], v[170:173], v[202:205], v[28:31]
	v_mfma_f32_16x16x32_bf16 v[24:27], v[178:181], v[202:205], v[24:27]
	v_mfma_f32_16x16x32_bf16 v[12:15], v[170:173], v[210:213], v[12:15]
	v_mfma_f32_16x16x32_bf16 v[8:11], v[178:181], v[210:213], v[8:11]
	v_mfma_f32_16x16x32_bf16 v[60:63], v[174:177], v[190:193], v[60:63]
	v_mfma_f32_16x16x32_bf16 v[56:59], v[182:185], v[190:193], v[56:59]
	v_mfma_f32_16x16x32_bf16 v[44:47], v[174:177], v[198:201], v[44:47]
	v_mfma_f32_16x16x32_bf16 v[40:43], v[182:185], v[198:201], v[40:43]
	v_mfma_f32_16x16x32_bf16 v[28:31], v[174:177], v[206:209], v[28:31]
	v_mfma_f32_16x16x32_bf16 v[24:27], v[182:185], v[206:209], v[24:27]
	v_mfma_f32_16x16x32_bf16 v[12:15], v[174:177], v[214:217], v[12:15]
	v_mfma_f32_16x16x32_bf16 v[8:11], v[182:185], v[214:217], v[8:11]
	s_barrier
	s_add_i32 s56, 0, 0x18000
	v_add_u32_e32 v153, s56, v147
	s_add_i32 s57, 0, 0x1c000
	ds_read_b128 v[154:157], v153
	ds_read_b128 v[158:161], v153 offset:1024
	ds_read_b128 v[162:165], v153 offset:2048
	ds_read_b128 v[166:169], v153 offset:3072
	v_add_u32_e32 v153, s57, v147
	ds_read_b128 v[170:173], v153
	ds_read_b128 v[174:177], v153 offset:1024
	ds_read_b128 v[178:181], v153 offset:2048
	ds_read_b128 v[182:185], v153 offset:3072
	s_add_u32 s26, s26, 0x40000
	s_addc_u32 s27, s27, 0
	s_mov_b32 m0, s34
	v_lshl_add_u64 v[226:227], s[26:27], 0, v[134:135]
	ds_read_b128 v[186:189], v151 offset:32768
	ds_read_b128 v[190:193], v151 offset:33792
	ds_read_b128 v[194:197], v151 offset:34816
	ds_read_b128 v[198:201], v151 offset:35840
	ds_read_b128 v[202:205], v151 offset:36864
	ds_read_b128 v[206:209], v151 offset:37888
	ds_read_b128 v[210:213], v151 offset:38912
	ds_read_b128 v[214:217], v151 offset:39936
	global_load_lds_dwordx4 v[226:227], off
	v_lshl_add_u64 v[226:227], s[26:27], 0, v[130:131]
	s_mov_b32 m0, s35
	s_nop 0
	global_load_lds_dwordx4 v[226:227], off
	s_waitcnt vmcnt(8)
	s_waitcnt lgkmcnt(0)
	s_barrier
	s_waitcnt lgkmcnt(0)
	v_mfma_f32_16x16x32_bf16 v[116:119], v[154:157], v[186:189], v[116:119]
	v_mfma_f32_16x16x32_bf16 v[112:115], v[162:165], v[186:189], v[112:115]
	v_mfma_f32_16x16x32_bf16 v[100:103], v[154:157], v[194:197], v[100:103]
	v_mfma_f32_16x16x32_bf16 v[96:99], v[162:165], v[194:197], v[96:99]
	v_mfma_f32_16x16x32_bf16 v[84:87], v[154:157], v[202:205], v[84:87]
	v_mfma_f32_16x16x32_bf16 v[80:83], v[162:165], v[202:205], v[80:83]
	v_mfma_f32_16x16x32_bf16 v[68:71], v[154:157], v[210:213], v[68:71]
	v_mfma_f32_16x16x32_bf16 v[64:67], v[162:165], v[210:213], v[64:67]
	v_mfma_f32_16x16x32_bf16 v[116:119], v[158:161], v[190:193], v[116:119]
	v_mfma_f32_16x16x32_bf16 v[112:115], v[166:169], v[190:193], v[112:115]
	v_mfma_f32_16x16x32_bf16 v[100:103], v[158:161], v[198:201], v[100:103]
	v_mfma_f32_16x16x32_bf16 v[96:99], v[166:169], v[198:201], v[96:99]
	v_mfma_f32_16x16x32_bf16 v[84:87], v[158:161], v[206:209], v[84:87]
	v_mfma_f32_16x16x32_bf16 v[80:83], v[166:169], v[206:209], v[80:83]
	v_mfma_f32_16x16x32_bf16 v[68:71], v[158:161], v[214:217], v[68:71]
	v_mfma_f32_16x16x32_bf16 v[64:67], v[166:169], v[214:217], v[64:67]
	v_mfma_f32_16x16x32_bf16 v[124:127], v[170:173], v[186:189], v[124:127]
	v_mfma_f32_16x16x32_bf16 v[120:123], v[178:181], v[186:189], v[120:123]
	v_mfma_f32_16x16x32_bf16 v[108:111], v[170:173], v[194:197], v[108:111]
	v_mfma_f32_16x16x32_bf16 v[104:107], v[178:181], v[194:197], v[104:107]
	v_mfma_f32_16x16x32_bf16 v[92:95], v[170:173], v[202:205], v[92:95]
	v_mfma_f32_16x16x32_bf16 v[88:91], v[178:181], v[202:205], v[88:91]
	v_mfma_f32_16x16x32_bf16 v[76:79], v[170:173], v[210:213], v[76:79]
	v_mfma_f32_16x16x32_bf16 v[72:75], v[178:181], v[210:213], v[72:75]
	v_mfma_f32_16x16x32_bf16 v[124:127], v[174:177], v[190:193], v[124:127]
	v_mfma_f32_16x16x32_bf16 v[120:123], v[182:185], v[190:193], v[120:123]
	v_mfma_f32_16x16x32_bf16 v[108:111], v[174:177], v[198:201], v[108:111]
	v_mfma_f32_16x16x32_bf16 v[104:107], v[182:185], v[198:201], v[104:107]
	v_mfma_f32_16x16x32_bf16 v[92:95], v[174:177], v[206:209], v[92:95]
	v_mfma_f32_16x16x32_bf16 v[88:91], v[182:185], v[206:209], v[88:91]
	v_mfma_f32_16x16x32_bf16 v[76:79], v[174:177], v[214:217], v[76:79]
	v_mfma_f32_16x16x32_bf16 v[72:75], v[182:185], v[214:217], v[72:75]
	s_barrier
; #define PG8_STAGE(bufoff, gbase, voff) do { _Pragma("unroll") for (int _i = 0; _i < 2; ++_i) \
;         __builtin_amdgcn_global_load_lds((const unsigned*)((const char*)(gbase) + (voff)[_i]), (PG8_LAS unsigned*)(lds + (bufoff) + ldsw + _i * 8192), 16, 0, 0); } while (0)
; #define PG8_LDA(dst, b, h) do { _Pragma("unroll") for (int m = 0; m < 4; ++m) _Pragma("unroll") for (int k = 0; k < 2; ++k) dst[m][k] = *(const PG8_LAS bf16x8*)(lds + PG8_SA(b, h) + aoff + m * 2048 + k * 1024); } while (0)
; #define PG8_MMA(ai, bj, At, Bt) do { __builtin_amdgcn_s_setprio(1); _Pragma("unroll") for (int m = 0; m < 4; ++m) _Pragma("unroll") for (int n = 0; n < 2; ++n) _Pragma("unroll") for (int k = 0; k < 2; ++k) \
;         acc[ai][bj][m][n] = __builtin_amdgcn_mfma_f32_16x16x32_bf16(Bt[n][k], At[m][k], acc[ai][bj][m][n], 0, 0, 0); __builtin_amdgcn_s_setprio(0); } while (0)
; #define PG8_WAIT_V(n) asm volatile("s_waitcnt vmcnt(" #n ")" ::: "memory")
; #define PG8_WAIT_L(n) asm volatile("s_waitcnt lgkmcnt(" #n ")" ::: "memory")
; #define PG8_BAR __builtin_amdgcn_s_barrier()
; #define PG8_SCHED __builtin_amdgcn_sched_barrier(0)
; template <class Epi, class Sched, bool ALIGN_EPI = false, bool SP2 = false>
; __device__ __forceinline__ void gemm_phase(PG8_LAS unsigned char* lds, const Gemm g, const Sched& S, const Epi& E) {
;     ...
;             PG8_LDA(At, 1, 1); PG8_STAGE(PG8_SB(1, 0), b3, voffB); PG8_STAGE(PG8_SB(1, 1), b3 + hstep, voffB); PG8_STAGE(PG8_SA(1, 0), a3, voffA);
;             PG8_WAIT_V(8); PG8_WAIT_L(0); PG8_BAR; PG8_MMA(1, 0, At, B0); PG8_MMA(1, 1, At, B1); PG8_BAR; PG8_SCHED;
;     ...
;         if constexpr (ALIGN_EPI) { if (wr == 0) PG8_BAR; }
;         if constexpr (!Epi::AFTER_DRAIN) { E(acc, cur, wr, wc, fr, fq); S.done(cur); }
;         if (!has_next) break;
	s_add_i32 s26, s56, s29
	v_lshl_add_u64 v[144:145], v[144:145], 0, s[10:11]
	s_mov_b32 m0, s26
	ds_read_b128 v[186:189], v151 offset:49152
	ds_read_b128 v[190:193], v151 offset:50176
	ds_read_b128 v[194:197], v151 offset:51200
	ds_read_b128 v[198:201], v151 offset:52224
	ds_read_b128 v[202:205], v151 offset:53248
	ds_read_b128 v[206:209], v151 offset:54272
	ds_read_b128 v[210:213], v151 offset:55296
	ds_read_b128 v[214:217], v151 offset:56320
	global_load_lds_dwordx4 v[144:145], off
	s_add_i32 m0, s26, 0x2000
	s_add_u32 s6, s6, 0x40080
	v_lshl_add_u64 v[144:145], v[218:219], 0, s[10:11]
	s_addc_u32 s7, s7, 0
	s_add_i32 s26, s57, s29
	global_load_lds_dwordx4 v[144:145], off
	v_lshl_add_u64 v[144:145], s[6:7], 0, v[132:133]
	s_mov_b32 m0, s26
	s_nop 0
	global_load_lds_dwordx4 v[144:145], off
	v_lshl_add_u64 v[144:145], s[6:7], 0, v[128:129]
	s_add_i32 m0, s26, 0x2000
	s_nop 0
	global_load_lds_dwordx4 v[144:145], off
	v_lshl_add_u64 v[144:145], v[222:223], 0, s[10:11]
	s_mov_b32 m0, s37
	s_nop 0
	global_load_lds_dwordx4 v[144:145], off
	v_lshl_add_u64 v[144:145], v[224:225], 0, s[10:11]
	s_mov_b32 m0, s44
	s_nop 0
	global_load_lds_dwordx4 v[144:145], off
	s_waitcnt vmcnt(8)
	s_waitcnt lgkmcnt(0)
	s_barrier
	s_waitcnt lgkmcnt(0)
	v_mfma_f32_16x16x32_bf16 v[52:55], v[154:157], v[186:189], v[52:55]
	v_mfma_f32_16x16x32_bf16 v[48:51], v[162:165], v[186:189], v[48:51]
	v_mfma_f32_16x16x32_bf16 v[36:39], v[154:157], v[194:197], v[36:39]
	v_mfma_f32_16x16x32_bf16 v[32:35], v[162:165], v[194:197], v[32:35]
	v_mfma_f32_16x16x32_bf16 v[20:23], v[154:157], v[202:205], v[20:23]
	v_mfma_f32_16x16x32_bf16 v[16:19], v[162:165], v[202:205], v[16:19]
	v_mfma_f32_16x16x32_bf16 v[4:7], v[154:157], v[210:213], v[4:7]
	v_mfma_f32_16x16x32_bf16 v[0:3], v[162:165], v[210:213], v[0:3]
	v_mfma_f32_16x16x32_bf16 v[52:55], v[158:161], v[190:193], v[52:55]
	v_mfma_f32_16x16x32_bf16 v[48:51], v[166:169], v[190:193], v[48:51]
	v_mfma_f32_16x16x32_bf16 v[36:39], v[158:161], v[198:201], v[36:39]
	v_mfma_f32_16x16x32_bf16 v[32:35], v[166:169], v[198:201], v[32:35]
	v_mfma_f32_16x16x32_bf16 v[20:23], v[158:161], v[206:209], v[20:23]
	v_mfma_f32_16x16x32_bf16 v[16:19], v[166:169], v[206:209], v[16:19]
	v_mfma_f32_16x16x32_bf16 v[4:7], v[158:161], v[214:217], v[4:7]
	v_mfma_f32_16x16x32_bf16 v[0:3], v[166:169], v[214:217], v[0:3]
	v_mfma_f32_16x16x32_bf16 v[60:63], v[170:173], v[186:189], v[60:63]
	v_mfma_f32_16x16x32_bf16 v[56:59], v[178:181], v[186:189], v[56:59]
	v_mfma_f32_16x16x32_bf16 v[44:47], v[170:173], v[194:197], v[44:47]
	v_mfma_f32_16x16x32_bf16 v[40:43], v[178:181], v[194:197], v[40:43]
	v_mfma_f32_16x16x32_bf16 v[28:31], v[170:173], v[202:205], v[28:31]
	v_mfma_f32_16x16x32_bf16 v[24:27], v[178:181], v[202:205], v[24:27]
	v_mfma_f32_16x16x32_bf16 v[12:15], v[170:173], v[210:213], v[12:15]
	v_mfma_f32_16x16x32_bf16 v[8:11], v[178:181], v[210:213], v[8:11]
	v_mfma_f32_16x16x32_bf16 v[60:63], v[174:177], v[190:193], v[60:63]
	v_mfma_f32_16x16x32_bf16 v[56:59], v[182:185], v[190:193], v[56:59]
	v_mfma_f32_16x16x32_bf16 v[44:47], v[174:177], v[198:201], v[44:47]
	v_mfma_f32_16x16x32_bf16 v[40:43], v[182:185], v[198:201], v[40:43]
	v_mfma_f32_16x16x32_bf16 v[28:31], v[174:177], v[206:209], v[28:31]
	v_mfma_f32_16x16x32_bf16 v[24:27], v[182:185], v[206:209], v[24:27]
	v_mfma_f32_16x16x32_bf16 v[12:15], v[174:177], v[214:217], v[12:15]
	v_mfma_f32_16x16x32_bf16 v[8:11], v[182:185], v[214:217], v[8:11]
	s_barrier
	s_add_i32 s55, s55, 2
	s_add_u32 s24, s24, 0x100
	s_addc_u32 s25, s25, 0
	s_add_u32 s53, s53, 0x100
	s_addc_u32 s54, s54, 0
	s_cmp_gt_u32 s55, 13
	s_cbranch_scc0 .LBB0_1082
	s_and_b64 vcc, exec, s[12:13]
	s_cbranch_vccz .LBB0_1085
	s_barrier

; #define PG8_STAGE(bufoff, gbase, voff) do { _Pragma("unroll") for (int _i = 0; _i < 2; ++_i) \
;         __builtin_amdgcn_global_load_lds((const unsigned*)((const char*)(gbase) + (voff)[_i]), (PG8_LAS unsigned*)(lds + (bufoff) + ldsw + _i * 8192), 16, 0, 0); } while (0)
; #define PG8_LDA(dst, b, h) do { _Pragma("unroll") for (int m = 0; m < 4; ++m) _Pragma("unroll") for (int k = 0; k < 2; ++k) dst[m][k] = *(const PG8_LAS bf16x8*)(lds + PG8_SA(b, h) + aoff + m * 2048 + k * 1024); } while (0)
; #define PG8_LDB(dst, b, h) do { _Pragma("unroll") for (int n = 0; n < 2; ++n) _Pragma("unroll") for (int k = 0; k < 2; ++k) dst[n][k] = *(const PG8_LAS bf16x8*)(lds + PG8_SB(b, h) + boff + n * 2048 + k * 1024); } while (0)
; #define PG8_WAIT_V(n) asm volatile("s_waitcnt vmcnt(" #n ")" ::: "memory")
; #define PG8_WAIT_L(n) asm volatile("s_waitcnt lgkmcnt(" #n ")" ::: "memory")
; #define PG8_BAR __builtin_amdgcn_s_barrier()
; #define PG8_SCHED __builtin_amdgcn_sched_barrier(0)
; template <class Epi, class Sched, bool ALIGN_EPI = false, bool SP2 = false>
; __device__ __forceinline__ void gemm_phase(PG8_LAS unsigned char* lds, const Gemm g, const Sched& S, const Epi& E) {
;     ...
;         const bool has_next = S.next(ui + 1, nxt);
;         const char* nA = has_next ? (const char*)g.A + (size_t)nxt.pm * tstep : cA; const char* nB = has_next ? (const char*)g.Bt + (size_t)nxt.pn * tstep : cB;
;         for (int t = 0; t < nt; t += 2) {
;             const bool last = (t == nt - 2);
;             const char* a1 = cA + (size_t)(t + 1) * kstep;
;             const char* a2 = last ? nA : cA + (size_t)(t + 2) * kstep; const char* b2 = last ? nB : cB + (size_t)(t + 2) * kstep;
;             const char* a3 = a2 + kstep; const char* b3 = b2 + kstep;
;             if (last && has_next) S.a_ready(nxt);
;             if constexpr (SP2) {
;             PG8_LDB(B0, 0, 0); PG8_LDB(B1, 0, 1); PG8_SCHED; PG8_LDA(At, 0, 0); PG8_STAGE(PG8_SA(1, 1), a1 + hstep, voffA);
;             PG8_WAIT_V(8); PG8_WAIT_L(0); PG8_BAR; PG8_MMA(0, 0, At, B0); PG8_MMA(0, 1, At, B1); PG8_BAR; PG8_SCHED;
;             PG8_LDA(At, 0, 1); PG8_STAGE(PG8_SB(0, 0), b2, voffB); PG8_STAGE(PG8_SB(0, 1), b2 + hstep, voffB); PG8_STAGE(PG8_SA(0, 0), a2, voffA);
;             PG8_WAIT_V(8); PG8_WAIT_L(0); PG8_BAR; PG8_MMA(1, 0, At, B0); PG8_MMA(1, 1, At, B1); PG8_BAR; PG8_SCHED;
.LBB0_1167:
	ds_read_b128 v[128:131], v189
	ds_read_b128 v[132:135], v189 offset:1024
	ds_read_b128 v[136:139], v189 offset:2048
	ds_read_b128 v[140:143], v189 offset:3072
	ds_read_b128 v[144:147], v190
	ds_read_b128 v[148:151], v190 offset:1024
	ds_read_b128 v[168:171], v190 offset:2048
	ds_read_b128 v[172:175], v190 offset:3072
	s_add_u32 s6, s22, 0xfff50080
	s_addc_u32 s7, s23, -1
	s_cmp_eq_u32 s53, 40
	s_cselect_b32 s25, s9, s7
	s_cselect_b32 s24, s8, s6
	s_cselect_b32 s7, s21, s52
	s_cselect_b32 s6, s20, s51
	v_lshl_add_u64 v[184:185], s[22:23], 0, v[160:161]
	s_add_i32 m0, s28, 0xc000
	ds_read_b128 v[176:179], v191
	ds_read_b128 v[180:183], v191 offset:1024
	ds_read_b128 v[194:197], v191 offset:2048
	ds_read_b128 v[198:201], v191 offset:3072
	ds_read_b128 v[202:205], v191 offset:4096
	ds_read_b128 v[206:209], v191 offset:5120
	ds_read_b128 v[210:213], v191 offset:6144
	ds_read_b128 v[214:217], v191 offset:7168
	global_load_lds_dwordx4 v[184:185], off
	v_lshl_add_u64 v[184:185], s[22:23], 0, v[162:163]
	s_add_i32 m0, s28, 0xe000
	s_nop 0
	global_load_lds_dwordx4 v[184:185], off
	s_waitcnt vmcnt(8)
	s_waitcnt lgkmcnt(0)
	s_barrier
	s_waitcnt lgkmcnt(0)
	v_mfma_f32_16x16x32_bf16 v[124:127], v[128:131], v[176:179], v[124:127]
	v_mfma_f32_16x16x32_bf16 v[120:123], v[136:139], v[176:179], v[120:123]
	v_mfma_f32_16x16x32_bf16 v[108:111], v[128:131], v[194:197], v[108:111]
	v_mfma_f32_16x16x32_bf16 v[104:107], v[136:139], v[194:197], v[104:107]
	v_mfma_f32_16x16x32_bf16 v[92:95], v[128:131], v[202:205], v[92:95]
	v_mfma_f32_16x16x32_bf16 v[88:91], v[136:139], v[202:205], v[88:91]
	v_mfma_f32_16x16x32_bf16 v[76:79], v[128:131], v[210:213], v[76:79]
	v_mfma_f32_16x16x32_bf16 v[72:75], v[136:139], v[210:213], v[72:75]
	v_mfma_f32_16x16x32_bf16 v[124:127], v[132:135], v[180:183], v[124:127]
	v_mfma_f32_16x16x32_bf16 v[120:123], v[140:143], v[180:183], v[120:123]
	v_mfma_f32_16x16x32_bf16 v[108:111], v[132:135], v[198:201], v[108:111]
	v_mfma_f32_16x16x32_bf16 v[104:107], v[140:143], v[198:201], v[104:107]
	v_mfma_f32_16x16x32_bf16 v[92:95], v[132:135], v[206:209], v[92:95]
	v_mfma_f32_16x16x32_bf16 v[88:91], v[140:143], v[206:209], v[88:91]
	v_mfma_f32_16x16x32_bf16 v[76:79], v[132:135], v[214:217], v[76:79]
	v_mfma_f32_16x16x32_bf16 v[72:75], v[140:143], v[214:217], v[72:75]
	v_mfma_f32_16x16x32_bf16 v[116:119], v[144:147], v[176:179], v[116:119]
	v_mfma_f32_16x16x32_bf16 v[112:115], v[168:171], v[176:179], v[112:115]
	v_mfma_f32_16x16x32_bf16 v[100:103], v[144:147], v[194:197], v[100:103]
	v_mfma_f32_16x16x32_bf16 v[96:99], v[168:171], v[194:197], v[96:99]
	v_mfma_f32_16x16x32_bf16 v[84:87], v[144:147], v[202:205], v[84:87]
	v_mfma_f32_16x16x32_bf16 v[80:83], v[168:171], v[202:205], v[80:83]
	v_mfma_f32_16x16x32_bf16 v[68:71], v[144:147], v[210:213], v[68:71]
	v_mfma_f32_16x16x32_bf16 v[64:67], v[168:171], v[210:213], v[64:67]
	v_mfma_f32_16x16x32_bf16 v[116:119], v[148:151], v[180:183], v[116:119]
	v_mfma_f32_16x16x32_bf16 v[112:115], v[172:175], v[180:183], v[112:115]
	v_mfma_f32_16x16x32_bf16 v[100:103], v[148:151], v[198:201], v[100:103]
	v_mfma_f32_16x16x32_bf16 v[96:99], v[172:175], v[198:201], v[96:99]
	v_mfma_f32_16x16x32_bf16 v[84:87], v[148:151], v[206:209], v[84:87]
	v_mfma_f32_16x16x32_bf16 v[80:83], v[172:175], v[206:209], v[80:83]
	v_mfma_f32_16x16x32_bf16 v[68:71], v[148:151], v[214:217], v[68:71]
	v_mfma_f32_16x16x32_bf16 v[64:67], v[172:175], v[214:217], v[64:67]
	s_barrier
	s_add_i32 s54, s45, s27
	v_lshl_add_u64 v[184:185], s[6:7], 0, v[154:155]
	s_mov_b32 m0, s54
	ds_read_b128 v[176:179], v191 offset:16384
	ds_read_b128 v[180:183], v191 offset:17408
	ds_read_b128 v[194:197], v191 offset:18432
	ds_read_b128 v[198:201], v191 offset:19456
	ds_read_b128 v[202:205], v191 offset:20480
	ds_read_b128 v[206:209], v191 offset:21504
	ds_read_b128 v[210:213], v191 offset:22528
	ds_read_b128 v[214:217], v191 offset:23552
	global_load_lds_dwordx4 v[184:185], off
	s_add_i32 m0, s54, 0x2000
	s_add_u32 s54, s6, 0xb0000
	v_lshl_add_u64 v[218:219], s[6:7], 0, v[158:159]
	s_addc_u32 s55, s7, 0
	s_add_i32 s56, s46, s27
	global_load_lds_dwordx4 v[218:219], off
	v_lshl_add_u64 v[222:223], s[54:55], 0, v[154:155]
	s_mov_b32 m0, s56
	v_lshl_add_u64 v[224:225], s[24:25], 0, v[156:157]
	global_load_lds_dwordx4 v[222:223], off
	v_lshl_add_u64 v[222:223], s[54:55], 0, v[158:159]
	s_add_i32 m0, s56, 0x2000
	s_nop 0
	global_load_lds_dwordx4 v[222:223], off
	v_lshl_add_u64 v[222:223], s[24:25], 0, v[152:153]
	s_mov_b32 m0, s28
	s_nop 0
	global_load_lds_dwordx4 v[222:223], off
	s_mov_b32 m0, s29
	s_nop 0
	global_load_lds_dwordx4 v[224:225], off
	s_waitcnt vmcnt(8)
	s_waitcnt lgkmcnt(0)
	s_barrier
; #define PG8_STAGE(bufoff, gbase, voff) do { _Pragma("unroll") for (int _i = 0; _i < 2; ++_i) \
;         __builtin_amdgcn_global_load_lds((const unsigned*)((const char*)(gbase) + (voff)[_i]), (PG8_LAS unsigned*)(lds + (bufoff) + ldsw + _i * 8192), 16, 0, 0); } while (0)
; #define PG8_LDA(dst, b, h) do { _Pragma("unroll") for (int m = 0; m < 4; ++m) _Pragma("unroll") for (int k = 0; k < 2; ++k) dst[m][k] = *(const PG8_LAS bf16x8*)(lds + PG8_SA(b, h) + aoff + m * 2048 + k * 1024); } while (0)
; #define PG8_LDB(dst, b, h) do { _Pragma("unroll") for (int n = 0; n < 2; ++n) _Pragma("unroll") for (int k = 0; k < 2; ++k) dst[n][k] = *(const PG8_LAS bf16x8*)(lds + PG8_SB(b, h) + boff + n * 2048 + k * 1024); } while (0)
; #define PG8_MMA(ai, bj, At, Bt) do { __builtin_amdgcn_s_setprio(1); _Pragma("unroll") for (int m = 0; m < 4; ++m) _Pragma("unroll") for (int n = 0; n < 2; ++n) _Pragma("unroll") for (int k = 0; k < 2; ++k) \
;         acc[ai][bj][m][n] = __builtin_amdgcn_mfma_f32_16x16x32_bf16(Bt[n][k], At[m][k], acc[ai][bj][m][n], 0, 0, 0); __builtin_amdgcn_s_setprio(0); } while (0)
; #define PG8_WAIT_V(n) asm volatile("s_waitcnt vmcnt(" #n ")" ::: "memory")
; #define PG8_WAIT_L(n) asm volatile("s_waitcnt lgkmcnt(" #n ")" ::: "memory")
; #define PG8_BAR __builtin_amdgcn_s_barrier()
; #define PG8_SCHED __builtin_amdgcn_sched_barrier(0)
; template <class Epi, class Sched, bool ALIGN_EPI = false, bool SP2 = false>
; __device__ __forceinline__ void gemm_phase(PG8_LAS unsigned char* lds, const Gemm g, const Sched& S, const Epi& E) {
;     ...
;             PG8_WAIT_V(8); PG8_WAIT_L(0); PG8_BAR; PG8_MMA(1, 0, At, B0); PG8_MMA(1, 1, At, B1); PG8_BAR; PG8_SCHED;
;             PG8_LDB(B0, 1, 0); PG8_LDB(B1, 1, 1); PG8_SCHED; PG8_LDA(At, 1, 0); PG8_STAGE(PG8_SA(0, 1), a2 + hstep, voffA);
;             PG8_WAIT_V(8); PG8_WAIT_L(0); PG8_BAR; PG8_MMA(0, 0, At, B0); PG8_MMA(0, 1, At, B1); PG8_BAR; PG8_SCHED;
	s_waitcnt lgkmcnt(0)
	v_mfma_f32_16x16x32_bf16 v[60:63], v[128:131], v[176:179], v[60:63]
	v_mfma_f32_16x16x32_bf16 v[56:59], v[136:139], v[176:179], v[56:59]
	v_mfma_f32_16x16x32_bf16 v[44:47], v[128:131], v[194:197], v[44:47]
	v_mfma_f32_16x16x32_bf16 v[40:43], v[136:139], v[194:197], v[40:43]
	v_mfma_f32_16x16x32_bf16 v[28:31], v[128:131], v[202:205], v[28:31]
	v_mfma_f32_16x16x32_bf16 v[24:27], v[136:139], v[202:205], v[24:27]
	v_mfma_f32_16x16x32_bf16 v[12:15], v[128:131], v[210:213], v[12:15]
	v_mfma_f32_16x16x32_bf16 v[8:11], v[136:139], v[210:213], v[8:11]
	v_mfma_f32_16x16x32_bf16 v[60:63], v[132:135], v[180:183], v[60:63]
	v_mfma_f32_16x16x32_bf16 v[56:59], v[140:143], v[180:183], v[56:59]
	v_mfma_f32_16x16x32_bf16 v[44:47], v[132:135], v[198:201], v[44:47]
	v_mfma_f32_16x16x32_bf16 v[40:43], v[140:143], v[198:201], v[40:43]
	v_mfma_f32_16x16x32_bf16 v[28:31], v[132:135], v[206:209], v[28:31]
	v_mfma_f32_16x16x32_bf16 v[24:27], v[140:143], v[206:209], v[24:27]
	v_mfma_f32_16x16x32_bf16 v[12:15], v[132:135], v[214:217], v[12:15]
	v_mfma_f32_16x16x32_bf16 v[8:11], v[140:143], v[214:217], v[8:11]
	v_mfma_f32_16x16x32_bf16 v[52:55], v[144:147], v[176:179], v[52:55]
	v_mfma_f32_16x16x32_bf16 v[48:51], v[168:171], v[176:179], v[48:51]
	v_mfma_f32_16x16x32_bf16 v[36:39], v[144:147], v[194:197], v[36:39]
	v_mfma_f32_16x16x32_bf16 v[32:35], v[168:171], v[194:197], v[32:35]
	v_mfma_f32_16x16x32_bf16 v[20:23], v[144:147], v[202:205], v[20:23]
	v_mfma_f32_16x16x32_bf16 v[16:19], v[168:171], v[202:205], v[16:19]
	v_mfma_f32_16x16x32_bf16 v[4:7], v[144:147], v[210:213], v[4:7]
	v_mfma_f32_16x16x32_bf16 v[0:3], v[168:171], v[210:213], v[0:3]
	v_mfma_f32_16x16x32_bf16 v[52:55], v[148:151], v[180:183], v[52:55]
	v_mfma_f32_16x16x32_bf16 v[48:51], v[172:175], v[180:183], v[48:51]
	v_mfma_f32_16x16x32_bf16 v[36:39], v[148:151], v[198:201], v[36:39]
	v_mfma_f32_16x16x32_bf16 v[32:35], v[172:175], v[198:201], v[32:35]
	v_mfma_f32_16x16x32_bf16 v[20:23], v[148:151], v[206:209], v[20:23]
	v_mfma_f32_16x16x32_bf16 v[16:19], v[172:175], v[206:209], v[16:19]
	v_mfma_f32_16x16x32_bf16 v[4:7], v[148:151], v[214:217], v[4:7]
	v_mfma_f32_16x16x32_bf16 v[0:3], v[172:175], v[214:217], v[0:3]
	s_barrier
	s_add_i32 s54, 0, 0x18000
	s_add_i32 s55, 0, 0x1c000
	v_add_u32_e32 v140, s54, v187
	v_add_u32_e32 v172, s55, v187
	ds_read_b128 v[128:131], v140
	ds_read_b128 v[132:135], v140 offset:1024
	ds_read_b128 v[136:139], v140 offset:2048
	ds_read_b128 v[140:143], v140 offset:3072
	ds_read_b128 v[144:147], v172
	ds_read_b128 v[148:151], v172 offset:1024
	ds_read_b128 v[168:171], v172 offset:2048
	ds_read_b128 v[172:175], v172 offset:3072
	s_add_u32 s24, s24, 0xb0000
	s_addc_u32 s25, s25, 0
	s_mov_b32 m0, s30
	v_lshl_add_u64 v[226:227], s[24:25], 0, v[152:153]
	ds_read_b128 v[176:179], v191 offset:32768
	ds_read_b128 v[180:183], v191 offset:33792
	ds_read_b128 v[194:197], v191 offset:34816
	ds_read_b128 v[198:201], v191 offset:35840
	ds_read_b128 v[202:205], v191 offset:36864
	ds_read_b128 v[206:209], v191 offset:37888
	ds_read_b128 v[210:213], v191 offset:38912
	ds_read_b128 v[214:217], v191 offset:39936
	global_load_lds_dwordx4 v[226:227], off
	v_lshl_add_u64 v[226:227], s[24:25], 0, v[156:157]
	s_mov_b32 m0, s31
	s_nop 0
	global_load_lds_dwordx4 v[226:227], off
	s_waitcnt vmcnt(8)
	s_waitcnt lgkmcnt(0)
	s_barrier
	s_waitcnt lgkmcnt(0)
	v_mfma_f32_16x16x32_bf16 v[124:127], v[128:131], v[176:179], v[124:127]
	v_mfma_f32_16x16x32_bf16 v[120:123], v[136:139], v[176:179], v[120:123]
	v_mfma_f32_16x16x32_bf16 v[108:111], v[128:131], v[194:197], v[108:111]
	v_mfma_f32_16x16x32_bf16 v[104:107], v[136:139], v[194:197], v[104:107]
	v_mfma_f32_16x16x32_bf16 v[92:95], v[128:131], v[202:205], v[92:95]
	v_mfma_f32_16x16x32_bf16 v[88:91], v[136:139], v[202:205], v[88:91]
	v_mfma_f32_16x16x32_bf16 v[76:79], v[128:131], v[210:213], v[76:79]
	v_mfma_f32_16x16x32_bf16 v[72:75], v[136:139], v[210:213], v[72:75]
	v_mfma_f32_16x16x32_bf16 v[124:127], v[132:135], v[180:183], v[124:127]
	v_mfma_f32_16x16x32_bf16 v[120:123], v[140:143], v[180:183], v[120:123]
	v_mfma_f32_16x16x32_bf16 v[108:111], v[132:135], v[198:201], v[108:111]
	v_mfma_f32_16x16x32_bf16 v[104:107], v[140:143], v[198:201], v[104:107]
	v_mfma_f32_16x16x32_bf16 v[92:95], v[132:135], v[206:209], v[92:95]
	v_mfma_f32_16x16x32_bf16 v[88:91], v[140:143], v[206:209], v[88:91]
	v_mfma_f32_16x16x32_bf16 v[76:79], v[132:135], v[214:217], v[76:79]
	v_mfma_f32_16x16x32_bf16 v[72:75], v[140:143], v[214:217], v[72:75]
	v_mfma_f32_16x16x32_bf16 v[116:119], v[144:147], v[176:179], v[116:119]
	v_mfma_f32_16x16x32_bf16 v[112:115], v[168:171], v[176:179], v[112:115]
	v_mfma_f32_16x16x32_bf16 v[100:103], v[144:147], v[194:197], v[100:103]
	v_mfma_f32_16x16x32_bf16 v[96:99], v[168:171], v[194:197], v[96:99]
	v_mfma_f32_16x16x32_bf16 v[84:87], v[144:147], v[202:205], v[84:87]
	v_mfma_f32_16x16x32_bf16 v[80:83], v[168:171], v[202:205], v[80:83]
	v_mfma_f32_16x16x32_bf16 v[68:71], v[144:147], v[210:213], v[68:71]
	v_mfma_f32_16x16x32_bf16 v[64:67], v[168:171], v[210:213], v[64:67]
	v_mfma_f32_16x16x32_bf16 v[116:119], v[148:151], v[180:183], v[116:119]
	v_mfma_f32_16x16x32_bf16 v[112:115], v[172:175], v[180:183], v[112:115]
	v_mfma_f32_16x16x32_bf16 v[100:103], v[148:151], v[198:201], v[100:103]
	v_mfma_f32_16x16x32_bf16 v[96:99], v[172:175], v[198:201], v[96:99]
	v_mfma_f32_16x16x32_bf16 v[84:87], v[148:151], v[206:209], v[84:87]
	v_mfma_f32_16x16x32_bf16 v[80:83], v[172:175], v[206:209], v[80:83]
	v_mfma_f32_16x16x32_bf16 v[68:71], v[148:151], v[214:217], v[68:71]
	v_mfma_f32_16x16x32_bf16 v[64:67], v[172:175], v[214:217], v[64:67]
	s_barrier
; #define PG8_STAGE(bufoff, gbase, voff) do { _Pragma("unroll") for (int _i = 0; _i < 2; ++_i) \
;         __builtin_amdgcn_global_load_lds((const unsigned*)((const char*)(gbase) + (voff)[_i]), (PG8_LAS unsigned*)(lds + (bufoff) + ldsw + _i * 8192), 16, 0, 0); } while (0)
; #define PG8_LDA(dst, b, h) do { _Pragma("unroll") for (int m = 0; m < 4; ++m) _Pragma("unroll") for (int k = 0; k < 2; ++k) dst[m][k] = *(const PG8_LAS bf16x8*)(lds + PG8_SA(b, h) + aoff + m * 2048 + k * 1024); } while (0)
; #define PG8_MMA(ai, bj, At, Bt) do { __builtin_amdgcn_s_setprio(1); _Pragma("unroll") for (int m = 0; m < 4; ++m) _Pragma("unroll") for (int n = 0; n < 2; ++n) _Pragma("unroll") for (int k = 0; k < 2; ++k) \
;         acc[ai][bj][m][n] = __builtin_amdgcn_mfma_f32_16x16x32_bf16(Bt[n][k], At[m][k], acc[ai][bj][m][n], 0, 0, 0); __builtin_amdgcn_s_setprio(0); } while (0)
; #define PG8_WAIT_V(n) asm volatile("s_waitcnt vmcnt(" #n ")" ::: "memory")
; #define PG8_WAIT_L(n) asm volatile("s_waitcnt lgkmcnt(" #n ")" ::: "memory")
; #define PG8_BAR __builtin_amdgcn_s_barrier()
; #define PG8_SCHED __builtin_amdgcn_sched_barrier(0)
; template <class Epi, class Sched, bool ALIGN_EPI = false, bool SP2 = false>
; __device__ __forceinline__ void gemm_phase(PG8_LAS unsigned char* lds, const Gemm g, const Sched& S, const Epi& E) {
;     ...
;             PG8_LDA(At, 1, 1); PG8_STAGE(PG8_SB(1, 0), b3, voffB); PG8_STAGE(PG8_SB(1, 1), b3 + hstep, voffB); PG8_STAGE(PG8_SA(1, 0), a3, voffA);
;             PG8_WAIT_V(8); PG8_WAIT_L(0); PG8_BAR; PG8_MMA(1, 0, At, B0); PG8_MMA(1, 1, At, B1); PG8_BAR; PG8_SCHED;
;     ...
;         if constexpr (ALIGN_EPI) { if (wr == 0) PG8_BAR; }
;         if constexpr (!Epi::AFTER_DRAIN) { E(acc, cur, wr, wc, fr, fq); S.done(cur); }
;         if (!has_next) break;
	s_add_i32 s24, s54, s27
	v_lshl_add_u64 v[184:185], v[184:185], 0, s[16:17]
	s_mov_b32 m0, s24
	ds_read_b128 v[176:179], v191 offset:49152
	ds_read_b128 v[180:183], v191 offset:50176
	ds_read_b128 v[194:197], v191 offset:51200
	ds_read_b128 v[198:201], v191 offset:52224
	ds_read_b128 v[202:205], v191 offset:53248
	ds_read_b128 v[206:209], v191 offset:54272
	ds_read_b128 v[210:213], v191 offset:55296
	ds_read_b128 v[214:217], v191 offset:56320
	global_load_lds_dwordx4 v[184:185], off
	s_add_i32 m0, s24, 0x2000
	s_add_u32 s6, s6, 0xb0080
	v_lshl_add_u64 v[184:185], v[218:219], 0, s[16:17]
	s_addc_u32 s7, s7, 0
	s_add_i32 s24, s55, s27
	global_load_lds_dwordx4 v[184:185], off
	v_lshl_add_u64 v[184:185], s[6:7], 0, v[154:155]
	s_mov_b32 m0, s24
	s_nop 0
	global_load_lds_dwordx4 v[184:185], off
	v_lshl_add_u64 v[184:185], s[6:7], 0, v[158:159]
	s_add_i32 m0, s24, 0x2000
	s_nop 0
	global_load_lds_dwordx4 v[184:185], off
	v_lshl_add_u64 v[184:185], v[222:223], 0, s[16:17]
	s_mov_b32 m0, s34
	s_nop 0
	global_load_lds_dwordx4 v[184:185], off
	v_lshl_add_u64 v[184:185], v[224:225], 0, s[16:17]
	s_mov_b32 m0, s35
	s_nop 0
	global_load_lds_dwordx4 v[184:185], off
	s_waitcnt vmcnt(8)
	s_waitcnt lgkmcnt(0)
	s_barrier
	s_waitcnt lgkmcnt(0)
	v_mfma_f32_16x16x32_bf16 v[60:63], v[128:131], v[176:179], v[60:63]
	v_mfma_f32_16x16x32_bf16 v[56:59], v[136:139], v[176:179], v[56:59]
	v_mfma_f32_16x16x32_bf16 v[44:47], v[128:131], v[194:197], v[44:47]
	v_mfma_f32_16x16x32_bf16 v[40:43], v[136:139], v[194:197], v[40:43]
	v_mfma_f32_16x16x32_bf16 v[28:31], v[128:131], v[202:205], v[28:31]
	v_mfma_f32_16x16x32_bf16 v[24:27], v[136:139], v[202:205], v[24:27]
	v_mfma_f32_16x16x32_bf16 v[12:15], v[128:131], v[210:213], v[12:15]
	v_mfma_f32_16x16x32_bf16 v[8:11], v[136:139], v[210:213], v[8:11]
	v_mfma_f32_16x16x32_bf16 v[60:63], v[132:135], v[180:183], v[60:63]
	v_mfma_f32_16x16x32_bf16 v[56:59], v[140:143], v[180:183], v[56:59]
	v_mfma_f32_16x16x32_bf16 v[44:47], v[132:135], v[198:201], v[44:47]
	v_mfma_f32_16x16x32_bf16 v[40:43], v[140:143], v[198:201], v[40:43]
	v_mfma_f32_16x16x32_bf16 v[28:31], v[132:135], v[206:209], v[28:31]
	v_mfma_f32_16x16x32_bf16 v[24:27], v[140:143], v[206:209], v[24:27]
	v_mfma_f32_16x16x32_bf16 v[12:15], v[132:135], v[214:217], v[12:15]
	v_mfma_f32_16x16x32_bf16 v[8:11], v[140:143], v[214:217], v[8:11]
	v_mfma_f32_16x16x32_bf16 v[52:55], v[144:147], v[176:179], v[52:55]
	v_mfma_f32_16x16x32_bf16 v[48:51], v[168:171], v[176:179], v[48:51]
	v_mfma_f32_16x16x32_bf16 v[36:39], v[144:147], v[194:197], v[36:39]
	v_mfma_f32_16x16x32_bf16 v[32:35], v[168:171], v[194:197], v[32:35]
	v_mfma_f32_16x16x32_bf16 v[20:23], v[144:147], v[202:205], v[20:23]
	v_mfma_f32_16x16x32_bf16 v[16:19], v[168:171], v[202:205], v[16:19]
	v_mfma_f32_16x16x32_bf16 v[4:7], v[144:147], v[210:213], v[4:7]
	v_mfma_f32_16x16x32_bf16 v[0:3], v[168:171], v[210:213], v[0:3]
	v_mfma_f32_16x16x32_bf16 v[52:55], v[148:151], v[180:183], v[52:55]
	v_mfma_f32_16x16x32_bf16 v[48:51], v[172:175], v[180:183], v[48:51]
	v_mfma_f32_16x16x32_bf16 v[36:39], v[148:151], v[198:201], v[36:39]
	v_mfma_f32_16x16x32_bf16 v[32:35], v[172:175], v[198:201], v[32:35]
	v_mfma_f32_16x16x32_bf16 v[20:23], v[148:151], v[206:209], v[20:23]
	v_mfma_f32_16x16x32_bf16 v[16:19], v[172:175], v[206:209], v[16:19]
	v_mfma_f32_16x16x32_bf16 v[4:7], v[148:151], v[214:217], v[4:7]
	v_mfma_f32_16x16x32_bf16 v[0:3], v[172:175], v[214:217], v[0:3]
	s_barrier
	s_add_i32 s53, s53, 2
	s_add_u32 s22, s22, 0x100
	s_addc_u32 s23, s23, 0
	s_add_u32 s51, s51, 0x100
	s_addc_u32 s52, s52, 0
	s_cmp_gt_u32 s53, 41
	s_cbranch_scc0 .LBB0_1167
	s_and_b64 vcc, exec, s[18:19]
	s_cbranch_vccz .LBB0_1170
	s_barrier
